# GEMM: k0 A-fragment reads of the second A half issued in the MFMA shadow of the previous segment (after its 9th MFMA) instead of in the load segment
# baseline (speedup 1.0000x reference)
.Lrot_enter_10:
	s_add_u32 s7, s46, 0xffea0080
	s_addc_u32 s78, s47, -1
	s_add_i32 s87, 0, 0x10000
	v_add_u32_e32 v132, s87, v135
	ds_read_b128 v[138:141], v132
	ds_read_b128 v[142:145], v132 offset:1024
	ds_read_b128 v[148:151], v132 offset:2048
	ds_read_b128 v[152:155], v132 offset:3072
	s_cmpk_eq_i32 s6, 0x54
	s_cselect_b32 s79, s43, s78
	s_cselect_b32 s78, s42, s7
	s_cselect_b32 s89, s45, s9
	s_cselect_b32 s88, s44, s8
	v_lshl_add_u64 v[132:133], s[46:47], 0, v[130:131]
	s_add_i32 m0, s54, 0xc000
	ds_read_b128 v[156:159], v136
	ds_read_b128 v[160:163], v136 offset:1024
	ds_read_b128 v[164:167], v136 offset:2048
	ds_read_b128 v[168:171], v136 offset:3072
	ds_read_b128 v[172:175], v136 offset:4096
	ds_read_b128 v[176:179], v136 offset:5120
	ds_read_b128 v[180:183], v136 offset:6144
	ds_read_b128 v[184:187], v136 offset:7168
	global_load_lds_dwordx4 v[132:133], off
	v_lshl_add_u64 v[132:133], v[132:133], 0, s[26:27]
	s_add_i32 m0, s54, 0xe000
	s_nop 0
	global_load_lds_dwordx4 v[132:133], off
	s_waitcnt lgkmcnt(8)
	s_barrier
	s_waitcnt lgkmcnt(0)
	v_mfma_f32_16x16x32_bf16 v[126:129], v[138:141], v[156:159], v[126:129]
	v_mfma_f32_16x16x32_bf16 v[122:125], v[148:151], v[156:159], v[122:125]
	v_mfma_f32_16x16x32_bf16 v[118:121], v[138:141], v[164:167], v[118:121]
	v_mfma_f32_16x16x32_bf16 v[110:113], v[148:151], v[164:167], v[110:113]
	v_mfma_f32_16x16x32_bf16 v[102:105], v[138:141], v[172:175], v[102:105]
	v_mfma_f32_16x16x32_bf16 v[94:97], v[148:151], v[172:175], v[94:97]
	v_mfma_f32_16x16x32_bf16 v[86:89], v[138:141], v[180:183], v[86:89]
	v_mfma_f32_16x16x32_bf16 v[78:81], v[148:151], v[180:183], v[78:81]
	v_mfma_f32_16x16x32_bf16 v[126:129], v[142:145], v[160:163], v[126:129]
	v_mfma_f32_16x16x32_bf16 v[122:125], v[152:155], v[160:163], v[122:125]
	v_mfma_f32_16x16x32_bf16 v[118:121], v[142:145], v[168:171], v[118:121]
	v_mfma_f32_16x16x32_bf16 v[110:113], v[152:155], v[168:171], v[110:113]
	v_mfma_f32_16x16x32_bf16 v[102:105], v[142:145], v[176:179], v[102:105]
	v_mfma_f32_16x16x32_bf16 v[94:97], v[152:155], v[176:179], v[94:97]
	v_mfma_f32_16x16x32_bf16 v[86:89], v[142:145], v[184:187], v[86:89]
	v_mfma_f32_16x16x32_bf16 v[78:81], v[152:155], v[184:187], v[78:81]
	s_barrier
	s_add_i32 s7, 0, 0x14000
	v_add_u32_e32 v132, s7, v135
	s_add_i32 s87, s87, s53
	ds_read_b128 v[188:191], v132
	ds_read_b128 v[192:195], v132 offset:1024
	ds_read_b128 v[196:199], v132 offset:2048
	ds_read_b128 v[200:203], v132 offset:3072
	v_lshl_add_u64 v[132:133], s[88:89], 0, v[0:1]
	s_mov_b32 m0, s87
	v_lshl_add_u64 v[204:205], v[132:133], 0, s[26:27]
	global_load_lds_dwordx4 v[132:133], off
	s_add_i32 m0, s87, 0x2000
	s_nop 0
	global_load_lds_dwordx4 v[204:205], off
	s_barrier
	s_waitcnt lgkmcnt(0)
	v_mfma_f32_16x16x32_bf16 v[114:117], v[188:191], v[156:159], v[114:117]
	v_mfma_f32_16x16x32_bf16 v[106:109], v[196:199], v[156:159], v[106:109]
	v_mfma_f32_16x16x32_bf16 v[98:101], v[188:191], v[164:167], v[98:101]
	v_mfma_f32_16x16x32_bf16 v[90:93], v[196:199], v[164:167], v[90:93]
	v_mfma_f32_16x16x32_bf16 v[82:85], v[188:191], v[172:175], v[82:85]
	v_mfma_f32_16x16x32_bf16 v[74:77], v[196:199], v[172:175], v[74:77]
	v_mfma_f32_16x16x32_bf16 v[70:73], v[188:191], v[180:183], v[70:73]
	v_mfma_f32_16x16x32_bf16 v[66:69], v[196:199], v[180:183], v[66:69]
	v_mfma_f32_16x16x32_bf16 v[114:117], v[192:195], v[160:163], v[114:117]
	ds_read_b128 v[156:159], v136 offset:16384
	v_mfma_f32_16x16x32_bf16 v[106:109], v[200:203], v[160:163], v[106:109]
	v_mfma_f32_16x16x32_bf16 v[98:101], v[192:195], v[168:171], v[98:101]
	ds_read_b128 v[164:167], v136 offset:18432
	v_mfma_f32_16x16x32_bf16 v[90:93], v[200:203], v[168:171], v[90:93]
	v_mfma_f32_16x16x32_bf16 v[82:85], v[192:195], v[176:179], v[82:85]
	ds_read_b128 v[172:175], v136 offset:20480
	v_mfma_f32_16x16x32_bf16 v[74:77], v[200:203], v[176:179], v[74:77]
	v_mfma_f32_16x16x32_bf16 v[70:73], v[192:195], v[184:187], v[70:73]
	ds_read_b128 v[180:183], v136 offset:22528
	v_mfma_f32_16x16x32_bf16 v[66:69], v[200:203], v[184:187], v[66:69]
	s_barrier
	s_mov_b32 m0, s54
	v_lshl_add_u64 v[204:205], s[78:79], 0, v[0:1]
	ds_read_b128 v[160:163], v136 offset:17408
	ds_read_b128 v[168:171], v136 offset:19456
	ds_read_b128 v[176:179], v136 offset:21504
	ds_read_b128 v[184:187], v136 offset:23552
	global_load_lds_dwordx4 v[204:205], off
	v_lshl_add_u64 v[206:207], v[204:205], 0, s[26:27]
	s_mov_b32 m0, s55
	s_nop 0
	global_load_lds_dwordx4 v[206:207], off
	s_barrier
	s_waitcnt lgkmcnt(0)
	v_mfma_f32_16x16x32_bf16 v[62:65], v[138:141], v[156:159], v[62:65]
	v_mfma_f32_16x16x32_bf16 v[58:61], v[148:151], v[156:159], v[58:61]
	v_mfma_f32_16x16x32_bf16 v[54:57], v[138:141], v[164:167], v[54:57]
	v_mfma_f32_16x16x32_bf16 v[46:49], v[148:151], v[164:167], v[46:49]
	v_mfma_f32_16x16x32_bf16 v[38:41], v[138:141], v[172:175], v[38:41]
	v_mfma_f32_16x16x32_bf16 v[30:33], v[148:151], v[172:175], v[30:33]
	v_mfma_f32_16x16x32_bf16 v[22:25], v[138:141], v[180:183], v[22:25]
	v_mfma_f32_16x16x32_bf16 v[14:17], v[148:151], v[180:183], v[14:17]
	v_mfma_f32_16x16x32_bf16 v[62:65], v[142:145], v[160:163], v[62:65]
	v_mfma_f32_16x16x32_bf16 v[58:61], v[152:155], v[160:163], v[58:61]
	v_mfma_f32_16x16x32_bf16 v[54:57], v[142:145], v[168:171], v[54:57]
	v_mfma_f32_16x16x32_bf16 v[46:49], v[152:155], v[168:171], v[46:49]
	v_mfma_f32_16x16x32_bf16 v[38:41], v[142:145], v[176:179], v[38:41]
	v_mfma_f32_16x16x32_bf16 v[30:33], v[152:155], v[176:179], v[30:33]
	v_mfma_f32_16x16x32_bf16 v[22:25], v[142:145], v[184:187], v[22:25]
	v_mfma_f32_16x16x32_bf16 v[14:17], v[152:155], v[184:187], v[14:17]
	s_barrier
	s_add_i32 s7, s7, s53
	v_lshl_add_u64 v[138:139], v[132:133], 0, s[28:29]
	s_mov_b32 m0, s7
	s_nop 0
	global_load_lds_dwordx4 v[138:139], off
	v_lshl_add_u64 v[138:139], v[132:133], 0, s[30:31]
	s_add_i32 m0, s7, 0x2000
	s_nop 0
	global_load_lds_dwordx4 v[138:139], off
	v_lshl_add_u64 v[230:231], v[204:205], 0, s[28:29]
	s_mov_b32 m0, s56
	s_nop 0
	global_load_lds_dwordx4 v[230:231], off
	v_lshl_add_u64 v[230:231], v[204:205], 0, s[30:31]
	s_mov_b32 m0, s57
	s_nop 0
	global_load_lds_dwordx4 v[230:231], off
	s_waitcnt vmcnt(8)
	s_barrier
	v_mfma_f32_16x16x32_bf16 v[50:53], v[188:191], v[156:159], v[50:53]
	v_mfma_f32_16x16x32_bf16 v[42:45], v[196:199], v[156:159], v[42:45]
	v_mfma_f32_16x16x32_bf16 v[34:37], v[188:191], v[164:167], v[34:37]
	v_mfma_f32_16x16x32_bf16 v[26:29], v[196:199], v[164:167], v[26:29]
	v_mfma_f32_16x16x32_bf16 v[18:21], v[188:191], v[172:175], v[18:21]
	v_mfma_f32_16x16x32_bf16 v[10:13], v[196:199], v[172:175], v[10:13]
	v_mfma_f32_16x16x32_bf16 v[6:9], v[188:191], v[180:183], v[6:9]
	v_mfma_f32_16x16x32_bf16 v[2:5], v[196:199], v[180:183], v[2:5]
	v_mfma_f32_16x16x32_bf16 v[50:53], v[192:195], v[160:163], v[50:53]
	v_mfma_f32_16x16x32_bf16 v[42:45], v[200:203], v[160:163], v[42:45]
	v_mfma_f32_16x16x32_bf16 v[34:37], v[192:195], v[168:171], v[34:37]
	v_mfma_f32_16x16x32_bf16 v[26:29], v[200:203], v[168:171], v[26:29]
	v_mfma_f32_16x16x32_bf16 v[18:21], v[192:195], v[176:179], v[18:21]
	v_mfma_f32_16x16x32_bf16 v[10:13], v[200:203], v[176:179], v[10:13]
	v_mfma_f32_16x16x32_bf16 v[6:9], v[192:195], v[184:187], v[6:9]
	v_mfma_f32_16x16x32_bf16 v[2:5], v[200:203], v[184:187], v[2:5]
	s_barrier
	s_add_i32 s7, 0, 0x18000
	v_add_u32_e32 v137, s7, v135
	ds_read_b128 v[138:141], v137
	ds_read_b128 v[142:145], v137 offset:1024
	ds_read_b128 v[148:151], v137 offset:2048
	ds_read_b128 v[152:155], v137 offset:3072
	ds_read_b128 v[156:159], v136 offset:32768
	ds_read_b128 v[160:163], v136 offset:33792
	ds_read_b128 v[164:167], v136 offset:34816
	ds_read_b128 v[168:171], v136 offset:35840
	ds_read_b128 v[172:175], v136 offset:36864
	ds_read_b128 v[176:179], v136 offset:37888
	ds_read_b128 v[180:183], v136 offset:38912
	ds_read_b128 v[184:187], v136 offset:39936
	s_waitcnt lgkmcnt(8)
	s_barrier
	s_waitcnt lgkmcnt(0)
	v_mfma_f32_16x16x32_bf16 v[126:129], v[138:141], v[156:159], v[126:129]
	v_mfma_f32_16x16x32_bf16 v[122:125], v[148:151], v[156:159], v[122:125]
	v_mfma_f32_16x16x32_bf16 v[118:121], v[138:141], v[164:167], v[118:121]
	v_mfma_f32_16x16x32_bf16 v[110:113], v[148:151], v[164:167], v[110:113]
	v_mfma_f32_16x16x32_bf16 v[102:105], v[138:141], v[172:175], v[102:105]
	v_mfma_f32_16x16x32_bf16 v[94:97], v[148:151], v[172:175], v[94:97]
	v_mfma_f32_16x16x32_bf16 v[86:89], v[138:141], v[180:183], v[86:89]
	v_mfma_f32_16x16x32_bf16 v[78:81], v[148:151], v[180:183], v[78:81]
	v_mfma_f32_16x16x32_bf16 v[126:129], v[142:145], v[160:163], v[126:129]
	v_mfma_f32_16x16x32_bf16 v[122:125], v[152:155], v[160:163], v[122:125]
	v_mfma_f32_16x16x32_bf16 v[118:121], v[142:145], v[168:171], v[118:121]
	v_mfma_f32_16x16x32_bf16 v[110:113], v[152:155], v[168:171], v[110:113]
	v_mfma_f32_16x16x32_bf16 v[102:105], v[142:145], v[176:179], v[102:105]
	v_mfma_f32_16x16x32_bf16 v[94:97], v[152:155], v[176:179], v[94:97]
	v_mfma_f32_16x16x32_bf16 v[86:89], v[142:145], v[184:187], v[86:89]
	v_mfma_f32_16x16x32_bf16 v[78:81], v[152:155], v[184:187], v[78:81]
	s_barrier
	s_add_i32 s78, 0, 0x1c000
	s_add_i32 s7, s7, s53
	v_add_u32_e32 v137, s78, v135
	v_lshl_add_u64 v[206:207], v[132:133], 0, s[34:35]
	s_mov_b32 m0, s7
	ds_read_b128 v[188:191], v137
	ds_read_b128 v[192:195], v137 offset:1024
	ds_read_b128 v[196:199], v137 offset:2048
	ds_read_b128 v[200:203], v137 offset:3072
	global_load_lds_dwordx4 v[206:207], off
	v_lshl_add_u64 v[206:207], v[132:133], 0, s[36:37]
	s_add_i32 m0, s7, 0x2000
	s_nop 0
	global_load_lds_dwordx4 v[206:207], off
	s_barrier
	s_waitcnt lgkmcnt(0)
	v_mfma_f32_16x16x32_bf16 v[114:117], v[188:191], v[156:159], v[114:117]
	v_mfma_f32_16x16x32_bf16 v[106:109], v[196:199], v[156:159], v[106:109]
	v_mfma_f32_16x16x32_bf16 v[98:101], v[188:191], v[164:167], v[98:101]
	v_mfma_f32_16x16x32_bf16 v[90:93], v[196:199], v[164:167], v[90:93]
	v_mfma_f32_16x16x32_bf16 v[82:85], v[188:191], v[172:175], v[82:85]
	v_mfma_f32_16x16x32_bf16 v[74:77], v[196:199], v[172:175], v[74:77]
	v_mfma_f32_16x16x32_bf16 v[70:73], v[188:191], v[180:183], v[70:73]
	v_mfma_f32_16x16x32_bf16 v[66:69], v[196:199], v[180:183], v[66:69]
	v_mfma_f32_16x16x32_bf16 v[114:117], v[192:195], v[160:163], v[114:117]
	ds_read_b128 v[156:159], v136 offset:49152
	v_mfma_f32_16x16x32_bf16 v[106:109], v[200:203], v[160:163], v[106:109]
	v_mfma_f32_16x16x32_bf16 v[98:101], v[192:195], v[168:171], v[98:101]
	ds_read_b128 v[164:167], v136 offset:51200
	v_mfma_f32_16x16x32_bf16 v[90:93], v[200:203], v[168:171], v[90:93]
	v_mfma_f32_16x16x32_bf16 v[82:85], v[192:195], v[176:179], v[82:85]
	ds_read_b128 v[172:175], v136 offset:53248
	v_mfma_f32_16x16x32_bf16 v[74:77], v[200:203], v[176:179], v[74:77]
	v_mfma_f32_16x16x32_bf16 v[70:73], v[192:195], v[184:187], v[70:73]
	ds_read_b128 v[180:183], v136 offset:55296
	v_mfma_f32_16x16x32_bf16 v[66:69], v[200:203], v[184:187], v[66:69]
	s_barrier
	s_mov_b32 m0, s62
	v_lshl_add_u64 v[206:207], v[204:205], 0, s[34:35]
	ds_read_b128 v[160:163], v136 offset:50176
	ds_read_b128 v[168:171], v136 offset:52224
	ds_read_b128 v[176:179], v136 offset:54272
	ds_read_b128 v[184:187], v136 offset:56320
	global_load_lds_dwordx4 v[206:207], off
	v_lshl_add_u64 v[204:205], v[204:205], 0, s[36:37]
	s_mov_b32 m0, s63
	s_nop 0
	global_load_lds_dwordx4 v[204:205], off
	s_barrier
	s_waitcnt lgkmcnt(0)
	v_mfma_f32_16x16x32_bf16 v[62:65], v[138:141], v[156:159], v[62:65]
	v_mfma_f32_16x16x32_bf16 v[58:61], v[148:151], v[156:159], v[58:61]
	v_mfma_f32_16x16x32_bf16 v[54:57], v[138:141], v[164:167], v[54:57]
	v_mfma_f32_16x16x32_bf16 v[46:49], v[148:151], v[164:167], v[46:49]
	v_mfma_f32_16x16x32_bf16 v[38:41], v[138:141], v[172:175], v[38:41]
	v_mfma_f32_16x16x32_bf16 v[30:33], v[148:151], v[172:175], v[30:33]
	v_mfma_f32_16x16x32_bf16 v[22:25], v[138:141], v[180:183], v[22:25]
	v_mfma_f32_16x16x32_bf16 v[14:17], v[148:151], v[180:183], v[14:17]
	v_mfma_f32_16x16x32_bf16 v[62:65], v[142:145], v[160:163], v[62:65]
	v_mfma_f32_16x16x32_bf16 v[58:61], v[152:155], v[160:163], v[58:61]
	v_mfma_f32_16x16x32_bf16 v[54:57], v[142:145], v[168:171], v[54:57]
	v_mfma_f32_16x16x32_bf16 v[46:49], v[152:155], v[168:171], v[46:49]
	v_mfma_f32_16x16x32_bf16 v[38:41], v[142:145], v[176:179], v[38:41]
	v_mfma_f32_16x16x32_bf16 v[30:33], v[152:155], v[176:179], v[30:33]
	v_mfma_f32_16x16x32_bf16 v[22:25], v[142:145], v[184:187], v[22:25]
	v_mfma_f32_16x16x32_bf16 v[14:17], v[152:155], v[184:187], v[14:17]
	s_barrier
	s_add_i32 s7, s78, s53
	v_lshl_add_u64 v[138:139], v[132:133], 0, s[18:19]
	s_mov_b32 m0, s7
	v_lshl_add_u64 v[132:133], v[132:133], 0, s[14:15]
	global_load_lds_dwordx4 v[138:139], off
	s_add_i32 m0, s7, 0x2000
	s_nop 0
	global_load_lds_dwordx4 v[132:133], off
	s_waitcnt vmcnt(6)
	s_add_i32 s6, s6, 2
	s_add_u32 s8, s8, 0x100
	s_addc_u32 s9, s9, 0
	s_add_u32 s46, s46, 0x100
	s_addc_u32 s47, s47, 0
	s_cmpk_gt_u32 s6, 0x55
	s_cbranch_scc0 .LBB0_37
	s_barrier
	v_mfma_f32_16x16x32_bf16 v[50:53], v[188:191], v[156:159], v[50:53]
	v_mfma_f32_16x16x32_bf16 v[42:45], v[196:199], v[156:159], v[42:45]
	v_mfma_f32_16x16x32_bf16 v[34:37], v[188:191], v[164:167], v[34:37]
	v_mfma_f32_16x16x32_bf16 v[26:29], v[196:199], v[164:167], v[26:29]
	v_mfma_f32_16x16x32_bf16 v[18:21], v[188:191], v[172:175], v[18:21]
	v_mfma_f32_16x16x32_bf16 v[10:13], v[196:199], v[172:175], v[10:13]
	v_mfma_f32_16x16x32_bf16 v[6:9], v[188:191], v[180:183], v[6:9]
	v_mfma_f32_16x16x32_bf16 v[2:5], v[196:199], v[180:183], v[2:5]
	v_mfma_f32_16x16x32_bf16 v[50:53], v[192:195], v[160:163], v[50:53]
	v_mfma_f32_16x16x32_bf16 v[42:45], v[200:203], v[160:163], v[42:45]
	v_mfma_f32_16x16x32_bf16 v[34:37], v[192:195], v[168:171], v[34:37]
	v_mfma_f32_16x16x32_bf16 v[26:29], v[200:203], v[168:171], v[26:29]
	v_mfma_f32_16x16x32_bf16 v[18:21], v[192:195], v[176:179], v[18:21]
	v_mfma_f32_16x16x32_bf16 v[10:13], v[200:203], v[176:179], v[10:13]
	v_mfma_f32_16x16x32_bf16 v[6:9], v[192:195], v[184:187], v[6:9]
	v_mfma_f32_16x16x32_bf16 v[2:5], v[200:203], v[184:187], v[2:5]
	s_barrier
	v_mov_b32_e32 v137, v134
	s_lshl_b32 s6, s86, 8
	v_ashrrev_i32_e32 v132, 2, v137
	s_or_b32 s6, s6, s59
	v_and_b32_e32 v132, -4, v132
	v_add_u32_e32 v132, s6, v132
	s_lshl_b32 s6, s85, 8
	s_add_i32 s6, s6, s58
	v_and_or_b32 v188, v137, 15, s6
	v_ashrrev_i32_e32 v189, 31, v188
	v_ashrrev_i32_e32 v133, 31, v132
	v_lshlrev_b64 v[206:207], 13, v[188:189]
	v_or_b32_e32 v156, 16, v188
	v_or_b32_e32 v172, 32, v188
	v_or_b32_e32 v188, 48, v188
	v_lshlrev_b64 v[132:133], 2, v[132:133]
	v_ashrrev_i32_e32 v157, 31, v156
	v_ashrrev_i32_e32 v173, 31, v172
	v_ashrrev_i32_e32 v189, 31, v188
	v_lshl_add_u64 v[204:205], s[4:5], 0, v[132:133]
	v_lshlrev_b64 v[208:209], 13, v[156:157]
	v_lshlrev_b64 v[210:211], 13, v[172:173]
	v_lshlrev_b64 v[212:213], 13, v[188:189]
	v_lshl_add_u64 v[152:153], v[204:205], 0, v[206:207]
	v_lshl_add_u64 v[168:169], v[204:205], 0, v[208:209]
	v_lshl_add_u64 v[184:185], v[204:205], 0, v[210:211]
	v_lshl_add_u64 v[200:201], v[204:205], 0, v[212:213]
	global_load_dwordx4 v[138:141], v[152:153], off
	global_load_dwordx4 v[142:145], v[152:153], off offset:64
	global_load_dwordx4 v[148:151], v[152:153], off offset:512
	s_nop 0
	global_load_dwordx4 v[152:155], v[152:153], off offset:576
	s_nop 0
	global_load_dwordx4 v[156:159], v[168:169], off
	global_load_dwordx4 v[160:163], v[168:169], off offset:64
	global_load_dwordx4 v[164:167], v[168:169], off offset:512
	s_nop 0
	global_load_dwordx4 v[168:171], v[168:169], off offset:576
	s_nop 0
	global_load_dwordx4 v[172:175], v[184:185], off
	global_load_dwordx4 v[176:179], v[184:185], off offset:64
	global_load_dwordx4 v[180:183], v[184:185], off offset:512
	s_nop 0
	global_load_dwordx4 v[184:187], v[184:185], off offset:576
	s_nop 0
	global_load_dwordx4 v[188:191], v[200:201], off
	global_load_dwordx4 v[192:195], v[200:201], off offset:64
	global_load_dwordx4 v[196:199], v[200:201], off offset:512
	s_nop 0
	global_load_dwordx4 v[200:203], v[200:201], off offset:576
	s_waitcnt vmcnt(0) lgkmcnt(0)
	v_pk_fma_f32 v[126:127], v[126:127], 0.5, v[138:139] op_sel_hi:[1,0,1]
	v_lshl_add_u64 v[138:139], s[4:5], 0, v[206:207]
	v_lshl_add_u64 v[138:139], v[138:139], 0, v[132:133]
	v_pk_fma_f32 v[116:117], v[116:117], 0.5, v[150:151] op_sel_hi:[1,0,1]
	v_pk_fma_f32 v[114:115], v[114:115], 0.5, v[148:149] op_sel_hi:[1,0,1]
	global_store_dwordx4 v[138:139], v[114:117], off offset:512
	v_pk_fma_f32 v[100:101], v[100:101], 0.5, v[166:167] op_sel_hi:[1,0,1]
	v_pk_fma_f32 v[98:99], v[98:99], 0.5, v[164:165] op_sel_hi:[1,0,1]
	v_lshl_add_u64 v[114:115], s[4:5], 0, v[208:209]
	v_lshl_add_u64 v[114:115], v[114:115], 0, v[132:133]
	global_store_dwordx4 v[114:115], v[98:101], off offset:512
	v_pk_fma_f32 v[84:85], v[84:85], 0.5, v[182:183] op_sel_hi:[1,0,1]
	v_pk_fma_f32 v[82:83], v[82:83], 0.5, v[180:181] op_sel_hi:[1,0,1]
	v_lshl_add_u64 v[98:99], s[4:5], 0, v[210:211]
	v_lshl_add_u64 v[98:99], v[98:99], 0, v[132:133]
	v_pk_fma_f32 v[108:109], v[108:109], 0.5, v[154:155] op_sel_hi:[1,0,1]
	v_pk_fma_f32 v[106:107], v[106:107], 0.5, v[152:153] op_sel_hi:[1,0,1]
	v_pk_fma_f32 v[92:93], v[92:93], 0.5, v[170:171] op_sel_hi:[1,0,1]
	v_pk_fma_f32 v[90:91], v[90:91], 0.5, v[168:169] op_sel_hi:[1,0,1]
	global_store_dwordx4 v[98:99], v[82:85], off offset:512
	v_pk_fma_f32 v[76:77], v[76:77], 0.5, v[186:187] op_sel_hi:[1,0,1]
	v_pk_fma_f32 v[74:75], v[74:75], 0.5, v[184:185] op_sel_hi:[1,0,1]
	v_lshl_add_u64 v[82:83], s[4:5], 0, v[212:213]
	global_store_dwordx4 v[138:139], v[106:109], off offset:576
	global_store_dwordx4 v[114:115], v[90:93], off offset:576
	global_store_dwordx4 v[98:99], v[74:77], off offset:576
	v_pk_fma_f32 v[108:109], v[120:121], 0.5, v[158:159] op_sel_hi:[1,0,1]
	v_pk_fma_f32 v[106:107], v[118:119], 0.5, v[156:157] op_sel_hi:[1,0,1]
	v_pk_fma_f32 v[92:93], v[104:105], 0.5, v[174:175] op_sel_hi:[1,0,1]
	v_pk_fma_f32 v[90:91], v[102:103], 0.5, v[172:173] op_sel_hi:[1,0,1]
	v_pk_fma_f32 v[76:77], v[88:89], 0.5, v[190:191] op_sel_hi:[1,0,1]
	v_pk_fma_f32 v[74:75], v[86:87], 0.5, v[188:189] op_sel_hi:[1,0,1]
	v_lshl_add_u64 v[82:83], v[82:83], 0, v[132:133]
	v_pk_fma_f32 v[128:129], v[128:129], 0.5, v[140:141] op_sel_hi:[1,0,1]
	v_pk_fma_f32 v[124:125], v[124:125], 0.5, v[144:145] op_sel_hi:[1,0,1]
	v_pk_fma_f32 v[122:123], v[122:123], 0.5, v[142:143] op_sel_hi:[1,0,1]
	global_store_dwordx4 v[114:115], v[106:109], off
	global_store_dwordx4 v[98:99], v[90:93], off
	global_store_dwordx4 v[82:83], v[74:77], off
	v_pk_fma_f32 v[108:109], v[112:113], 0.5, v[162:163] op_sel_hi:[1,0,1]
	v_pk_fma_f32 v[106:107], v[110:111], 0.5, v[160:161] op_sel_hi:[1,0,1]
	v_pk_fma_f32 v[92:93], v[96:97], 0.5, v[178:179] op_sel_hi:[1,0,1]
	v_pk_fma_f32 v[90:91], v[94:95], 0.5, v[176:177] op_sel_hi:[1,0,1]
	v_pk_fma_f32 v[76:77], v[80:81], 0.5, v[194:195] op_sel_hi:[1,0,1]
	v_pk_fma_f32 v[74:75], v[78:79], 0.5, v[192:193] op_sel_hi:[1,0,1]
	v_pk_fma_f32 v[72:73], v[72:73], 0.5, v[198:199] op_sel_hi:[1,0,1]
	v_pk_fma_f32 v[70:71], v[70:71], 0.5, v[196:197] op_sel_hi:[1,0,1]
	v_pk_fma_f32 v[68:69], v[68:69], 0.5, v[202:203] op_sel_hi:[1,0,1]
	v_pk_fma_f32 v[66:67], v[66:67], 0.5, v[200:201] op_sel_hi:[1,0,1]
	global_store_dwordx4 v[138:139], v[126:129], off
	global_store_dwordx4 v[138:139], v[122:125], off offset:64
	global_store_dwordx4 v[114:115], v[106:109], off offset:64
	global_store_dwordx4 v[98:99], v[90:93], off offset:64
	global_store_dwordx4 v[82:83], v[74:77], off offset:64
	global_store_dwordx4 v[82:83], v[70:73], off offset:512
	global_store_dwordx4 v[82:83], v[66:69], off offset:576
	s_mov_b64 s[6:7], 0x120000
	v_lshl_add_u64 v[140:141], v[206:207], 0, s[6:7]
	s_mov_b64 s[6:7], 0x140000
	v_lshl_add_u64 v[138:139], v[206:207], 0, s[0:1]
	v_lshl_add_u64 v[142:143], v[206:207], 0, s[6:7]
	v_lshl_add_u64 v[144:145], v[206:207], 0, s[28:29]
	v_lshl_add_u64 v[78:79], v[204:205], 0, v[138:139]
	v_lshl_add_u64 v[94:95], v[204:205], 0, v[140:141]
	v_lshl_add_u64 v[110:111], v[204:205], 0, v[142:143]
	v_lshl_add_u64 v[126:127], v[204:205], 0, v[144:145]
	global_load_dwordx4 v[66:69], v[78:79], off
	global_load_dwordx4 v[70:73], v[78:79], off offset:64
	global_load_dwordx4 v[74:77], v[78:79], off offset:512
	s_nop 0
	global_load_dwordx4 v[78:81], v[78:79], off offset:576
	s_nop 0
	global_load_dwordx4 v[82:85], v[94:95], off
	global_load_dwordx4 v[86:89], v[94:95], off offset:64
	global_load_dwordx4 v[90:93], v[94:95], off offset:512
	s_nop 0
	global_load_dwordx4 v[94:97], v[94:95], off offset:576
	s_nop 0
	global_load_dwordx4 v[98:101], v[110:111], off
	global_load_dwordx4 v[102:105], v[110:111], off offset:64
	global_load_dwordx4 v[106:109], v[110:111], off offset:512
	s_nop 0
	global_load_dwordx4 v[110:113], v[110:111], off offset:576
	s_nop 0
	global_load_dwordx4 v[114:117], v[126:127], off
	global_load_dwordx4 v[118:121], v[126:127], off offset:64
	global_load_dwordx4 v[122:125], v[126:127], off offset:512
	s_nop 0
	global_load_dwordx4 v[126:129], v[126:127], off offset:576
	s_waitcnt vmcnt(0) lgkmcnt(0)
	v_pk_fma_f32 v[62:63], v[62:63], 0.5, v[66:67] op_sel_hi:[1,0,1]
	v_lshl_add_u64 v[66:67], s[4:5], 0, v[138:139]
	v_lshl_add_u64 v[66:67], v[66:67], 0, v[132:133]
	v_pk_fma_f32 v[52:53], v[52:53], 0.5, v[76:77] op_sel_hi:[1,0,1]
	v_pk_fma_f32 v[50:51], v[50:51], 0.5, v[74:75] op_sel_hi:[1,0,1]
	global_store_dwordx4 v[66:67], v[50:53], off offset:512
	v_pk_fma_f32 v[36:37], v[36:37], 0.5, v[92:93] op_sel_hi:[1,0,1]
	v_pk_fma_f32 v[34:35], v[34:35], 0.5, v[90:91] op_sel_hi:[1,0,1]
	v_lshl_add_u64 v[50:51], s[4:5], 0, v[140:141]
	v_lshl_add_u64 v[50:51], v[50:51], 0, v[132:133]
	global_store_dwordx4 v[50:51], v[34:37], off offset:512
	v_pk_fma_f32 v[20:21], v[20:21], 0.5, v[108:109] op_sel_hi:[1,0,1]
	v_pk_fma_f32 v[18:19], v[18:19], 0.5, v[106:107] op_sel_hi:[1,0,1]
	v_lshl_add_u64 v[34:35], s[4:5], 0, v[142:143]
	v_lshl_add_u64 v[34:35], v[34:35], 0, v[132:133]
	v_pk_fma_f32 v[44:45], v[44:45], 0.5, v[80:81] op_sel_hi:[1,0,1]
	v_pk_fma_f32 v[42:43], v[42:43], 0.5, v[78:79] op_sel_hi:[1,0,1]
	v_pk_fma_f32 v[28:29], v[28:29], 0.5, v[96:97] op_sel_hi:[1,0,1]
	v_pk_fma_f32 v[26:27], v[26:27], 0.5, v[94:95] op_sel_hi:[1,0,1]
	global_store_dwordx4 v[34:35], v[18:21], off offset:512
	v_pk_fma_f32 v[12:13], v[12:13], 0.5, v[112:113] op_sel_hi:[1,0,1]
	v_pk_fma_f32 v[10:11], v[10:11], 0.5, v[110:111] op_sel_hi:[1,0,1]
	v_lshl_add_u64 v[18:19], s[4:5], 0, v[144:145]
	global_store_dwordx4 v[66:67], v[42:45], off offset:576
	global_store_dwordx4 v[50:51], v[26:29], off offset:576
	global_store_dwordx4 v[34:35], v[10:13], off offset:576
	v_pk_fma_f32 v[44:45], v[56:57], 0.5, v[84:85] op_sel_hi:[1,0,1]
	v_pk_fma_f32 v[42:43], v[54:55], 0.5, v[82:83] op_sel_hi:[1,0,1]
	v_pk_fma_f32 v[28:29], v[40:41], 0.5, v[100:101] op_sel_hi:[1,0,1]
	v_pk_fma_f32 v[26:27], v[38:39], 0.5, v[98:99] op_sel_hi:[1,0,1]
	v_pk_fma_f32 v[12:13], v[24:25], 0.5, v[116:117] op_sel_hi:[1,0,1]
	v_pk_fma_f32 v[10:11], v[22:23], 0.5, v[114:115] op_sel_hi:[1,0,1]
	v_lshl_add_u64 v[18:19], v[18:19], 0, v[132:133]
	v_pk_fma_f32 v[64:65], v[64:65], 0.5, v[68:69] op_sel_hi:[1,0,1]
	v_pk_fma_f32 v[60:61], v[60:61], 0.5, v[72:73] op_sel_hi:[1,0,1]
	v_pk_fma_f32 v[58:59], v[58:59], 0.5, v[70:71] op_sel_hi:[1,0,1]
	global_store_dwordx4 v[50:51], v[42:45], off
	global_store_dwordx4 v[34:35], v[26:29], off
	global_store_dwordx4 v[18:19], v[10:13], off
	v_pk_fma_f32 v[44:45], v[48:49], 0.5, v[88:89] op_sel_hi:[1,0,1]
	v_pk_fma_f32 v[42:43], v[46:47], 0.5, v[86:87] op_sel_hi:[1,0,1]
	v_pk_fma_f32 v[28:29], v[32:33], 0.5, v[104:105] op_sel_hi:[1,0,1]
	v_pk_fma_f32 v[26:27], v[30:31], 0.5, v[102:103] op_sel_hi:[1,0,1]
	v_pk_fma_f32 v[12:13], v[16:17], 0.5, v[120:121] op_sel_hi:[1,0,1]
	v_pk_fma_f32 v[10:11], v[14:15], 0.5, v[118:119] op_sel_hi:[1,0,1]
	v_pk_fma_f32 v[8:9], v[8:9], 0.5, v[124:125] op_sel_hi:[1,0,1]
	v_pk_fma_f32 v[6:7], v[6:7], 0.5, v[122:123] op_sel_hi:[1,0,1]
	v_pk_fma_f32 v[4:5], v[4:5], 0.5, v[128:129] op_sel_hi:[1,0,1]
	v_pk_fma_f32 v[2:3], v[2:3], 0.5, v[126:127] op_sel_hi:[1,0,1]
	global_store_dwordx4 v[66:67], v[62:65], off
	global_store_dwordx4 v[66:67], v[58:61], off offset:64
	global_store_dwordx4 v[50:51], v[42:45], off offset:64
	global_store_dwordx4 v[34:35], v[26:29], off offset:64
	global_store_dwordx4 v[18:19], v[10:13], off offset:64
	global_store_dwordx4 v[18:19], v[6:9], off offset:512
	global_store_dwordx4 v[18:19], v[2:5], off offset:576
	s_and_b64 vcc, exec, s[40:41]
	s_mov_b32 s85, s10
	s_mov_b32 s86, s11
	s_mov_b64 s[8:9], s[44:45]
	s_mov_b64 s[6:7], s[42:43]
	s_movk_i32 s89, 0x37ff
	s_mov_b32 s88, 0x16000
	s_cbranch_vccz .LBB0_30
	s_waitcnt vmcnt(0)
	s_cmpk_gt_u32 s48, 0xff
	s_cbranch_scc1 .LBB0_41
	s_barrier

.Lrot_enter_9:
	s_add_u32 s8, s6, 0x100
	s_addc_u32 s9, s7, 0
	s_add_i32 s90, 0, 0x10000
	v_add_u32_e32 v134, s90, v137
	ds_read_b128 v[140:143], v134
	ds_read_b128 v[148:151], v134 offset:1024
	ds_read_b128 v[152:155], v134 offset:2048
	ds_read_b128 v[156:159], v134 offset:3072
	s_cmp_eq_u32 s87, 28
	s_cselect_b32 s79, s43, s9
	s_cselect_b32 s78, s42, s8
	s_cselect_b32 s89, s47, s86
	s_cselect_b32 s88, s46, s41
	v_lshl_add_u64 v[134:135], s[6:7], 0, v[132:133]
	v_lshl_add_u64 v[144:145], v[134:135], 0, s[16:17]
	s_add_i32 m0, s49, 0xc000
	ds_read_b128 v[160:163], v138
	ds_read_b128 v[164:167], v138 offset:1024
	ds_read_b128 v[168:171], v138 offset:2048
	ds_read_b128 v[172:175], v138 offset:3072
	ds_read_b128 v[176:179], v138 offset:4096
	ds_read_b128 v[180:183], v138 offset:5120
	ds_read_b128 v[184:187], v138 offset:6144
	ds_read_b128 v[188:191], v138 offset:7168
	global_load_lds_dwordx4 v[144:145], off
	v_lshl_add_u64 v[134:135], v[134:135], 0, s[80:81]
	s_add_i32 m0, s49, 0xe000
	s_nop 0
	global_load_lds_dwordx4 v[134:135], off
	s_waitcnt lgkmcnt(8)
	s_barrier
	s_waitcnt lgkmcnt(0)
	v_mfma_f32_16x16x32_bf16 v[126:129], v[140:143], v[160:163], v[126:129]
	v_mfma_f32_16x16x32_bf16 v[118:121], v[152:155], v[160:163], v[118:121]
	v_mfma_f32_16x16x32_bf16 v[110:113], v[140:143], v[168:171], v[110:113]
	v_mfma_f32_16x16x32_bf16 v[102:105], v[152:155], v[168:171], v[102:105]
	v_mfma_f32_16x16x32_bf16 v[94:97], v[140:143], v[176:179], v[94:97]
	v_mfma_f32_16x16x32_bf16 v[86:89], v[152:155], v[176:179], v[86:89]
	v_mfma_f32_16x16x32_bf16 v[78:81], v[140:143], v[184:187], v[78:81]
	v_mfma_f32_16x16x32_bf16 v[70:73], v[152:155], v[184:187], v[70:73]
	v_mfma_f32_16x16x32_bf16 v[126:129], v[148:151], v[164:167], v[126:129]
	v_mfma_f32_16x16x32_bf16 v[118:121], v[156:159], v[164:167], v[118:121]
	v_mfma_f32_16x16x32_bf16 v[110:113], v[148:151], v[172:175], v[110:113]
	v_mfma_f32_16x16x32_bf16 v[102:105], v[156:159], v[172:175], v[102:105]
	v_mfma_f32_16x16x32_bf16 v[94:97], v[148:151], v[180:183], v[94:97]
	v_mfma_f32_16x16x32_bf16 v[86:89], v[156:159], v[180:183], v[86:89]
	v_mfma_f32_16x16x32_bf16 v[78:81], v[148:151], v[188:191], v[78:81]
	v_mfma_f32_16x16x32_bf16 v[70:73], v[156:159], v[188:191], v[70:73]
	s_barrier
	s_add_i32 s6, 0, 0x14000
	v_add_u32_e32 v134, s6, v137
	s_add_i32 s7, s90, s54
	ds_read_b128 v[192:195], v134
	ds_read_b128 v[196:199], v134 offset:1024
	ds_read_b128 v[200:203], v134 offset:2048
	ds_read_b128 v[204:207], v134 offset:3072
	v_lshl_add_u64 v[134:135], s[88:89], 0, v[0:1]
	s_mov_b32 m0, s7
	v_lshl_add_u64 v[144:145], v[134:135], 0, s[60:61]
	global_load_lds_dwordx4 v[134:135], off
	s_add_i32 m0, s7, 0x2000
	s_nop 0
	global_load_lds_dwordx4 v[144:145], off
	s_barrier
	s_waitcnt lgkmcnt(0)
	v_mfma_f32_16x16x32_bf16 v[122:125], v[192:195], v[160:163], v[122:125]
	v_mfma_f32_16x16x32_bf16 v[114:117], v[200:203], v[160:163], v[114:117]
	v_mfma_f32_16x16x32_bf16 v[106:109], v[192:195], v[168:171], v[106:109]
	v_mfma_f32_16x16x32_bf16 v[98:101], v[200:203], v[168:171], v[98:101]
	v_mfma_f32_16x16x32_bf16 v[90:93], v[192:195], v[176:179], v[90:93]
	v_mfma_f32_16x16x32_bf16 v[82:85], v[200:203], v[176:179], v[82:85]
	v_mfma_f32_16x16x32_bf16 v[74:77], v[192:195], v[184:187], v[74:77]
	v_mfma_f32_16x16x32_bf16 v[66:69], v[200:203], v[184:187], v[66:69]
	v_mfma_f32_16x16x32_bf16 v[122:125], v[196:199], v[164:167], v[122:125]
	ds_read_b128 v[160:163], v138 offset:16384
	v_mfma_f32_16x16x32_bf16 v[114:117], v[204:207], v[164:167], v[114:117]
	v_mfma_f32_16x16x32_bf16 v[106:109], v[196:199], v[172:175], v[106:109]
	ds_read_b128 v[168:171], v138 offset:18432
	v_mfma_f32_16x16x32_bf16 v[98:101], v[204:207], v[172:175], v[98:101]
	v_mfma_f32_16x16x32_bf16 v[90:93], v[196:199], v[180:183], v[90:93]
	ds_read_b128 v[176:179], v138 offset:20480
	v_mfma_f32_16x16x32_bf16 v[82:85], v[204:207], v[180:183], v[82:85]
	v_mfma_f32_16x16x32_bf16 v[74:77], v[196:199], v[188:191], v[74:77]
	ds_read_b128 v[184:187], v138 offset:22528
	v_mfma_f32_16x16x32_bf16 v[66:69], v[204:207], v[188:191], v[66:69]
	s_barrier
	s_mov_b32 m0, s49
	v_lshl_add_u64 v[144:145], s[78:79], 0, v[130:131]
	ds_read_b128 v[164:167], v138 offset:17408
	ds_read_b128 v[172:175], v138 offset:19456
	ds_read_b128 v[180:183], v138 offset:21504
	ds_read_b128 v[188:191], v138 offset:23552
	global_load_lds_dwordx4 v[144:145], off
	v_lshl_add_u64 v[208:209], v[144:145], 0, s[60:61]
	s_mov_b32 m0, s55
	s_nop 0
	global_load_lds_dwordx4 v[208:209], off
	s_barrier
	s_waitcnt lgkmcnt(0)
	v_mfma_f32_16x16x32_bf16 v[62:65], v[140:143], v[160:163], v[62:65]
	v_mfma_f32_16x16x32_bf16 v[54:57], v[152:155], v[160:163], v[54:57]
	v_mfma_f32_16x16x32_bf16 v[46:49], v[140:143], v[168:171], v[46:49]
	v_mfma_f32_16x16x32_bf16 v[38:41], v[152:155], v[168:171], v[38:41]
	v_mfma_f32_16x16x32_bf16 v[30:33], v[140:143], v[176:179], v[30:33]
	v_mfma_f32_16x16x32_bf16 v[22:25], v[152:155], v[176:179], v[22:25]
	v_mfma_f32_16x16x32_bf16 v[14:17], v[140:143], v[184:187], v[14:17]
	v_mfma_f32_16x16x32_bf16 v[6:9], v[152:155], v[184:187], v[6:9]
	v_mfma_f32_16x16x32_bf16 v[62:65], v[148:151], v[164:167], v[62:65]
	v_mfma_f32_16x16x32_bf16 v[54:57], v[156:159], v[164:167], v[54:57]
	v_mfma_f32_16x16x32_bf16 v[46:49], v[148:151], v[172:175], v[46:49]
	v_mfma_f32_16x16x32_bf16 v[38:41], v[156:159], v[172:175], v[38:41]
	v_mfma_f32_16x16x32_bf16 v[30:33], v[148:151], v[180:183], v[30:33]
	v_mfma_f32_16x16x32_bf16 v[22:25], v[156:159], v[180:183], v[22:25]
	v_mfma_f32_16x16x32_bf16 v[14:17], v[148:151], v[188:191], v[14:17]
	v_mfma_f32_16x16x32_bf16 v[6:9], v[156:159], v[188:191], v[6:9]
	s_barrier
	s_add_i32 s6, s6, s54
	v_lshl_add_u64 v[140:141], v[134:135], 0, s[20:21]
	s_mov_b32 m0, s6
	s_nop 0
	global_load_lds_dwordx4 v[140:141], off
	v_lshl_add_u64 v[140:141], v[134:135], 0, s[64:65]
	s_add_i32 m0, s6, 0x2000
	s_nop 0
	global_load_lds_dwordx4 v[140:141], off
	v_lshl_add_u64 v[230:231], v[144:145], 0, s[20:21]
	s_mov_b32 m0, s56
	s_nop 0
	global_load_lds_dwordx4 v[230:231], off
	v_lshl_add_u64 v[230:231], v[144:145], 0, s[64:65]
	s_mov_b32 m0, s57
	s_nop 0
	global_load_lds_dwordx4 v[230:231], off
	s_waitcnt vmcnt(8)
	s_barrier
	v_mfma_f32_16x16x32_bf16 v[58:61], v[192:195], v[160:163], v[58:61]
	v_mfma_f32_16x16x32_bf16 v[50:53], v[200:203], v[160:163], v[50:53]
	v_mfma_f32_16x16x32_bf16 v[42:45], v[192:195], v[168:171], v[42:45]
	v_mfma_f32_16x16x32_bf16 v[34:37], v[200:203], v[168:171], v[34:37]
	v_mfma_f32_16x16x32_bf16 v[26:29], v[192:195], v[176:179], v[26:29]
	v_mfma_f32_16x16x32_bf16 v[18:21], v[200:203], v[176:179], v[18:21]
	v_mfma_f32_16x16x32_bf16 v[10:13], v[192:195], v[184:187], v[10:13]
	v_mfma_f32_16x16x32_bf16 v[2:5], v[200:203], v[184:187], v[2:5]
	v_mfma_f32_16x16x32_bf16 v[58:61], v[196:199], v[164:167], v[58:61]
	v_mfma_f32_16x16x32_bf16 v[50:53], v[204:207], v[164:167], v[50:53]
	v_mfma_f32_16x16x32_bf16 v[42:45], v[196:199], v[172:175], v[42:45]
	v_mfma_f32_16x16x32_bf16 v[34:37], v[204:207], v[172:175], v[34:37]
	v_mfma_f32_16x16x32_bf16 v[26:29], v[196:199], v[180:183], v[26:29]
	v_mfma_f32_16x16x32_bf16 v[18:21], v[204:207], v[180:183], v[18:21]
	v_mfma_f32_16x16x32_bf16 v[10:13], v[196:199], v[188:191], v[10:13]
	v_mfma_f32_16x16x32_bf16 v[2:5], v[204:207], v[188:191], v[2:5]
	s_barrier
	s_add_i32 s6, 0, 0x18000
	v_add_u32_e32 v139, s6, v137
	ds_read_b128 v[140:143], v139
	ds_read_b128 v[148:151], v139 offset:1024
	ds_read_b128 v[152:155], v139 offset:2048
	ds_read_b128 v[156:159], v139 offset:3072
	ds_read_b128 v[160:163], v138 offset:32768
	ds_read_b128 v[164:167], v138 offset:33792
	ds_read_b128 v[168:171], v138 offset:34816
	ds_read_b128 v[172:175], v138 offset:35840
	ds_read_b128 v[176:179], v138 offset:36864
	ds_read_b128 v[180:183], v138 offset:37888
	ds_read_b128 v[184:187], v138 offset:38912
	ds_read_b128 v[188:191], v138 offset:39936
	s_waitcnt lgkmcnt(8)
	s_barrier
	s_waitcnt lgkmcnt(0)
	v_mfma_f32_16x16x32_bf16 v[126:129], v[140:143], v[160:163], v[126:129]
	v_mfma_f32_16x16x32_bf16 v[118:121], v[152:155], v[160:163], v[118:121]
	v_mfma_f32_16x16x32_bf16 v[110:113], v[140:143], v[168:171], v[110:113]
	v_mfma_f32_16x16x32_bf16 v[102:105], v[152:155], v[168:171], v[102:105]
	v_mfma_f32_16x16x32_bf16 v[94:97], v[140:143], v[176:179], v[94:97]
	v_mfma_f32_16x16x32_bf16 v[86:89], v[152:155], v[176:179], v[86:89]
	v_mfma_f32_16x16x32_bf16 v[78:81], v[140:143], v[184:187], v[78:81]
	v_mfma_f32_16x16x32_bf16 v[70:73], v[152:155], v[184:187], v[70:73]
	v_mfma_f32_16x16x32_bf16 v[126:129], v[148:151], v[164:167], v[126:129]
	v_mfma_f32_16x16x32_bf16 v[118:121], v[156:159], v[164:167], v[118:121]
	v_mfma_f32_16x16x32_bf16 v[110:113], v[148:151], v[172:175], v[110:113]
	v_mfma_f32_16x16x32_bf16 v[102:105], v[156:159], v[172:175], v[102:105]
	v_mfma_f32_16x16x32_bf16 v[94:97], v[148:151], v[180:183], v[94:97]
	v_mfma_f32_16x16x32_bf16 v[86:89], v[156:159], v[180:183], v[86:89]
	v_mfma_f32_16x16x32_bf16 v[78:81], v[148:151], v[188:191], v[78:81]
	v_mfma_f32_16x16x32_bf16 v[70:73], v[156:159], v[188:191], v[70:73]
	s_barrier
	s_add_i32 s7, 0, 0x1c000
	s_add_i32 s6, s6, s54
	v_add_u32_e32 v139, s7, v137
	v_lshl_add_u64 v[208:209], v[134:135], 0, s[34:35]
	s_mov_b32 m0, s6
	ds_read_b128 v[192:195], v139
	ds_read_b128 v[196:199], v139 offset:1024
	ds_read_b128 v[200:203], v139 offset:2048
	ds_read_b128 v[204:207], v139 offset:3072
	global_load_lds_dwordx4 v[208:209], off
	v_lshl_add_u64 v[208:209], v[134:135], 0, s[66:67]
	s_add_i32 m0, s6, 0x2000
	s_nop 0
	global_load_lds_dwordx4 v[208:209], off
	s_barrier
	s_waitcnt lgkmcnt(0)
	v_mfma_f32_16x16x32_bf16 v[122:125], v[192:195], v[160:163], v[122:125]
	v_mfma_f32_16x16x32_bf16 v[114:117], v[200:203], v[160:163], v[114:117]
	v_mfma_f32_16x16x32_bf16 v[106:109], v[192:195], v[168:171], v[106:109]
	v_mfma_f32_16x16x32_bf16 v[98:101], v[200:203], v[168:171], v[98:101]
	v_mfma_f32_16x16x32_bf16 v[90:93], v[192:195], v[176:179], v[90:93]
	v_mfma_f32_16x16x32_bf16 v[82:85], v[200:203], v[176:179], v[82:85]
	v_mfma_f32_16x16x32_bf16 v[74:77], v[192:195], v[184:187], v[74:77]
	v_mfma_f32_16x16x32_bf16 v[66:69], v[200:203], v[184:187], v[66:69]
	v_mfma_f32_16x16x32_bf16 v[122:125], v[196:199], v[164:167], v[122:125]
	ds_read_b128 v[160:163], v138 offset:49152
	v_mfma_f32_16x16x32_bf16 v[114:117], v[204:207], v[164:167], v[114:117]
	v_mfma_f32_16x16x32_bf16 v[106:109], v[196:199], v[172:175], v[106:109]
	ds_read_b128 v[168:171], v138 offset:51200
	v_mfma_f32_16x16x32_bf16 v[98:101], v[204:207], v[172:175], v[98:101]
	v_mfma_f32_16x16x32_bf16 v[90:93], v[196:199], v[180:183], v[90:93]
	ds_read_b128 v[176:179], v138 offset:53248
	v_mfma_f32_16x16x32_bf16 v[82:85], v[204:207], v[180:183], v[82:85]
	v_mfma_f32_16x16x32_bf16 v[74:77], v[196:199], v[188:191], v[74:77]
	ds_read_b128 v[184:187], v138 offset:55296
	v_mfma_f32_16x16x32_bf16 v[66:69], v[204:207], v[188:191], v[66:69]
	s_barrier
	s_mov_b32 m0, s59
	v_lshl_add_u64 v[208:209], v[144:145], 0, s[34:35]
	ds_read_b128 v[164:167], v138 offset:50176
	ds_read_b128 v[172:175], v138 offset:52224
	ds_read_b128 v[180:183], v138 offset:54272
	ds_read_b128 v[188:191], v138 offset:56320
	global_load_lds_dwordx4 v[208:209], off
	v_lshl_add_u64 v[144:145], v[144:145], 0, s[66:67]
	s_mov_b32 m0, s62
	s_nop 0
	global_load_lds_dwordx4 v[144:145], off
	s_barrier
	s_waitcnt lgkmcnt(0)
	v_mfma_f32_16x16x32_bf16 v[62:65], v[140:143], v[160:163], v[62:65]
	v_mfma_f32_16x16x32_bf16 v[54:57], v[152:155], v[160:163], v[54:57]
	v_mfma_f32_16x16x32_bf16 v[46:49], v[140:143], v[168:171], v[46:49]
	v_mfma_f32_16x16x32_bf16 v[38:41], v[152:155], v[168:171], v[38:41]
	v_mfma_f32_16x16x32_bf16 v[30:33], v[140:143], v[176:179], v[30:33]
	v_mfma_f32_16x16x32_bf16 v[22:25], v[152:155], v[176:179], v[22:25]
	v_mfma_f32_16x16x32_bf16 v[14:17], v[140:143], v[184:187], v[14:17]
	v_mfma_f32_16x16x32_bf16 v[6:9], v[152:155], v[184:187], v[6:9]
	v_mfma_f32_16x16x32_bf16 v[62:65], v[148:151], v[164:167], v[62:65]
	v_mfma_f32_16x16x32_bf16 v[54:57], v[156:159], v[164:167], v[54:57]
	v_mfma_f32_16x16x32_bf16 v[46:49], v[148:151], v[172:175], v[46:49]
	v_mfma_f32_16x16x32_bf16 v[38:41], v[156:159], v[172:175], v[38:41]
	v_mfma_f32_16x16x32_bf16 v[30:33], v[148:151], v[180:183], v[30:33]
	v_mfma_f32_16x16x32_bf16 v[22:25], v[156:159], v[180:183], v[22:25]
	v_mfma_f32_16x16x32_bf16 v[14:17], v[148:151], v[188:191], v[14:17]
	v_mfma_f32_16x16x32_bf16 v[6:9], v[156:159], v[188:191], v[6:9]
	s_barrier
	s_add_i32 s6, s7, s54
	v_lshl_add_u64 v[140:141], v[134:135], 0, s[16:17]
	s_mov_b32 m0, s6
	v_lshl_add_u64 v[134:135], v[134:135], 0, s[80:81]
	global_load_lds_dwordx4 v[140:141], off
	s_add_i32 m0, s6, 0x2000
	s_nop 0
	global_load_lds_dwordx4 v[134:135], off
	s_waitcnt vmcnt(6)
	s_add_i32 s87, s87, 2
	s_add_u32 s41, s41, 0x100
	s_addc_u32 s86, s86, 0
	s_cmp_gt_u32 s87, 29
	s_mov_b64 s[6:7], s[8:9]
	s_cbranch_scc0 .LBB0_51
	s_barrier
	v_mfma_f32_16x16x32_bf16 v[58:61], v[192:195], v[160:163], v[58:61]
	v_mfma_f32_16x16x32_bf16 v[50:53], v[200:203], v[160:163], v[50:53]
	v_mfma_f32_16x16x32_bf16 v[42:45], v[192:195], v[168:171], v[42:45]
	v_mfma_f32_16x16x32_bf16 v[34:37], v[200:203], v[168:171], v[34:37]
	v_mfma_f32_16x16x32_bf16 v[26:29], v[192:195], v[176:179], v[26:29]
	v_mfma_f32_16x16x32_bf16 v[18:21], v[200:203], v[176:179], v[18:21]
	v_mfma_f32_16x16x32_bf16 v[10:13], v[192:195], v[184:187], v[10:13]
	v_mfma_f32_16x16x32_bf16 v[2:5], v[200:203], v[184:187], v[2:5]
	v_mfma_f32_16x16x32_bf16 v[58:61], v[196:199], v[164:167], v[58:61]
	v_mfma_f32_16x16x32_bf16 v[50:53], v[204:207], v[164:167], v[50:53]
	v_mfma_f32_16x16x32_bf16 v[42:45], v[196:199], v[172:175], v[42:45]
	v_mfma_f32_16x16x32_bf16 v[34:37], v[204:207], v[172:175], v[34:37]
	v_mfma_f32_16x16x32_bf16 v[26:29], v[196:199], v[180:183], v[26:29]
	v_mfma_f32_16x16x32_bf16 v[18:21], v[204:207], v[180:183], v[18:21]
	v_mfma_f32_16x16x32_bf16 v[10:13], v[196:199], v[188:191], v[10:13]
	v_mfma_f32_16x16x32_bf16 v[2:5], v[204:207], v[188:191], v[2:5]
	s_barrier
	v_mul_f32_e32 v144, 0xbfb8aa3b, v126
	v_exp_f32_e32 v144, v144
	v_mov_b32_e32 v134, v136
	s_lshl_b32 s6, s48, 8
	v_add_f32_e32 v144, 1.0, v144
	v_rcp_f32_e32 v144, v144
	s_add_i32 s6, s6, s10
	v_and_or_b32 v139, v134, 15, s6
	s_lshl_b32 s6, s85, 7
	v_mul_f32_e32 v126, v126, v144
	v_mul_f32_e32 v122, v126, v122
	v_mul_f32_e32 v126, 0xbfb8aa3b, v127
	v_exp_f32_e32 v126, v126
	v_ashrrev_i32_e32 v134, 1, v134
	s_or_b32 s6, s6, s58
	v_and_b32_e32 v134, -8, v134
	v_add_f32_e32 v126, 1.0, v126
	v_rcp_f32_e32 v126, v126
	v_add_u32_e32 v140, s6, v134
	v_ashrrev_i32_e32 v141, 31, v140
	v_mov_b64_e32 v[134:135], s[4:5]
	v_mul_f32_e32 v126, v127, v126
	v_mul_f32_e32 v123, v126, v123
	v_mul_f32_e32 v126, 0xbfb8aa3b, v128
	v_exp_f32_e32 v126, v126
	v_mad_i64_i32 v[142:143], s[6:7], v139, s74, v[134:135]
	s_and_b64 vcc, exec, s[44:45]
	v_add_f32_e32 v126, 1.0, v126
	v_rcp_f32_e32 v126, v126
	s_mov_b32 s48, s40
	s_mov_b32 s85, s84
	s_mov_b64 s[8:9], s[46:47]
	v_mul_f32_e32 v126, v128, v126
	v_mul_f32_e32 v124, v126, v124
	v_mul_f32_e32 v126, 0xbfb8aa3b, v129
	v_exp_f32_e32 v126, v126
	s_nop 0
	v_add_f32_e32 v126, 1.0, v126
	v_rcp_f32_e32 v126, v126
	s_nop 0
	v_mul_f32_e32 v126, v129, v126
	v_mul_f32_e32 v125, v126, v125
	v_mul_f32_e32 v126, 0xbfb8aa3b, v118
	v_exp_f32_e32 v126, v126
	s_nop 0
	v_add_f32_e32 v126, 1.0, v126
	v_rcp_f32_e32 v126, v126
	s_nop 0
	v_mul_f32_e32 v118, v118, v126
	v_mul_f32_e32 v118, v118, v114
	v_mul_f32_e32 v114, 0xbfb8aa3b, v119
	v_exp_f32_e32 v114, v114
	s_nop 0
	v_add_f32_e32 v114, 1.0, v114
	v_rcp_f32_e32 v114, v114
	s_nop 0
	v_mul_f32_e32 v114, v119, v114
	v_mul_f32_e32 v119, v114, v115
	v_mul_f32_e32 v114, 0xbfb8aa3b, v120
	v_exp_f32_e32 v114, v114
	s_nop 0
	v_add_f32_e32 v114, 1.0, v114
	v_rcp_f32_e32 v114, v114
	s_nop 0
	v_mul_f32_e32 v114, v120, v114
	v_mul_f32_e32 v126, v114, v116
	v_mul_f32_e32 v114, 0xbfb8aa3b, v121
	v_exp_f32_e32 v114, v114
	v_cvt_pk_bf16_f32 v116, v122, v123
	s_nop 0
	v_add_f32_e32 v114, 1.0, v114
	v_rcp_f32_e32 v114, v114
	s_nop 0
	v_mul_f32_e32 v114, v121, v114
	v_mul_f32_e32 v127, v114, v117
	v_lshlrev_b64 v[114:115], 1, v[140:141]
	v_lshl_add_u64 v[120:121], v[142:143], 0, v[114:115]
	v_cvt_pk_bf16_f32 v117, v124, v125
	v_cvt_pk_bf16_f32 v118, v118, v119
	v_cvt_pk_bf16_f32 v119, v126, v127
	global_store_dwordx4 v[120:121], v[116:119], off
	s_nop 1
	v_mul_f32_e32 v118, 0xbfb8aa3b, v110
	v_exp_f32_e32 v118, v118
	v_or_b32_e32 v116, 16, v139
	v_mad_i64_i32 v[116:117], s[6:7], v116, s74, v[134:135]
	v_add_f32_e32 v118, 1.0, v118
	v_rcp_f32_e32 v118, v118
	s_nop 0
	v_mul_f32_e32 v110, v110, v118
	v_mul_f32_e32 v106, v110, v106
	v_mul_f32_e32 v110, 0xbfb8aa3b, v111
	v_exp_f32_e32 v110, v110
	s_nop 0
	v_add_f32_e32 v110, 1.0, v110
	v_rcp_f32_e32 v110, v110
	s_nop 0
	v_mul_f32_e32 v110, v111, v110
	v_mul_f32_e32 v107, v110, v107
	v_mul_f32_e32 v110, 0xbfb8aa3b, v112
	v_exp_f32_e32 v110, v110
	s_nop 0
	v_add_f32_e32 v110, 1.0, v110
	v_rcp_f32_e32 v110, v110
	s_nop 0
	v_mul_f32_e32 v110, v112, v110
	v_mul_f32_e32 v108, v110, v108
	v_mul_f32_e32 v110, 0xbfb8aa3b, v113
	v_exp_f32_e32 v110, v110
	s_nop 0
	v_add_f32_e32 v110, 1.0, v110
	v_rcp_f32_e32 v110, v110
	s_nop 0
	v_mul_f32_e32 v110, v113, v110
	v_mul_f32_e32 v109, v110, v109
	v_mul_f32_e32 v110, 0xbfb8aa3b, v102
	v_exp_f32_e32 v110, v110
	s_nop 0
	v_add_f32_e32 v110, 1.0, v110
	v_rcp_f32_e32 v110, v110
	s_nop 0
	v_mul_f32_e32 v102, v102, v110
	v_mul_f32_e32 v110, v102, v98
	v_mul_f32_e32 v98, 0xbfb8aa3b, v103
	v_exp_f32_e32 v98, v98
	s_nop 0
	v_add_f32_e32 v98, 1.0, v98
	v_rcp_f32_e32 v98, v98
	s_nop 0
	v_mul_f32_e32 v98, v103, v98
	v_mul_f32_e32 v111, v98, v99
	v_mul_f32_e32 v98, 0xbfb8aa3b, v104
	v_exp_f32_e32 v98, v98
	v_lshl_add_u64 v[102:103], v[116:117], 0, v[114:115]
	v_add_f32_e32 v98, 1.0, v98
	v_rcp_f32_e32 v98, v98
	s_nop 0
	v_mul_f32_e32 v98, v104, v98
	v_mul_f32_e32 v104, v98, v100
	v_mul_f32_e32 v98, 0xbfb8aa3b, v105
	v_exp_f32_e32 v98, v98
	s_nop 0
	v_add_f32_e32 v98, 1.0, v98
	v_rcp_f32_e32 v98, v98
	s_nop 0
	v_mul_f32_e32 v98, v105, v98
	v_mul_f32_e32 v101, v98, v101
	v_cvt_pk_bf16_f32 v98, v106, v107
	v_cvt_pk_bf16_f32 v99, v108, v109
	v_cvt_pk_bf16_f32 v100, v110, v111
	v_cvt_pk_bf16_f32 v101, v104, v101
	global_store_dwordx4 v[102:103], v[98:101], off
	s_nop 1
	v_mul_f32_e32 v100, 0xbfb8aa3b, v94
	v_exp_f32_e32 v100, v100
	v_or_b32_e32 v98, 32, v139
	v_mad_i64_i32 v[98:99], s[6:7], v98, s74, v[134:135]
	v_add_f32_e32 v100, 1.0, v100
	v_rcp_f32_e32 v100, v100
	s_nop 0
	v_mul_f32_e32 v94, v94, v100
	v_mul_f32_e32 v90, v94, v90
	v_mul_f32_e32 v94, 0xbfb8aa3b, v95
	v_exp_f32_e32 v94, v94
	s_nop 0
	v_add_f32_e32 v94, 1.0, v94
	v_rcp_f32_e32 v94, v94
	s_nop 0
	v_mul_f32_e32 v94, v95, v94
	v_mul_f32_e32 v91, v94, v91
	v_mul_f32_e32 v94, 0xbfb8aa3b, v96
	v_exp_f32_e32 v94, v94
	s_nop 0
	v_add_f32_e32 v94, 1.0, v94
	v_rcp_f32_e32 v94, v94
	s_nop 0
	v_mul_f32_e32 v94, v96, v94
	v_mul_f32_e32 v92, v94, v92
	v_mul_f32_e32 v94, 0xbfb8aa3b, v97
	v_exp_f32_e32 v94, v94
	s_nop 0
	v_add_f32_e32 v94, 1.0, v94
	v_rcp_f32_e32 v94, v94
	s_nop 0
	v_mul_f32_e32 v94, v97, v94
	v_mul_f32_e32 v93, v94, v93
	v_mul_f32_e32 v94, 0xbfb8aa3b, v86
	v_exp_f32_e32 v94, v94
	s_nop 0
	v_add_f32_e32 v94, 1.0, v94
	v_rcp_f32_e32 v94, v94
	s_nop 0
	v_mul_f32_e32 v86, v86, v94
	v_mul_f32_e32 v94, v86, v82
	v_mul_f32_e32 v82, 0xbfb8aa3b, v87
	v_exp_f32_e32 v82, v82
	s_nop 0
	v_add_f32_e32 v82, 1.0, v82
	v_rcp_f32_e32 v82, v82
	s_nop 0
	v_mul_f32_e32 v82, v87, v82
	v_mul_f32_e32 v95, v82, v83
	v_mul_f32_e32 v82, 0xbfb8aa3b, v88
	v_exp_f32_e32 v82, v82
	v_lshl_add_u64 v[86:87], v[98:99], 0, v[114:115]
	v_add_f32_e32 v82, 1.0, v82
	v_rcp_f32_e32 v82, v82
	s_nop 0
	v_mul_f32_e32 v82, v88, v82
	v_mul_f32_e32 v88, v82, v84
	v_mul_f32_e32 v82, 0xbfb8aa3b, v89
	v_exp_f32_e32 v82, v82
	s_nop 0
	v_add_f32_e32 v82, 1.0, v82
	v_rcp_f32_e32 v82, v82
	s_nop 0
	v_mul_f32_e32 v82, v89, v82
	v_mul_f32_e32 v85, v82, v85
	v_cvt_pk_bf16_f32 v82, v90, v91
	v_cvt_pk_bf16_f32 v83, v92, v93
	v_cvt_pk_bf16_f32 v84, v94, v95
	v_cvt_pk_bf16_f32 v85, v88, v85
	global_store_dwordx4 v[86:87], v[82:85], off
	s_nop 1
	v_mul_f32_e32 v84, 0xbfb8aa3b, v78
	v_exp_f32_e32 v84, v84
	v_or_b32_e32 v82, 48, v139
	v_mad_i64_i32 v[82:83], s[6:7], v82, s74, v[134:135]
	v_add_f32_e32 v84, 1.0, v84
	v_rcp_f32_e32 v84, v84
	s_nop 0
	v_mul_f32_e32 v78, v78, v84
	v_mul_f32_e32 v74, v78, v74
	v_mul_f32_e32 v78, 0xbfb8aa3b, v79
	v_exp_f32_e32 v78, v78
	s_nop 0
	v_add_f32_e32 v78, 1.0, v78
	v_rcp_f32_e32 v78, v78
	s_nop 0
	v_mul_f32_e32 v78, v79, v78
	v_mul_f32_e32 v75, v78, v75
	v_mul_f32_e32 v78, 0xbfb8aa3b, v80
	v_exp_f32_e32 v78, v78
	s_nop 0
	v_add_f32_e32 v78, 1.0, v78
	v_rcp_f32_e32 v78, v78
	s_nop 0
	v_mul_f32_e32 v78, v80, v78
	v_mul_f32_e32 v76, v78, v76
	v_mul_f32_e32 v78, 0xbfb8aa3b, v81
	v_exp_f32_e32 v78, v78
	s_nop 0
	v_add_f32_e32 v78, 1.0, v78
	v_rcp_f32_e32 v78, v78
	s_nop 0
	v_mul_f32_e32 v78, v81, v78
	v_mul_f32_e32 v77, v78, v77
	v_mul_f32_e32 v78, 0xbfb8aa3b, v70
	v_exp_f32_e32 v78, v78
	s_nop 0
	v_add_f32_e32 v78, 1.0, v78
	v_rcp_f32_e32 v78, v78
	s_nop 0
	v_mul_f32_e32 v70, v70, v78
	v_mul_f32_e32 v78, v70, v66
	v_mul_f32_e32 v66, 0xbfb8aa3b, v71
	v_exp_f32_e32 v66, v66
	s_nop 0
	v_add_f32_e32 v66, 1.0, v66
	v_rcp_f32_e32 v66, v66
	s_nop 0
	v_mul_f32_e32 v66, v71, v66
	v_mul_f32_e32 v79, v66, v67
	v_mul_f32_e32 v66, 0xbfb8aa3b, v72
	v_exp_f32_e32 v66, v66
	v_lshl_add_u64 v[70:71], v[82:83], 0, v[114:115]
	v_add_f32_e32 v66, 1.0, v66
	v_rcp_f32_e32 v66, v66
	s_nop 0
	v_mul_f32_e32 v66, v72, v66
	v_mul_f32_e32 v72, v66, v68
	v_mul_f32_e32 v66, 0xbfb8aa3b, v73
	v_exp_f32_e32 v66, v66
	s_nop 0
	v_add_f32_e32 v66, 1.0, v66
	v_rcp_f32_e32 v66, v66
	s_nop 0
	v_mul_f32_e32 v66, v73, v66
	v_mul_f32_e32 v69, v66, v69
	v_cvt_pk_bf16_f32 v66, v74, v75
	v_cvt_pk_bf16_f32 v67, v76, v77
	v_cvt_pk_bf16_f32 v68, v78, v79
	v_cvt_pk_bf16_f32 v69, v72, v69
	global_store_dwordx4 v[70:71], v[66:69], off
	s_nop 1
	v_mul_f32_e32 v68, 0xbfb8aa3b, v62
	v_exp_f32_e32 v68, v68
	v_add_u32_e32 v66, 0x80, v139
	v_mad_i64_i32 v[66:67], s[6:7], v66, s74, v[134:135]
	v_add_f32_e32 v68, 1.0, v68
	v_rcp_f32_e32 v68, v68
	s_nop 0
	v_mul_f32_e32 v62, v62, v68
	v_mul_f32_e32 v58, v62, v58
	v_mul_f32_e32 v62, 0xbfb8aa3b, v63
	v_exp_f32_e32 v62, v62
	s_nop 0
	v_add_f32_e32 v62, 1.0, v62
	v_rcp_f32_e32 v62, v62
	s_nop 0
	v_mul_f32_e32 v62, v63, v62
	v_mul_f32_e32 v59, v62, v59
	v_mul_f32_e32 v62, 0xbfb8aa3b, v64
	v_exp_f32_e32 v62, v62
	s_nop 0
	v_add_f32_e32 v62, 1.0, v62
	v_rcp_f32_e32 v62, v62
	s_nop 0
	v_mul_f32_e32 v62, v64, v62
	v_mul_f32_e32 v60, v62, v60
	v_mul_f32_e32 v62, 0xbfb8aa3b, v65
	v_exp_f32_e32 v62, v62
	s_nop 0
	v_add_f32_e32 v62, 1.0, v62
	v_rcp_f32_e32 v62, v62
	s_nop 0
	v_mul_f32_e32 v62, v65, v62
	v_mul_f32_e32 v61, v62, v61
	v_mul_f32_e32 v62, 0xbfb8aa3b, v54
	v_exp_f32_e32 v62, v62
	s_nop 0
	v_add_f32_e32 v62, 1.0, v62
	v_rcp_f32_e32 v62, v62
	s_nop 0
	v_mul_f32_e32 v54, v54, v62
	v_mul_f32_e32 v62, v54, v50
	v_mul_f32_e32 v50, 0xbfb8aa3b, v55
	v_exp_f32_e32 v50, v50
	s_nop 0
	v_add_f32_e32 v50, 1.0, v50
	v_rcp_f32_e32 v50, v50
	s_nop 0
	v_mul_f32_e32 v50, v55, v50
	v_mul_f32_e32 v63, v50, v51
	v_mul_f32_e32 v50, 0xbfb8aa3b, v56
	v_exp_f32_e32 v50, v50
	v_lshl_add_u64 v[54:55], v[66:67], 0, v[114:115]
	v_add_f32_e32 v50, 1.0, v50
	v_rcp_f32_e32 v50, v50
	s_nop 0
	v_mul_f32_e32 v50, v56, v50
	v_mul_f32_e32 v56, v50, v52
	v_mul_f32_e32 v50, 0xbfb8aa3b, v57
	v_exp_f32_e32 v50, v50
	s_nop 0
	v_add_f32_e32 v50, 1.0, v50
	v_rcp_f32_e32 v50, v50
	s_nop 0
	v_mul_f32_e32 v50, v57, v50
	v_mul_f32_e32 v53, v50, v53
	v_cvt_pk_bf16_f32 v50, v58, v59
	v_cvt_pk_bf16_f32 v51, v60, v61
	v_cvt_pk_bf16_f32 v52, v62, v63
	v_cvt_pk_bf16_f32 v53, v56, v53
	global_store_dwordx4 v[54:55], v[50:53], off
	s_nop 1
	v_mul_f32_e32 v52, 0xbfb8aa3b, v46
	v_exp_f32_e32 v52, v52
	v_add_u32_e32 v50, 0x90, v139
	v_mad_i64_i32 v[50:51], s[6:7], v50, s74, v[134:135]
	v_add_f32_e32 v52, 1.0, v52
	v_rcp_f32_e32 v52, v52
	s_nop 0
	v_mul_f32_e32 v46, v46, v52
	v_mul_f32_e32 v42, v46, v42
	v_mul_f32_e32 v46, 0xbfb8aa3b, v47
	v_exp_f32_e32 v46, v46
	s_nop 0
	v_add_f32_e32 v46, 1.0, v46
	v_rcp_f32_e32 v46, v46
	s_nop 0
	v_mul_f32_e32 v46, v47, v46
	v_mul_f32_e32 v43, v46, v43
	v_mul_f32_e32 v46, 0xbfb8aa3b, v48
	v_exp_f32_e32 v46, v46
	s_nop 0
	v_add_f32_e32 v46, 1.0, v46
	v_rcp_f32_e32 v46, v46
	s_nop 0
	v_mul_f32_e32 v46, v48, v46
	v_mul_f32_e32 v44, v46, v44
	v_mul_f32_e32 v46, 0xbfb8aa3b, v49
	v_exp_f32_e32 v46, v46
	s_nop 0
	v_add_f32_e32 v46, 1.0, v46
	v_rcp_f32_e32 v46, v46
	s_nop 0
	v_mul_f32_e32 v46, v49, v46
	v_mul_f32_e32 v45, v46, v45
	v_mul_f32_e32 v46, 0xbfb8aa3b, v38
	v_exp_f32_e32 v46, v46
	s_nop 0
	v_add_f32_e32 v46, 1.0, v46
	v_rcp_f32_e32 v46, v46
	s_nop 0
	v_mul_f32_e32 v38, v38, v46
	v_mul_f32_e32 v46, v38, v34
	v_mul_f32_e32 v34, 0xbfb8aa3b, v39
	v_exp_f32_e32 v34, v34
	s_nop 0
	v_add_f32_e32 v34, 1.0, v34
	v_rcp_f32_e32 v34, v34
	s_nop 0
	v_mul_f32_e32 v34, v39, v34
	v_mul_f32_e32 v47, v34, v35
	v_mul_f32_e32 v34, 0xbfb8aa3b, v40
	v_exp_f32_e32 v34, v34
	v_lshl_add_u64 v[38:39], v[50:51], 0, v[114:115]
	v_add_f32_e32 v34, 1.0, v34
	v_rcp_f32_e32 v34, v34
	s_nop 0
	v_mul_f32_e32 v34, v40, v34
	v_mul_f32_e32 v40, v34, v36
	v_mul_f32_e32 v34, 0xbfb8aa3b, v41
	v_exp_f32_e32 v34, v34
	s_nop 0
	v_add_f32_e32 v34, 1.0, v34
	v_rcp_f32_e32 v34, v34
	s_nop 0
	v_mul_f32_e32 v34, v41, v34
	v_mul_f32_e32 v37, v34, v37
	v_cvt_pk_bf16_f32 v34, v42, v43
	v_cvt_pk_bf16_f32 v35, v44, v45
	v_cvt_pk_bf16_f32 v36, v46, v47
	v_cvt_pk_bf16_f32 v37, v40, v37
	global_store_dwordx4 v[38:39], v[34:37], off
	s_nop 1
	v_mul_f32_e32 v36, 0xbfb8aa3b, v30
	v_exp_f32_e32 v36, v36
	v_add_u32_e32 v34, 0xa0, v139
	v_mad_i64_i32 v[34:35], s[6:7], v34, s74, v[134:135]
	v_add_f32_e32 v36, 1.0, v36
	v_rcp_f32_e32 v36, v36
	s_nop 0
	v_mul_f32_e32 v30, v30, v36
	v_mul_f32_e32 v26, v30, v26
	v_mul_f32_e32 v30, 0xbfb8aa3b, v31
	v_exp_f32_e32 v30, v30
	s_nop 0
	v_add_f32_e32 v30, 1.0, v30
	v_rcp_f32_e32 v30, v30
	s_nop 0
	v_mul_f32_e32 v30, v31, v30
	v_mul_f32_e32 v27, v30, v27
	v_mul_f32_e32 v30, 0xbfb8aa3b, v32
	v_exp_f32_e32 v30, v30
	s_nop 0
	v_add_f32_e32 v30, 1.0, v30
	v_rcp_f32_e32 v30, v30
	s_nop 0
	v_mul_f32_e32 v30, v32, v30
	v_mul_f32_e32 v28, v30, v28
	v_mul_f32_e32 v30, 0xbfb8aa3b, v33
	v_exp_f32_e32 v30, v30
	s_nop 0
	v_add_f32_e32 v30, 1.0, v30
	v_rcp_f32_e32 v30, v30
	s_nop 0
	v_mul_f32_e32 v30, v33, v30
	v_mul_f32_e32 v29, v30, v29
	v_mul_f32_e32 v30, 0xbfb8aa3b, v22
	v_exp_f32_e32 v30, v30
	s_nop 0
	v_add_f32_e32 v30, 1.0, v30
	v_rcp_f32_e32 v30, v30
	s_nop 0
	v_mul_f32_e32 v22, v22, v30
	v_mul_f32_e32 v30, v22, v18
	v_mul_f32_e32 v18, 0xbfb8aa3b, v23
	v_exp_f32_e32 v18, v18
	s_nop 0
	v_add_f32_e32 v18, 1.0, v18
	v_rcp_f32_e32 v18, v18
	s_nop 0
	v_mul_f32_e32 v18, v23, v18
	v_mul_f32_e32 v31, v18, v19
	v_mul_f32_e32 v18, 0xbfb8aa3b, v24
	v_exp_f32_e32 v18, v18
	v_lshl_add_u64 v[22:23], v[34:35], 0, v[114:115]
	v_add_f32_e32 v18, 1.0, v18
	v_rcp_f32_e32 v18, v18
	s_nop 0
	v_mul_f32_e32 v18, v24, v18
	v_mul_f32_e32 v24, v18, v20
	v_mul_f32_e32 v18, 0xbfb8aa3b, v25
	v_exp_f32_e32 v18, v18
	s_nop 0
	v_add_f32_e32 v18, 1.0, v18
	v_rcp_f32_e32 v18, v18
	s_nop 0
	v_mul_f32_e32 v18, v25, v18
	v_mul_f32_e32 v21, v18, v21
	v_cvt_pk_bf16_f32 v18, v26, v27
	v_cvt_pk_bf16_f32 v19, v28, v29
	v_cvt_pk_bf16_f32 v20, v30, v31
	v_cvt_pk_bf16_f32 v21, v24, v21
	global_store_dwordx4 v[22:23], v[18:21], off
	s_nop 1
	v_mul_f32_e32 v20, 0xbfb8aa3b, v14
	v_exp_f32_e32 v20, v20
	v_add_u32_e32 v18, 0xb0, v139
	v_mad_i64_i32 v[18:19], s[6:7], v18, s74, v[134:135]
	v_add_f32_e32 v20, 1.0, v20
	v_rcp_f32_e32 v20, v20
	s_mov_b64 s[6:7], s[42:43]
	v_mul_f32_e32 v14, v14, v20
	v_mul_f32_e32 v10, v14, v10
	v_mul_f32_e32 v14, 0xbfb8aa3b, v15
	v_exp_f32_e32 v14, v14
	s_nop 0
	v_add_f32_e32 v14, 1.0, v14
	v_rcp_f32_e32 v14, v14
	s_nop 0
	v_mul_f32_e32 v14, v15, v14
	v_mul_f32_e32 v11, v14, v11
	v_mul_f32_e32 v14, 0xbfb8aa3b, v16
	v_exp_f32_e32 v14, v14
	s_nop 0
	v_add_f32_e32 v14, 1.0, v14
	v_rcp_f32_e32 v14, v14
	s_nop 0
	v_mul_f32_e32 v14, v16, v14
	v_mul_f32_e32 v12, v14, v12
	v_mul_f32_e32 v14, 0xbfb8aa3b, v17
	v_exp_f32_e32 v14, v14
	s_nop 0
	v_add_f32_e32 v14, 1.0, v14
	v_rcp_f32_e32 v14, v14
	s_nop 0
	v_mul_f32_e32 v14, v17, v14
	v_mul_f32_e32 v13, v14, v13
	v_mul_f32_e32 v14, 0xbfb8aa3b, v6
	v_exp_f32_e32 v14, v14
	s_nop 0
	v_add_f32_e32 v14, 1.0, v14
	v_rcp_f32_e32 v14, v14
	s_nop 0
	v_mul_f32_e32 v6, v6, v14
	v_mul_f32_e32 v14, v6, v2
	v_mul_f32_e32 v2, 0xbfb8aa3b, v7
	v_exp_f32_e32 v2, v2
	s_nop 0
	v_add_f32_e32 v2, 1.0, v2
	v_rcp_f32_e32 v2, v2
	s_nop 0
	v_mul_f32_e32 v2, v7, v2
	v_mul_f32_e32 v15, v2, v3
	v_mul_f32_e32 v2, 0xbfb8aa3b, v8
	v_exp_f32_e32 v2, v2
	v_lshl_add_u64 v[6:7], v[18:19], 0, v[114:115]
	v_add_f32_e32 v2, 1.0, v2
	v_rcp_f32_e32 v2, v2
	s_nop 0
	v_mul_f32_e32 v2, v8, v2
	v_mul_f32_e32 v8, v2, v4
	v_mul_f32_e32 v2, 0xbfb8aa3b, v9
	v_exp_f32_e32 v2, v2
	s_nop 0
	v_add_f32_e32 v2, 1.0, v2
	v_rcp_f32_e32 v2, v2
	s_nop 0
	v_mul_f32_e32 v2, v9, v2
	v_mul_f32_e32 v5, v2, v5
	v_cvt_pk_bf16_f32 v2, v10, v11
	v_cvt_pk_bf16_f32 v3, v12, v13
	v_cvt_pk_bf16_f32 v4, v14, v15
	v_cvt_pk_bf16_f32 v5, v8, v5
	global_store_dwordx4 v[6:7], v[2:5], off
	s_cbranch_vccz .LBB0_48
	s_waitcnt vmcnt(0)
	v_readlane_b32 s0, v255, 8
	v_readlane_b32 s62, v255, 10
	v_readlane_b32 s84, v255, 12
	s_cmpk_gt_u32 s22, 0xff
	v_readlane_b32 s1, v255, 9
	s_mov_b64 s[58:59], s[92:93]
	v_readlane_b32 s63, v255, 11
	v_readlane_b32 s85, v255, 13
	s_cbranch_scc1 .LBB0_55
	s_barrier

.Lrot_enter_8:
	s_add_u32 s7, s50, 0xfff80080
	s_addc_u32 s11, s51, -1
	s_add_i32 s43, 0, 0x10000
	v_add_u32_e32 v132, s43, v135
	ds_read_b128 v[138:141], v132
	ds_read_b128 v[142:145], v132 offset:1024
	ds_read_b128 v[148:151], v132 offset:2048
	ds_read_b128 v[152:155], v132 offset:3072
	s_cmp_eq_u32 s6, 28
	s_cselect_b32 s79, s45, s11
	s_cselect_b32 s78, s44, s7
	s_cselect_b32 s91, s47, s9
	s_cselect_b32 s90, s46, s8
	v_lshl_add_u64 v[132:133], s[50:51], 0, v[130:131]
	s_add_i32 m0, s49, 0xc000
	ds_read_b128 v[156:159], v136
	ds_read_b128 v[160:163], v136 offset:1024
	ds_read_b128 v[164:167], v136 offset:2048
	ds_read_b128 v[168:171], v136 offset:3072
	ds_read_b128 v[172:175], v136 offset:4096
	ds_read_b128 v[176:179], v136 offset:5120
	ds_read_b128 v[180:183], v136 offset:6144
	ds_read_b128 v[184:187], v136 offset:7168
	global_load_lds_dwordx4 v[132:133], off
	v_lshl_add_u64 v[132:133], v[132:133], 0, s[60:61]
	s_add_i32 m0, s49, 0xe000
	s_nop 0
	global_load_lds_dwordx4 v[132:133], off
	s_waitcnt lgkmcnt(8)
	s_barrier
	s_waitcnt lgkmcnt(0)
	v_mfma_f32_16x16x32_bf16 v[126:129], v[138:141], v[156:159], v[126:129]
	v_mfma_f32_16x16x32_bf16 v[122:125], v[148:151], v[156:159], v[122:125]
	v_mfma_f32_16x16x32_bf16 v[118:121], v[138:141], v[164:167], v[118:121]
	v_mfma_f32_16x16x32_bf16 v[110:113], v[148:151], v[164:167], v[110:113]
	v_mfma_f32_16x16x32_bf16 v[102:105], v[138:141], v[172:175], v[102:105]
	v_mfma_f32_16x16x32_bf16 v[94:97], v[148:151], v[172:175], v[94:97]
	v_mfma_f32_16x16x32_bf16 v[86:89], v[138:141], v[180:183], v[86:89]
	v_mfma_f32_16x16x32_bf16 v[78:81], v[148:151], v[180:183], v[78:81]
	v_mfma_f32_16x16x32_bf16 v[126:129], v[142:145], v[160:163], v[126:129]
	v_mfma_f32_16x16x32_bf16 v[122:125], v[152:155], v[160:163], v[122:125]
	v_mfma_f32_16x16x32_bf16 v[118:121], v[142:145], v[168:171], v[118:121]
	v_mfma_f32_16x16x32_bf16 v[110:113], v[152:155], v[168:171], v[110:113]
	v_mfma_f32_16x16x32_bf16 v[102:105], v[142:145], v[176:179], v[102:105]
	v_mfma_f32_16x16x32_bf16 v[94:97], v[152:155], v[176:179], v[94:97]
	v_mfma_f32_16x16x32_bf16 v[86:89], v[142:145], v[184:187], v[86:89]
	v_mfma_f32_16x16x32_bf16 v[78:81], v[152:155], v[184:187], v[78:81]
	s_barrier
	s_add_i32 s7, 0, 0x14000
	v_add_u32_e32 v132, s7, v135
	s_add_i32 s11, s43, s57
	ds_read_b128 v[188:191], v132
	ds_read_b128 v[192:195], v132 offset:1024
	ds_read_b128 v[196:199], v132 offset:2048
	ds_read_b128 v[200:203], v132 offset:3072
	v_lshl_add_u64 v[132:133], s[90:91], 0, v[0:1]
	s_mov_b32 m0, s11
	v_lshl_add_u64 v[204:205], v[132:133], 0, s[60:61]
	global_load_lds_dwordx4 v[132:133], off
	s_add_i32 m0, s11, 0x2000
	s_nop 0
	global_load_lds_dwordx4 v[204:205], off
	s_barrier
	s_waitcnt lgkmcnt(0)
	v_mfma_f32_16x16x32_bf16 v[114:117], v[188:191], v[156:159], v[114:117]
	v_mfma_f32_16x16x32_bf16 v[106:109], v[196:199], v[156:159], v[106:109]
	v_mfma_f32_16x16x32_bf16 v[98:101], v[188:191], v[164:167], v[98:101]
	v_mfma_f32_16x16x32_bf16 v[90:93], v[196:199], v[164:167], v[90:93]
	v_mfma_f32_16x16x32_bf16 v[82:85], v[188:191], v[172:175], v[82:85]
	v_mfma_f32_16x16x32_bf16 v[74:77], v[196:199], v[172:175], v[74:77]
	v_mfma_f32_16x16x32_bf16 v[70:73], v[188:191], v[180:183], v[70:73]
	v_mfma_f32_16x16x32_bf16 v[66:69], v[196:199], v[180:183], v[66:69]
	v_mfma_f32_16x16x32_bf16 v[114:117], v[192:195], v[160:163], v[114:117]
	ds_read_b128 v[156:159], v136 offset:16384
	v_mfma_f32_16x16x32_bf16 v[106:109], v[200:203], v[160:163], v[106:109]
	v_mfma_f32_16x16x32_bf16 v[98:101], v[192:195], v[168:171], v[98:101]
	ds_read_b128 v[164:167], v136 offset:18432
	v_mfma_f32_16x16x32_bf16 v[90:93], v[200:203], v[168:171], v[90:93]
	v_mfma_f32_16x16x32_bf16 v[82:85], v[192:195], v[176:179], v[82:85]
	ds_read_b128 v[172:175], v136 offset:20480
	v_mfma_f32_16x16x32_bf16 v[74:77], v[200:203], v[176:179], v[74:77]
	v_mfma_f32_16x16x32_bf16 v[70:73], v[192:195], v[184:187], v[70:73]
	ds_read_b128 v[180:183], v136 offset:22528
	v_mfma_f32_16x16x32_bf16 v[66:69], v[200:203], v[184:187], v[66:69]
	s_barrier
	s_mov_b32 m0, s49
	v_lshl_add_u64 v[204:205], s[78:79], 0, v[0:1]
	ds_read_b128 v[160:163], v136 offset:17408
	ds_read_b128 v[168:171], v136 offset:19456
	ds_read_b128 v[176:179], v136 offset:21504
	ds_read_b128 v[184:187], v136 offset:23552
	global_load_lds_dwordx4 v[204:205], off
	v_lshl_add_u64 v[206:207], v[204:205], 0, s[60:61]
	s_mov_b32 m0, s58
	s_nop 0
	global_load_lds_dwordx4 v[206:207], off
	s_barrier
	s_waitcnt lgkmcnt(0)
	v_mfma_f32_16x16x32_bf16 v[62:65], v[138:141], v[156:159], v[62:65]
	v_mfma_f32_16x16x32_bf16 v[58:61], v[148:151], v[156:159], v[58:61]
	v_mfma_f32_16x16x32_bf16 v[54:57], v[138:141], v[164:167], v[54:57]
	v_mfma_f32_16x16x32_bf16 v[46:49], v[148:151], v[164:167], v[46:49]
	v_mfma_f32_16x16x32_bf16 v[38:41], v[138:141], v[172:175], v[38:41]
	v_mfma_f32_16x16x32_bf16 v[30:33], v[148:151], v[172:175], v[30:33]
	v_mfma_f32_16x16x32_bf16 v[22:25], v[138:141], v[180:183], v[22:25]
	v_mfma_f32_16x16x32_bf16 v[14:17], v[148:151], v[180:183], v[14:17]
	v_mfma_f32_16x16x32_bf16 v[62:65], v[142:145], v[160:163], v[62:65]
	v_mfma_f32_16x16x32_bf16 v[58:61], v[152:155], v[160:163], v[58:61]
	v_mfma_f32_16x16x32_bf16 v[54:57], v[142:145], v[168:171], v[54:57]
	v_mfma_f32_16x16x32_bf16 v[46:49], v[152:155], v[168:171], v[46:49]
	v_mfma_f32_16x16x32_bf16 v[38:41], v[142:145], v[176:179], v[38:41]
	v_mfma_f32_16x16x32_bf16 v[30:33], v[152:155], v[176:179], v[30:33]
	v_mfma_f32_16x16x32_bf16 v[22:25], v[142:145], v[184:187], v[22:25]
	v_mfma_f32_16x16x32_bf16 v[14:17], v[152:155], v[184:187], v[14:17]
	s_barrier
	s_add_i32 s7, s7, s57
	v_lshl_add_u64 v[138:139], v[132:133], 0, s[20:21]
	s_mov_b32 m0, s7
	s_nop 0
	global_load_lds_dwordx4 v[138:139], off
	v_lshl_add_u64 v[138:139], v[132:133], 0, s[64:65]
	s_add_i32 m0, s7, 0x2000
	s_nop 0
	global_load_lds_dwordx4 v[138:139], off
	v_lshl_add_u64 v[230:231], v[204:205], 0, s[20:21]
	s_mov_b32 m0, s59
	s_nop 0
	global_load_lds_dwordx4 v[230:231], off
	v_lshl_add_u64 v[230:231], v[204:205], 0, s[64:65]
	s_mov_b32 m0, s62
	s_nop 0
	global_load_lds_dwordx4 v[230:231], off
	s_waitcnt vmcnt(8)
	s_barrier
	v_mfma_f32_16x16x32_bf16 v[50:53], v[188:191], v[156:159], v[50:53]
	v_mfma_f32_16x16x32_bf16 v[42:45], v[196:199], v[156:159], v[42:45]
	v_mfma_f32_16x16x32_bf16 v[34:37], v[188:191], v[164:167], v[34:37]
	v_mfma_f32_16x16x32_bf16 v[26:29], v[196:199], v[164:167], v[26:29]
	v_mfma_f32_16x16x32_bf16 v[18:21], v[188:191], v[172:175], v[18:21]
	v_mfma_f32_16x16x32_bf16 v[10:13], v[196:199], v[172:175], v[10:13]
	v_mfma_f32_16x16x32_bf16 v[6:9], v[188:191], v[180:183], v[6:9]
	v_mfma_f32_16x16x32_bf16 v[2:5], v[196:199], v[180:183], v[2:5]
	v_mfma_f32_16x16x32_bf16 v[50:53], v[192:195], v[160:163], v[50:53]
	v_mfma_f32_16x16x32_bf16 v[42:45], v[200:203], v[160:163], v[42:45]
	v_mfma_f32_16x16x32_bf16 v[34:37], v[192:195], v[168:171], v[34:37]
	v_mfma_f32_16x16x32_bf16 v[26:29], v[200:203], v[168:171], v[26:29]
	v_mfma_f32_16x16x32_bf16 v[18:21], v[192:195], v[176:179], v[18:21]
	v_mfma_f32_16x16x32_bf16 v[10:13], v[200:203], v[176:179], v[10:13]
	v_mfma_f32_16x16x32_bf16 v[6:9], v[192:195], v[184:187], v[6:9]
	v_mfma_f32_16x16x32_bf16 v[2:5], v[200:203], v[184:187], v[2:5]
	s_barrier
	s_add_i32 s7, 0, 0x18000
	v_add_u32_e32 v137, s7, v135
	ds_read_b128 v[138:141], v137
	ds_read_b128 v[142:145], v137 offset:1024
	ds_read_b128 v[148:151], v137 offset:2048
	ds_read_b128 v[152:155], v137 offset:3072
	ds_read_b128 v[156:159], v136 offset:32768
	ds_read_b128 v[160:163], v136 offset:33792
	ds_read_b128 v[164:167], v136 offset:34816
	ds_read_b128 v[168:171], v136 offset:35840
	ds_read_b128 v[172:175], v136 offset:36864
	ds_read_b128 v[176:179], v136 offset:37888
	ds_read_b128 v[180:183], v136 offset:38912
	ds_read_b128 v[184:187], v136 offset:39936
	s_waitcnt lgkmcnt(8)
	s_barrier
	s_waitcnt lgkmcnt(0)
	v_mfma_f32_16x16x32_bf16 v[126:129], v[138:141], v[156:159], v[126:129]
	v_mfma_f32_16x16x32_bf16 v[122:125], v[148:151], v[156:159], v[122:125]
	v_mfma_f32_16x16x32_bf16 v[118:121], v[138:141], v[164:167], v[118:121]
	v_mfma_f32_16x16x32_bf16 v[110:113], v[148:151], v[164:167], v[110:113]
	v_mfma_f32_16x16x32_bf16 v[102:105], v[138:141], v[172:175], v[102:105]
	v_mfma_f32_16x16x32_bf16 v[94:97], v[148:151], v[172:175], v[94:97]
	v_mfma_f32_16x16x32_bf16 v[86:89], v[138:141], v[180:183], v[86:89]
	v_mfma_f32_16x16x32_bf16 v[78:81], v[148:151], v[180:183], v[78:81]
	v_mfma_f32_16x16x32_bf16 v[126:129], v[142:145], v[160:163], v[126:129]
	v_mfma_f32_16x16x32_bf16 v[122:125], v[152:155], v[160:163], v[122:125]
	v_mfma_f32_16x16x32_bf16 v[118:121], v[142:145], v[168:171], v[118:121]
	v_mfma_f32_16x16x32_bf16 v[110:113], v[152:155], v[168:171], v[110:113]
	v_mfma_f32_16x16x32_bf16 v[102:105], v[142:145], v[176:179], v[102:105]
	v_mfma_f32_16x16x32_bf16 v[94:97], v[152:155], v[176:179], v[94:97]
	v_mfma_f32_16x16x32_bf16 v[86:89], v[142:145], v[184:187], v[86:89]
	v_mfma_f32_16x16x32_bf16 v[78:81], v[152:155], v[184:187], v[78:81]
	s_barrier
	s_add_i32 s11, 0, 0x1c000
	s_add_i32 s7, s7, s57
	v_add_u32_e32 v137, s11, v135
	v_lshl_add_u64 v[206:207], v[132:133], 0, s[34:35]
	s_mov_b32 m0, s7
	ds_read_b128 v[188:191], v137
	ds_read_b128 v[192:195], v137 offset:1024
	ds_read_b128 v[196:199], v137 offset:2048
	ds_read_b128 v[200:203], v137 offset:3072
	global_load_lds_dwordx4 v[206:207], off
	v_lshl_add_u64 v[206:207], v[132:133], 0, s[66:67]
	s_add_i32 m0, s7, 0x2000
	s_nop 0
	global_load_lds_dwordx4 v[206:207], off
	s_barrier
	s_waitcnt lgkmcnt(0)
	v_mfma_f32_16x16x32_bf16 v[114:117], v[188:191], v[156:159], v[114:117]
	v_mfma_f32_16x16x32_bf16 v[106:109], v[196:199], v[156:159], v[106:109]
	v_mfma_f32_16x16x32_bf16 v[98:101], v[188:191], v[164:167], v[98:101]
	v_mfma_f32_16x16x32_bf16 v[90:93], v[196:199], v[164:167], v[90:93]
	v_mfma_f32_16x16x32_bf16 v[82:85], v[188:191], v[172:175], v[82:85]
	v_mfma_f32_16x16x32_bf16 v[74:77], v[196:199], v[172:175], v[74:77]
	v_mfma_f32_16x16x32_bf16 v[70:73], v[188:191], v[180:183], v[70:73]
	v_mfma_f32_16x16x32_bf16 v[66:69], v[196:199], v[180:183], v[66:69]
	v_mfma_f32_16x16x32_bf16 v[114:117], v[192:195], v[160:163], v[114:117]
	ds_read_b128 v[156:159], v136 offset:49152
	v_mfma_f32_16x16x32_bf16 v[106:109], v[200:203], v[160:163], v[106:109]
	v_mfma_f32_16x16x32_bf16 v[98:101], v[192:195], v[168:171], v[98:101]
	ds_read_b128 v[164:167], v136 offset:51200
	v_mfma_f32_16x16x32_bf16 v[90:93], v[200:203], v[168:171], v[90:93]
	v_mfma_f32_16x16x32_bf16 v[82:85], v[192:195], v[176:179], v[82:85]
	ds_read_b128 v[172:175], v136 offset:53248
	v_mfma_f32_16x16x32_bf16 v[74:77], v[200:203], v[176:179], v[74:77]
	v_mfma_f32_16x16x32_bf16 v[70:73], v[192:195], v[184:187], v[70:73]
	ds_read_b128 v[180:183], v136 offset:55296
	v_mfma_f32_16x16x32_bf16 v[66:69], v[200:203], v[184:187], v[66:69]
	s_barrier
	s_mov_b32 m0, s85
	v_lshl_add_u64 v[206:207], v[204:205], 0, s[34:35]
	ds_read_b128 v[160:163], v136 offset:50176
	ds_read_b128 v[168:171], v136 offset:52224
	ds_read_b128 v[176:179], v136 offset:54272
	ds_read_b128 v[184:187], v136 offset:56320
	global_load_lds_dwordx4 v[206:207], off
	v_lshl_add_u64 v[204:205], v[204:205], 0, s[66:67]
	s_mov_b32 m0, s86
	s_nop 0
	global_load_lds_dwordx4 v[204:205], off
	s_barrier
	s_waitcnt lgkmcnt(0)
	v_mfma_f32_16x16x32_bf16 v[62:65], v[138:141], v[156:159], v[62:65]
	v_mfma_f32_16x16x32_bf16 v[58:61], v[148:151], v[156:159], v[58:61]
	v_mfma_f32_16x16x32_bf16 v[54:57], v[138:141], v[164:167], v[54:57]
	v_mfma_f32_16x16x32_bf16 v[46:49], v[148:151], v[164:167], v[46:49]
	v_mfma_f32_16x16x32_bf16 v[38:41], v[138:141], v[172:175], v[38:41]
	v_mfma_f32_16x16x32_bf16 v[30:33], v[148:151], v[172:175], v[30:33]
	v_mfma_f32_16x16x32_bf16 v[22:25], v[138:141], v[180:183], v[22:25]
	v_mfma_f32_16x16x32_bf16 v[14:17], v[148:151], v[180:183], v[14:17]
	v_mfma_f32_16x16x32_bf16 v[62:65], v[142:145], v[160:163], v[62:65]
	v_mfma_f32_16x16x32_bf16 v[58:61], v[152:155], v[160:163], v[58:61]
	v_mfma_f32_16x16x32_bf16 v[54:57], v[142:145], v[168:171], v[54:57]
	v_mfma_f32_16x16x32_bf16 v[46:49], v[152:155], v[168:171], v[46:49]
	v_mfma_f32_16x16x32_bf16 v[38:41], v[142:145], v[176:179], v[38:41]
	v_mfma_f32_16x16x32_bf16 v[30:33], v[152:155], v[176:179], v[30:33]
	v_mfma_f32_16x16x32_bf16 v[22:25], v[142:145], v[184:187], v[22:25]
	v_mfma_f32_16x16x32_bf16 v[14:17], v[152:155], v[184:187], v[14:17]
	s_barrier
	s_add_i32 s7, s11, s57
	v_lshl_add_u64 v[138:139], v[132:133], 0, s[16:17]
	s_mov_b32 m0, s7
	v_lshl_add_u64 v[132:133], v[132:133], 0, s[80:81]
	global_load_lds_dwordx4 v[138:139], off
	s_add_i32 m0, s7, 0x2000
	s_nop 0
	global_load_lds_dwordx4 v[132:133], off
	s_waitcnt vmcnt(6)
	s_add_i32 s6, s6, 2
	s_add_u32 s8, s8, 0x100
	s_addc_u32 s9, s9, 0
	s_add_u32 s50, s50, 0x100
	s_addc_u32 s51, s51, 0
	s_cmp_gt_u32 s6, 29
	s_cbranch_scc0 .LBB0_97
	s_barrier
	v_mfma_f32_16x16x32_bf16 v[50:53], v[188:191], v[156:159], v[50:53]
	v_mfma_f32_16x16x32_bf16 v[42:45], v[196:199], v[156:159], v[42:45]
	v_mfma_f32_16x16x32_bf16 v[34:37], v[188:191], v[164:167], v[34:37]
	v_mfma_f32_16x16x32_bf16 v[26:29], v[196:199], v[164:167], v[26:29]
	v_mfma_f32_16x16x32_bf16 v[18:21], v[188:191], v[172:175], v[18:21]
	v_mfma_f32_16x16x32_bf16 v[10:13], v[196:199], v[172:175], v[10:13]
	v_mfma_f32_16x16x32_bf16 v[6:9], v[188:191], v[180:183], v[6:9]
	v_mfma_f32_16x16x32_bf16 v[2:5], v[196:199], v[180:183], v[2:5]
	v_mfma_f32_16x16x32_bf16 v[50:53], v[192:195], v[160:163], v[50:53]
	v_mfma_f32_16x16x32_bf16 v[42:45], v[200:203], v[160:163], v[42:45]
	v_mfma_f32_16x16x32_bf16 v[34:37], v[192:195], v[168:171], v[34:37]
	v_mfma_f32_16x16x32_bf16 v[26:29], v[200:203], v[168:171], v[26:29]
	v_mfma_f32_16x16x32_bf16 v[18:21], v[192:195], v[176:179], v[18:21]
	v_mfma_f32_16x16x32_bf16 v[10:13], v[200:203], v[176:179], v[10:13]
	v_mfma_f32_16x16x32_bf16 v[6:9], v[192:195], v[184:187], v[6:9]
	v_mfma_f32_16x16x32_bf16 v[2:5], v[200:203], v[184:187], v[2:5]
	s_barrier
	v_mov_b32_e32 v137, v134
	s_lshl_b32 s6, s88, 8
	v_ashrrev_i32_e32 v132, 2, v137
	s_or_b32 s6, s6, s84
	v_and_b32_e32 v132, -4, v132
	v_add_u32_e32 v132, s6, v132
	s_lshl_b32 s6, s48, 8
	s_add_i32 s6, s6, s63
	v_and_or_b32 v188, v137, 15, s6
	v_ashrrev_i32_e32 v189, 31, v188
	v_ashrrev_i32_e32 v133, 31, v132
	v_lshlrev_b64 v[206:207], 13, v[188:189]
	v_or_b32_e32 v156, 16, v188
	v_or_b32_e32 v172, 32, v188
	v_or_b32_e32 v188, 48, v188
	v_lshlrev_b64 v[132:133], 2, v[132:133]
	v_ashrrev_i32_e32 v157, 31, v156
	v_ashrrev_i32_e32 v173, 31, v172
	v_ashrrev_i32_e32 v189, 31, v188
	v_lshl_add_u64 v[204:205], s[4:5], 0, v[132:133]
	v_lshlrev_b64 v[208:209], 13, v[156:157]
	v_lshlrev_b64 v[210:211], 13, v[172:173]
	v_lshlrev_b64 v[212:213], 13, v[188:189]
	v_lshl_add_u64 v[152:153], v[204:205], 0, v[206:207]
	v_lshl_add_u64 v[168:169], v[204:205], 0, v[208:209]
	v_lshl_add_u64 v[184:185], v[204:205], 0, v[210:211]
	v_lshl_add_u64 v[200:201], v[204:205], 0, v[212:213]
	global_load_dwordx4 v[138:141], v[152:153], off
	global_load_dwordx4 v[142:145], v[152:153], off offset:64
	global_load_dwordx4 v[148:151], v[152:153], off offset:512
	s_nop 0
	global_load_dwordx4 v[152:155], v[152:153], off offset:576
	s_nop 0
	global_load_dwordx4 v[156:159], v[168:169], off
	global_load_dwordx4 v[160:163], v[168:169], off offset:64
	global_load_dwordx4 v[164:167], v[168:169], off offset:512
	s_nop 0
	global_load_dwordx4 v[168:171], v[168:169], off offset:576
	s_nop 0
	global_load_dwordx4 v[172:175], v[184:185], off
	global_load_dwordx4 v[176:179], v[184:185], off offset:64
	global_load_dwordx4 v[180:183], v[184:185], off offset:512
	s_nop 0
	global_load_dwordx4 v[184:187], v[184:185], off offset:576
	s_nop 0
	global_load_dwordx4 v[188:191], v[200:201], off
	global_load_dwordx4 v[192:195], v[200:201], off offset:64
	global_load_dwordx4 v[196:199], v[200:201], off offset:512
	s_nop 0
	global_load_dwordx4 v[200:203], v[200:201], off offset:576
	s_waitcnt vmcnt(0) lgkmcnt(0)
	v_pk_add_f32 v[126:127], v[126:127], v[138:139]
	v_lshl_add_u64 v[138:139], s[4:5], 0, v[206:207]
	v_lshl_add_u64 v[138:139], v[138:139], 0, v[132:133]
	v_pk_add_f32 v[116:117], v[116:117], v[150:151]
	v_pk_add_f32 v[114:115], v[114:115], v[148:149]
	global_store_dwordx4 v[138:139], v[114:117], off offset:512
	v_pk_add_f32 v[100:101], v[100:101], v[166:167]
	v_pk_add_f32 v[98:99], v[98:99], v[164:165]
	v_lshl_add_u64 v[114:115], s[4:5], 0, v[208:209]
	v_lshl_add_u64 v[114:115], v[114:115], 0, v[132:133]
	global_store_dwordx4 v[114:115], v[98:101], off offset:512
	v_pk_add_f32 v[84:85], v[84:85], v[182:183]
	v_pk_add_f32 v[82:83], v[82:83], v[180:181]
	v_lshl_add_u64 v[98:99], s[4:5], 0, v[210:211]
	v_lshl_add_u64 v[98:99], v[98:99], 0, v[132:133]
	v_pk_add_f32 v[108:109], v[108:109], v[154:155]
	v_pk_add_f32 v[106:107], v[106:107], v[152:153]
	v_pk_add_f32 v[92:93], v[92:93], v[170:171]
	v_pk_add_f32 v[90:91], v[90:91], v[168:169]
	global_store_dwordx4 v[98:99], v[82:85], off offset:512
	v_pk_add_f32 v[76:77], v[76:77], v[186:187]
	v_pk_add_f32 v[74:75], v[74:75], v[184:185]
	v_lshl_add_u64 v[82:83], s[4:5], 0, v[212:213]
	global_store_dwordx4 v[138:139], v[106:109], off offset:576
	global_store_dwordx4 v[114:115], v[90:93], off offset:576
	global_store_dwordx4 v[98:99], v[74:77], off offset:576
	v_pk_add_f32 v[108:109], v[120:121], v[158:159]
	v_pk_add_f32 v[106:107], v[118:119], v[156:157]
	v_pk_add_f32 v[92:93], v[104:105], v[174:175]
	v_pk_add_f32 v[90:91], v[102:103], v[172:173]
	v_pk_add_f32 v[76:77], v[88:89], v[190:191]
	v_pk_add_f32 v[74:75], v[86:87], v[188:189]
	v_lshl_add_u64 v[82:83], v[82:83], 0, v[132:133]
	v_pk_add_f32 v[128:129], v[128:129], v[140:141]
	v_pk_add_f32 v[124:125], v[124:125], v[144:145]
	v_pk_add_f32 v[122:123], v[122:123], v[142:143]
	global_store_dwordx4 v[114:115], v[106:109], off
	global_store_dwordx4 v[98:99], v[90:93], off
	global_store_dwordx4 v[82:83], v[74:77], off
	v_pk_add_f32 v[108:109], v[112:113], v[162:163]
	v_pk_add_f32 v[106:107], v[110:111], v[160:161]
	v_pk_add_f32 v[92:93], v[96:97], v[178:179]
	v_pk_add_f32 v[90:91], v[94:95], v[176:177]
	v_pk_add_f32 v[76:77], v[80:81], v[194:195]
	v_pk_add_f32 v[74:75], v[78:79], v[192:193]
	v_pk_add_f32 v[72:73], v[72:73], v[198:199]
	v_pk_add_f32 v[70:71], v[70:71], v[196:197]
	v_pk_add_f32 v[68:69], v[68:69], v[202:203]
	v_pk_add_f32 v[66:67], v[66:67], v[200:201]
	global_store_dwordx4 v[138:139], v[126:129], off
	global_store_dwordx4 v[138:139], v[122:125], off offset:64
	global_store_dwordx4 v[114:115], v[106:109], off offset:64
	global_store_dwordx4 v[98:99], v[90:93], off offset:64
	global_store_dwordx4 v[82:83], v[74:77], off offset:64
	global_store_dwordx4 v[82:83], v[70:73], off offset:512
	global_store_dwordx4 v[82:83], v[66:69], off offset:576
	s_mov_b64 s[6:7], 0x120000
	v_lshl_add_u64 v[140:141], v[206:207], 0, s[6:7]
	s_mov_b64 s[6:7], 0x140000
	v_lshl_add_u64 v[138:139], v[206:207], 0, s[0:1]
	v_lshl_add_u64 v[142:143], v[206:207], 0, s[6:7]
	v_lshl_add_u64 v[144:145], v[206:207], 0, s[28:29]
	v_lshl_add_u64 v[78:79], v[204:205], 0, v[138:139]
	v_lshl_add_u64 v[94:95], v[204:205], 0, v[140:141]
	v_lshl_add_u64 v[110:111], v[204:205], 0, v[142:143]
	v_lshl_add_u64 v[126:127], v[204:205], 0, v[144:145]
	global_load_dwordx4 v[66:69], v[78:79], off
	global_load_dwordx4 v[70:73], v[78:79], off offset:64
	global_load_dwordx4 v[74:77], v[78:79], off offset:512
	s_nop 0
	global_load_dwordx4 v[78:81], v[78:79], off offset:576
	s_nop 0
	global_load_dwordx4 v[82:85], v[94:95], off
	global_load_dwordx4 v[86:89], v[94:95], off offset:64
	global_load_dwordx4 v[90:93], v[94:95], off offset:512
	s_nop 0
	global_load_dwordx4 v[94:97], v[94:95], off offset:576
	s_nop 0
	global_load_dwordx4 v[98:101], v[110:111], off
	global_load_dwordx4 v[102:105], v[110:111], off offset:64
	global_load_dwordx4 v[106:109], v[110:111], off offset:512
	s_nop 0
	global_load_dwordx4 v[110:113], v[110:111], off offset:576
	s_nop 0
	global_load_dwordx4 v[114:117], v[126:127], off
	global_load_dwordx4 v[118:121], v[126:127], off offset:64
	global_load_dwordx4 v[122:125], v[126:127], off offset:512
	s_nop 0
	global_load_dwordx4 v[126:129], v[126:127], off offset:576
	s_waitcnt vmcnt(0) lgkmcnt(0)
	v_pk_add_f32 v[62:63], v[62:63], v[66:67]
	v_lshl_add_u64 v[66:67], s[4:5], 0, v[138:139]
	v_lshl_add_u64 v[66:67], v[66:67], 0, v[132:133]
	v_pk_add_f32 v[52:53], v[52:53], v[76:77]
	v_pk_add_f32 v[50:51], v[50:51], v[74:75]
	global_store_dwordx4 v[66:67], v[50:53], off offset:512
	v_pk_add_f32 v[36:37], v[36:37], v[92:93]
	v_pk_add_f32 v[34:35], v[34:35], v[90:91]
	v_lshl_add_u64 v[50:51], s[4:5], 0, v[140:141]
	v_lshl_add_u64 v[50:51], v[50:51], 0, v[132:133]
	global_store_dwordx4 v[50:51], v[34:37], off offset:512
	v_pk_add_f32 v[20:21], v[20:21], v[108:109]
	v_pk_add_f32 v[18:19], v[18:19], v[106:107]
	v_lshl_add_u64 v[34:35], s[4:5], 0, v[142:143]
	v_lshl_add_u64 v[34:35], v[34:35], 0, v[132:133]
	v_pk_add_f32 v[44:45], v[44:45], v[80:81]
	v_pk_add_f32 v[42:43], v[42:43], v[78:79]
	v_pk_add_f32 v[28:29], v[28:29], v[96:97]
	v_pk_add_f32 v[26:27], v[26:27], v[94:95]
	global_store_dwordx4 v[34:35], v[18:21], off offset:512
	v_pk_add_f32 v[12:13], v[12:13], v[112:113]
	v_pk_add_f32 v[10:11], v[10:11], v[110:111]
	v_lshl_add_u64 v[18:19], s[4:5], 0, v[144:145]
	global_store_dwordx4 v[66:67], v[42:45], off offset:576
	global_store_dwordx4 v[50:51], v[26:29], off offset:576
	global_store_dwordx4 v[34:35], v[10:13], off offset:576
	v_pk_add_f32 v[44:45], v[56:57], v[84:85]
	v_pk_add_f32 v[42:43], v[54:55], v[82:83]
	v_pk_add_f32 v[28:29], v[40:41], v[100:101]
	v_pk_add_f32 v[26:27], v[38:39], v[98:99]
	v_pk_add_f32 v[12:13], v[24:25], v[116:117]
	v_pk_add_f32 v[10:11], v[22:23], v[114:115]
	v_lshl_add_u64 v[18:19], v[18:19], 0, v[132:133]
	v_pk_add_f32 v[64:65], v[64:65], v[68:69]
	v_pk_add_f32 v[60:61], v[60:61], v[72:73]
	v_pk_add_f32 v[58:59], v[58:59], v[70:71]
	global_store_dwordx4 v[50:51], v[42:45], off
	global_store_dwordx4 v[34:35], v[26:29], off
	global_store_dwordx4 v[18:19], v[10:13], off
	v_pk_add_f32 v[44:45], v[48:49], v[88:89]
	v_pk_add_f32 v[42:43], v[46:47], v[86:87]
	v_pk_add_f32 v[28:29], v[32:33], v[104:105]
	v_pk_add_f32 v[26:27], v[30:31], v[102:103]
	v_pk_add_f32 v[12:13], v[16:17], v[120:121]
	v_pk_add_f32 v[10:11], v[14:15], v[118:119]
	v_pk_add_f32 v[8:9], v[8:9], v[124:125]
	v_pk_add_f32 v[6:7], v[6:7], v[122:123]
	v_pk_add_f32 v[4:5], v[4:5], v[128:129]
	v_pk_add_f32 v[2:3], v[2:3], v[126:127]
	global_store_dwordx4 v[66:67], v[62:65], off
	global_store_dwordx4 v[66:67], v[58:61], off offset:64
	global_store_dwordx4 v[50:51], v[42:45], off offset:64
	global_store_dwordx4 v[34:35], v[26:29], off offset:64
	global_store_dwordx4 v[18:19], v[10:13], off offset:64
	global_store_dwordx4 v[18:19], v[6:9], off offset:512
	global_store_dwordx4 v[18:19], v[2:5], off offset:576
	v_readlane_b32 s50, v255, 28
	s_and_b64 vcc, exec, s[40:41]
	s_mov_b32 s48, s42
	s_mov_b32 s88, s10
	s_mov_b64 s[8:9], s[46:47]
	s_mov_b64 s[6:7], s[44:45]
	v_readlane_b32 s51, v255, 29
	s_movk_i32 s91, 0x60
	s_mov_b32 s78, 0x2a000000
	s_mov_b32 s79, 0x3fffe
	s_mov_b32 s90, 0xc0000
	s_cbranch_vccz .LBB0_90
	s_waitcnt vmcnt(0)
	s_cmpk_gt_u32 s52, 0xff
	s_cbranch_scc1 .LBB0_101
	s_barrier

.Lrot_enter_7:
	s_add_u32 s6, s4, 0x100
	s_addc_u32 s7, s5, 0
	s_add_i32 s11, 0, 0x10000
	v_add_u32_e32 v138, s11, v141
	ds_read_b128 v[130:133], v138
	ds_read_b128 v[148:151], v138 offset:1024
	ds_read_b128 v[152:155], v138 offset:2048
	ds_read_b128 v[156:159], v138 offset:3072
	s_cmp_eq_u32 s10, 28
	s_cselect_b32 s41, s47, s7
	s_cselect_b32 s40, s46, s6
	s_cselect_b32 s93, s49, s9
	s_cselect_b32 s92, s48, s8
	v_lshl_add_u64 v[144:145], s[4:5], 0, v[136:137]
	v_lshl_add_u64 v[192:193], v[144:145], 0, s[16:17]
	s_add_i32 m0, s54, 0xc000
	ds_read_b128 v[160:163], v142
	ds_read_b128 v[164:167], v142 offset:1024
	ds_read_b128 v[168:171], v142 offset:2048
	ds_read_b128 v[172:175], v142 offset:3072
	ds_read_b128 v[176:179], v142 offset:4096
	ds_read_b128 v[180:183], v142 offset:5120
	ds_read_b128 v[184:187], v142 offset:6144
	ds_read_b128 v[188:191], v142 offset:7168
	global_load_lds_dwordx4 v[192:193], off
	v_lshl_add_u64 v[144:145], v[144:145], 0, s[80:81]
	s_add_i32 m0, s54, 0xe000
	s_nop 0
	global_load_lds_dwordx4 v[144:145], off
	s_waitcnt lgkmcnt(8)
	s_barrier
	s_waitcnt lgkmcnt(0)
	v_mfma_f32_16x16x32_bf16 v[126:129], v[130:133], v[160:163], v[126:129]
	v_mfma_f32_16x16x32_bf16 v[122:125], v[152:155], v[160:163], v[122:125]
	v_mfma_f32_16x16x32_bf16 v[110:113], v[130:133], v[168:171], v[110:113]
	v_mfma_f32_16x16x32_bf16 v[106:109], v[152:155], v[168:171], v[106:109]
	v_mfma_f32_16x16x32_bf16 v[94:97], v[130:133], v[176:179], v[94:97]
	v_mfma_f32_16x16x32_bf16 v[90:93], v[152:155], v[176:179], v[90:93]
	v_mfma_f32_16x16x32_bf16 v[78:81], v[130:133], v[184:187], v[78:81]
	v_mfma_f32_16x16x32_bf16 v[74:77], v[152:155], v[184:187], v[74:77]
	v_mfma_f32_16x16x32_bf16 v[126:129], v[148:151], v[164:167], v[126:129]
	v_mfma_f32_16x16x32_bf16 v[122:125], v[156:159], v[164:167], v[122:125]
	v_mfma_f32_16x16x32_bf16 v[110:113], v[148:151], v[172:175], v[110:113]
	v_mfma_f32_16x16x32_bf16 v[106:109], v[156:159], v[172:175], v[106:109]
	v_mfma_f32_16x16x32_bf16 v[94:97], v[148:151], v[180:183], v[94:97]
	v_mfma_f32_16x16x32_bf16 v[90:93], v[156:159], v[180:183], v[90:93]
	v_mfma_f32_16x16x32_bf16 v[78:81], v[148:151], v[188:191], v[78:81]
	v_mfma_f32_16x16x32_bf16 v[74:77], v[156:159], v[188:191], v[74:77]
	s_barrier
	s_add_i32 s4, 0, 0x14000
	s_add_i32 s5, s11, s53
	v_add_u32_e32 v138, s4, v141
	v_lshl_add_u64 v[144:145], s[92:93], 0, v[0:1]
	s_mov_b32 m0, s5
	ds_read_b128 v[192:195], v138
	ds_read_b128 v[196:199], v138 offset:1024
	ds_read_b128 v[200:203], v138 offset:2048
	ds_read_b128 v[204:207], v138 offset:3072
	global_load_lds_dwordx4 v[144:145], off
	v_lshl_add_u64 v[208:209], v[144:145], 0, s[60:61]
	s_add_i32 m0, s5, 0x2000
	s_nop 0
	global_load_lds_dwordx4 v[208:209], off
	s_barrier
	s_waitcnt lgkmcnt(0)
	v_mfma_f32_16x16x32_bf16 v[118:121], v[192:195], v[160:163], v[118:121]
	v_mfma_f32_16x16x32_bf16 v[114:117], v[200:203], v[160:163], v[114:117]
	v_mfma_f32_16x16x32_bf16 v[102:105], v[192:195], v[168:171], v[102:105]
	v_mfma_f32_16x16x32_bf16 v[98:101], v[200:203], v[168:171], v[98:101]
	v_mfma_f32_16x16x32_bf16 v[86:89], v[192:195], v[176:179], v[86:89]
	v_mfma_f32_16x16x32_bf16 v[82:85], v[200:203], v[176:179], v[82:85]
	v_mfma_f32_16x16x32_bf16 v[70:73], v[192:195], v[184:187], v[70:73]
	v_mfma_f32_16x16x32_bf16 v[66:69], v[200:203], v[184:187], v[66:69]
	v_mfma_f32_16x16x32_bf16 v[118:121], v[196:199], v[164:167], v[118:121]
	ds_read_b128 v[160:163], v142 offset:16384
	v_mfma_f32_16x16x32_bf16 v[114:117], v[204:207], v[164:167], v[114:117]
	v_mfma_f32_16x16x32_bf16 v[102:105], v[196:199], v[172:175], v[102:105]
	ds_read_b128 v[168:171], v142 offset:18432
	v_mfma_f32_16x16x32_bf16 v[98:101], v[204:207], v[172:175], v[98:101]
	v_mfma_f32_16x16x32_bf16 v[86:89], v[196:199], v[180:183], v[86:89]
	ds_read_b128 v[176:179], v142 offset:20480
	v_mfma_f32_16x16x32_bf16 v[82:85], v[204:207], v[180:183], v[82:85]
	v_mfma_f32_16x16x32_bf16 v[70:73], v[196:199], v[188:191], v[70:73]
	ds_read_b128 v[184:187], v142 offset:22528
	v_mfma_f32_16x16x32_bf16 v[66:69], v[204:207], v[188:191], v[66:69]
	s_barrier
	s_mov_b32 m0, s54
	v_lshl_add_u64 v[208:209], s[40:41], 0, v[134:135]
	ds_read_b128 v[164:167], v142 offset:17408
	ds_read_b128 v[172:175], v142 offset:19456
	ds_read_b128 v[180:183], v142 offset:21504
	ds_read_b128 v[188:191], v142 offset:23552
	global_load_lds_dwordx4 v[208:209], off
	v_lshl_add_u64 v[210:211], v[208:209], 0, s[60:61]
	s_mov_b32 m0, s55
	s_nop 0
	global_load_lds_dwordx4 v[210:211], off
	s_barrier
	s_waitcnt lgkmcnt(0)
	v_mfma_f32_16x16x32_bf16 v[62:65], v[130:133], v[160:163], v[62:65]
	v_mfma_f32_16x16x32_bf16 v[58:61], v[152:155], v[160:163], v[58:61]
	v_mfma_f32_16x16x32_bf16 v[46:49], v[130:133], v[168:171], v[46:49]
	v_mfma_f32_16x16x32_bf16 v[42:45], v[152:155], v[168:171], v[42:45]
	v_mfma_f32_16x16x32_bf16 v[30:33], v[130:133], v[176:179], v[30:33]
	v_mfma_f32_16x16x32_bf16 v[26:29], v[152:155], v[176:179], v[26:29]
	v_mfma_f32_16x16x32_bf16 v[14:17], v[130:133], v[184:187], v[14:17]
	v_mfma_f32_16x16x32_bf16 v[10:13], v[152:155], v[184:187], v[10:13]
	v_mfma_f32_16x16x32_bf16 v[62:65], v[148:151], v[164:167], v[62:65]
	v_mfma_f32_16x16x32_bf16 v[58:61], v[156:159], v[164:167], v[58:61]
	v_mfma_f32_16x16x32_bf16 v[46:49], v[148:151], v[172:175], v[46:49]
	v_mfma_f32_16x16x32_bf16 v[42:45], v[156:159], v[172:175], v[42:45]
	v_mfma_f32_16x16x32_bf16 v[30:33], v[148:151], v[180:183], v[30:33]
	v_mfma_f32_16x16x32_bf16 v[26:29], v[156:159], v[180:183], v[26:29]
	v_mfma_f32_16x16x32_bf16 v[14:17], v[148:151], v[188:191], v[14:17]
	v_mfma_f32_16x16x32_bf16 v[10:13], v[156:159], v[188:191], v[10:13]
	s_barrier
	s_add_i32 s4, s4, s53
	v_lshl_add_u64 v[130:131], v[144:145], 0, s[20:21]
	s_mov_b32 m0, s4
	s_nop 0
	global_load_lds_dwordx4 v[130:131], off
	v_lshl_add_u64 v[130:131], v[144:145], 0, s[64:65]
	s_add_i32 m0, s4, 0x2000
	s_nop 0
	global_load_lds_dwordx4 v[130:131], off
	v_lshl_add_u64 v[230:231], v[208:209], 0, s[20:21]
	s_mov_b32 m0, s56
	s_nop 0
	global_load_lds_dwordx4 v[230:231], off
	v_lshl_add_u64 v[230:231], v[208:209], 0, s[64:65]
	s_mov_b32 m0, s57
	s_nop 0
	global_load_lds_dwordx4 v[230:231], off
	s_waitcnt vmcnt(8)
	s_barrier
	v_mfma_f32_16x16x32_bf16 v[54:57], v[192:195], v[160:163], v[54:57]
	v_mfma_f32_16x16x32_bf16 v[50:53], v[200:203], v[160:163], v[50:53]
	v_mfma_f32_16x16x32_bf16 v[38:41], v[192:195], v[168:171], v[38:41]
	v_mfma_f32_16x16x32_bf16 v[34:37], v[200:203], v[168:171], v[34:37]
	v_mfma_f32_16x16x32_bf16 v[22:25], v[192:195], v[176:179], v[22:25]
	v_mfma_f32_16x16x32_bf16 v[18:21], v[200:203], v[176:179], v[18:21]
	v_mfma_f32_16x16x32_bf16 v[6:9], v[192:195], v[184:187], v[6:9]
	v_mfma_f32_16x16x32_bf16 v[2:5], v[200:203], v[184:187], v[2:5]
	v_mfma_f32_16x16x32_bf16 v[54:57], v[196:199], v[164:167], v[54:57]
	v_mfma_f32_16x16x32_bf16 v[50:53], v[204:207], v[164:167], v[50:53]
	v_mfma_f32_16x16x32_bf16 v[38:41], v[196:199], v[172:175], v[38:41]
	v_mfma_f32_16x16x32_bf16 v[34:37], v[204:207], v[172:175], v[34:37]
	v_mfma_f32_16x16x32_bf16 v[22:25], v[196:199], v[180:183], v[22:25]
	v_mfma_f32_16x16x32_bf16 v[18:21], v[204:207], v[180:183], v[18:21]
	v_mfma_f32_16x16x32_bf16 v[6:9], v[196:199], v[188:191], v[6:9]
	v_mfma_f32_16x16x32_bf16 v[2:5], v[204:207], v[188:191], v[2:5]
	s_barrier
	s_add_i32 s4, 0, 0x18000
	v_add_u32_e32 v138, s4, v141
	ds_read_b128 v[130:133], v138
	ds_read_b128 v[148:151], v138 offset:1024
	ds_read_b128 v[152:155], v138 offset:2048
	ds_read_b128 v[156:159], v138 offset:3072
	ds_read_b128 v[160:163], v142 offset:32768
	ds_read_b128 v[164:167], v142 offset:33792
	ds_read_b128 v[168:171], v142 offset:34816
	ds_read_b128 v[172:175], v142 offset:35840
	ds_read_b128 v[176:179], v142 offset:36864
	ds_read_b128 v[180:183], v142 offset:37888
	ds_read_b128 v[184:187], v142 offset:38912
	ds_read_b128 v[188:191], v142 offset:39936
	s_waitcnt lgkmcnt(8)
	s_barrier
	s_waitcnt lgkmcnt(0)
	v_mfma_f32_16x16x32_bf16 v[126:129], v[130:133], v[160:163], v[126:129]
	v_mfma_f32_16x16x32_bf16 v[122:125], v[152:155], v[160:163], v[122:125]
	v_mfma_f32_16x16x32_bf16 v[110:113], v[130:133], v[168:171], v[110:113]
	v_mfma_f32_16x16x32_bf16 v[106:109], v[152:155], v[168:171], v[106:109]
	v_mfma_f32_16x16x32_bf16 v[94:97], v[130:133], v[176:179], v[94:97]
	v_mfma_f32_16x16x32_bf16 v[90:93], v[152:155], v[176:179], v[90:93]
	v_mfma_f32_16x16x32_bf16 v[78:81], v[130:133], v[184:187], v[78:81]
	v_mfma_f32_16x16x32_bf16 v[74:77], v[152:155], v[184:187], v[74:77]
	v_mfma_f32_16x16x32_bf16 v[126:129], v[148:151], v[164:167], v[126:129]
	v_mfma_f32_16x16x32_bf16 v[122:125], v[156:159], v[164:167], v[122:125]
	v_mfma_f32_16x16x32_bf16 v[110:113], v[148:151], v[172:175], v[110:113]
	v_mfma_f32_16x16x32_bf16 v[106:109], v[156:159], v[172:175], v[106:109]
	v_mfma_f32_16x16x32_bf16 v[94:97], v[148:151], v[180:183], v[94:97]
	v_mfma_f32_16x16x32_bf16 v[90:93], v[156:159], v[180:183], v[90:93]
	v_mfma_f32_16x16x32_bf16 v[78:81], v[148:151], v[188:191], v[78:81]
	v_mfma_f32_16x16x32_bf16 v[74:77], v[156:159], v[188:191], v[74:77]
	s_barrier
	s_add_i32 s5, 0, 0x1c000
	s_add_i32 s4, s4, s53
	v_add_u32_e32 v138, s5, v141
	v_lshl_add_u64 v[210:211], v[144:145], 0, s[34:35]
	s_mov_b32 m0, s4
	ds_read_b128 v[192:195], v138
	ds_read_b128 v[196:199], v138 offset:1024
	ds_read_b128 v[200:203], v138 offset:2048
	ds_read_b128 v[204:207], v138 offset:3072
	global_load_lds_dwordx4 v[210:211], off
	v_lshl_add_u64 v[210:211], v[144:145], 0, s[66:67]
	s_add_i32 m0, s4, 0x2000
	s_nop 0
	global_load_lds_dwordx4 v[210:211], off
	s_barrier
	s_waitcnt lgkmcnt(0)
	v_mfma_f32_16x16x32_bf16 v[118:121], v[192:195], v[160:163], v[118:121]
	v_mfma_f32_16x16x32_bf16 v[114:117], v[200:203], v[160:163], v[114:117]
	v_mfma_f32_16x16x32_bf16 v[102:105], v[192:195], v[168:171], v[102:105]
	v_mfma_f32_16x16x32_bf16 v[98:101], v[200:203], v[168:171], v[98:101]
	v_mfma_f32_16x16x32_bf16 v[86:89], v[192:195], v[176:179], v[86:89]
	v_mfma_f32_16x16x32_bf16 v[82:85], v[200:203], v[176:179], v[82:85]
	v_mfma_f32_16x16x32_bf16 v[70:73], v[192:195], v[184:187], v[70:73]
	v_mfma_f32_16x16x32_bf16 v[66:69], v[200:203], v[184:187], v[66:69]
	v_mfma_f32_16x16x32_bf16 v[118:121], v[196:199], v[164:167], v[118:121]
	ds_read_b128 v[160:163], v142 offset:49152
	v_mfma_f32_16x16x32_bf16 v[114:117], v[204:207], v[164:167], v[114:117]
	v_mfma_f32_16x16x32_bf16 v[102:105], v[196:199], v[172:175], v[102:105]
	ds_read_b128 v[168:171], v142 offset:51200
	v_mfma_f32_16x16x32_bf16 v[98:101], v[204:207], v[172:175], v[98:101]
	v_mfma_f32_16x16x32_bf16 v[86:89], v[196:199], v[180:183], v[86:89]
	ds_read_b128 v[176:179], v142 offset:53248
	v_mfma_f32_16x16x32_bf16 v[82:85], v[204:207], v[180:183], v[82:85]
	v_mfma_f32_16x16x32_bf16 v[70:73], v[196:199], v[188:191], v[70:73]
	ds_read_b128 v[184:187], v142 offset:55296
	v_mfma_f32_16x16x32_bf16 v[66:69], v[204:207], v[188:191], v[66:69]
	s_barrier
	s_mov_b32 m0, s62
	v_lshl_add_u64 v[210:211], v[208:209], 0, s[34:35]
	ds_read_b128 v[164:167], v142 offset:50176
	ds_read_b128 v[172:175], v142 offset:52224
	ds_read_b128 v[180:183], v142 offset:54272
	ds_read_b128 v[188:191], v142 offset:56320
	global_load_lds_dwordx4 v[210:211], off
	v_lshl_add_u64 v[208:209], v[208:209], 0, s[66:67]
	s_mov_b32 m0, s63
	s_nop 0
	global_load_lds_dwordx4 v[208:209], off
	s_barrier
	s_waitcnt lgkmcnt(0)
	v_mfma_f32_16x16x32_bf16 v[62:65], v[130:133], v[160:163], v[62:65]
	v_mfma_f32_16x16x32_bf16 v[58:61], v[152:155], v[160:163], v[58:61]
	v_mfma_f32_16x16x32_bf16 v[46:49], v[130:133], v[168:171], v[46:49]
	v_mfma_f32_16x16x32_bf16 v[42:45], v[152:155], v[168:171], v[42:45]
	v_mfma_f32_16x16x32_bf16 v[30:33], v[130:133], v[176:179], v[30:33]
	v_mfma_f32_16x16x32_bf16 v[26:29], v[152:155], v[176:179], v[26:29]
	v_mfma_f32_16x16x32_bf16 v[14:17], v[130:133], v[184:187], v[14:17]
	v_mfma_f32_16x16x32_bf16 v[10:13], v[152:155], v[184:187], v[10:13]
	v_mfma_f32_16x16x32_bf16 v[62:65], v[148:151], v[164:167], v[62:65]
	v_mfma_f32_16x16x32_bf16 v[58:61], v[156:159], v[164:167], v[58:61]
	v_mfma_f32_16x16x32_bf16 v[46:49], v[148:151], v[172:175], v[46:49]
	v_mfma_f32_16x16x32_bf16 v[42:45], v[156:159], v[172:175], v[42:45]
	v_mfma_f32_16x16x32_bf16 v[30:33], v[148:151], v[180:183], v[30:33]
	v_mfma_f32_16x16x32_bf16 v[26:29], v[156:159], v[180:183], v[26:29]
	v_mfma_f32_16x16x32_bf16 v[14:17], v[148:151], v[188:191], v[14:17]
	v_mfma_f32_16x16x32_bf16 v[10:13], v[156:159], v[188:191], v[10:13]
	s_barrier
	s_add_i32 s4, s5, s53
	v_lshl_add_u64 v[130:131], v[144:145], 0, s[16:17]
	s_mov_b32 m0, s4
	s_nop 0
	global_load_lds_dwordx4 v[130:131], off
	v_lshl_add_u64 v[130:131], v[144:145], 0, s[80:81]
	s_add_i32 m0, s4, 0x2000
	s_nop 0
	global_load_lds_dwordx4 v[130:131], off
	s_waitcnt vmcnt(6)
	s_add_i32 s10, s10, 2
	s_add_u32 s8, s8, 0x100
	s_addc_u32 s9, s9, 0
	s_cmp_gt_u32 s10, 29
	s_mov_b64 s[4:5], s[6:7]
	s_cbranch_scc0 .LBB0_292
	s_barrier
	v_mfma_f32_16x16x32_bf16 v[54:57], v[192:195], v[160:163], v[54:57]
	v_mfma_f32_16x16x32_bf16 v[50:53], v[200:203], v[160:163], v[50:53]
	v_mfma_f32_16x16x32_bf16 v[38:41], v[192:195], v[168:171], v[38:41]
	v_mfma_f32_16x16x32_bf16 v[34:37], v[200:203], v[168:171], v[34:37]
	v_mfma_f32_16x16x32_bf16 v[22:25], v[192:195], v[176:179], v[22:25]
	v_mfma_f32_16x16x32_bf16 v[18:21], v[200:203], v[176:179], v[18:21]
	v_mfma_f32_16x16x32_bf16 v[6:9], v[192:195], v[184:187], v[6:9]
	v_mfma_f32_16x16x32_bf16 v[2:5], v[200:203], v[184:187], v[2:5]
	v_mfma_f32_16x16x32_bf16 v[54:57], v[196:199], v[164:167], v[54:57]
	v_mfma_f32_16x16x32_bf16 v[50:53], v[204:207], v[164:167], v[50:53]
	v_mfma_f32_16x16x32_bf16 v[38:41], v[196:199], v[172:175], v[38:41]
	v_mfma_f32_16x16x32_bf16 v[34:37], v[204:207], v[172:175], v[34:37]
	v_mfma_f32_16x16x32_bf16 v[22:25], v[196:199], v[180:183], v[22:25]
	v_mfma_f32_16x16x32_bf16 v[18:21], v[204:207], v[180:183], v[18:21]
	v_mfma_f32_16x16x32_bf16 v[6:9], v[196:199], v[188:191], v[6:9]
	v_mfma_f32_16x16x32_bf16 v[2:5], v[204:207], v[188:191], v[2:5]
	s_barrier
	s_cmp_eq_u32 s52, 3
	v_mov_b32_e32 v144, v139
	s_cselect_b64 s[4:5], -1, 0
	s_cmp_lt_i32 s52, 5
	s_cbranch_scc1 .LBB0_295
	s_cmp_eq_u32 s52, 5
	s_cselect_b64 s[6:7], -1, 0
	s_movk_i32 s93, 0xf800
	s_cbranch_execz .LBB0_296
	s_branch .LBB0_297

.Lrot_enter_6:
	s_add_u32 s7, s46, 0xffea0080
	s_addc_u32 s78, s47, -1
	s_add_i32 s79, 0, 0x10000
	v_add_u32_e32 v132, s79, v135
	ds_read_b128 v[138:141], v132
	ds_read_b128 v[142:145], v132 offset:1024
	ds_read_b128 v[148:151], v132 offset:2048
	ds_read_b128 v[152:155], v132 offset:3072
	s_cmpk_eq_i32 s6, 0x54
	s_cselect_b32 s89, s43, s78
	s_cselect_b32 s88, s42, s7
	s_cselect_b32 s91, s45, s9
	s_cselect_b32 s90, s44, s8
	v_lshl_add_u64 v[132:133], s[46:47], 0, v[130:131]
	s_add_i32 m0, s54, 0xc000
	ds_read_b128 v[156:159], v136
	ds_read_b128 v[160:163], v136 offset:1024
	ds_read_b128 v[164:167], v136 offset:2048
	ds_read_b128 v[168:171], v136 offset:3072
	ds_read_b128 v[172:175], v136 offset:4096
	ds_read_b128 v[176:179], v136 offset:5120
	ds_read_b128 v[180:183], v136 offset:6144
	ds_read_b128 v[184:187], v136 offset:7168
	global_load_lds_dwordx4 v[132:133], off
	v_lshl_add_u64 v[132:133], v[132:133], 0, s[26:27]
	s_add_i32 m0, s54, 0xe000
	s_nop 0
	global_load_lds_dwordx4 v[132:133], off
	s_waitcnt lgkmcnt(8)
	s_barrier
	s_waitcnt lgkmcnt(0)
	v_mfma_f32_16x16x32_bf16 v[126:129], v[138:141], v[156:159], v[126:129]
	v_mfma_f32_16x16x32_bf16 v[122:125], v[148:151], v[156:159], v[122:125]
	v_mfma_f32_16x16x32_bf16 v[118:121], v[138:141], v[164:167], v[118:121]
	v_mfma_f32_16x16x32_bf16 v[110:113], v[148:151], v[164:167], v[110:113]
	v_mfma_f32_16x16x32_bf16 v[102:105], v[138:141], v[172:175], v[102:105]
	v_mfma_f32_16x16x32_bf16 v[94:97], v[148:151], v[172:175], v[94:97]
	v_mfma_f32_16x16x32_bf16 v[86:89], v[138:141], v[180:183], v[86:89]
	v_mfma_f32_16x16x32_bf16 v[78:81], v[148:151], v[180:183], v[78:81]
	v_mfma_f32_16x16x32_bf16 v[126:129], v[142:145], v[160:163], v[126:129]
	v_mfma_f32_16x16x32_bf16 v[122:125], v[152:155], v[160:163], v[122:125]
	v_mfma_f32_16x16x32_bf16 v[118:121], v[142:145], v[168:171], v[118:121]
	v_mfma_f32_16x16x32_bf16 v[110:113], v[152:155], v[168:171], v[110:113]
	v_mfma_f32_16x16x32_bf16 v[102:105], v[142:145], v[176:179], v[102:105]
	v_mfma_f32_16x16x32_bf16 v[94:97], v[152:155], v[176:179], v[94:97]
	v_mfma_f32_16x16x32_bf16 v[86:89], v[142:145], v[184:187], v[86:89]
	v_mfma_f32_16x16x32_bf16 v[78:81], v[152:155], v[184:187], v[78:81]
	s_barrier
	s_add_i32 s7, 0, 0x14000
	v_add_u32_e32 v132, s7, v135
	s_add_i32 s78, s79, s53
	ds_read_b128 v[188:191], v132
	ds_read_b128 v[192:195], v132 offset:1024
	ds_read_b128 v[196:199], v132 offset:2048
	ds_read_b128 v[200:203], v132 offset:3072
	v_lshl_add_u64 v[132:133], s[90:91], 0, v[0:1]
	s_mov_b32 m0, s78
	v_lshl_add_u64 v[204:205], v[132:133], 0, s[26:27]
	global_load_lds_dwordx4 v[132:133], off
	s_add_i32 m0, s78, 0x2000
	s_nop 0
	global_load_lds_dwordx4 v[204:205], off
	s_barrier
	s_waitcnt lgkmcnt(0)
	v_mfma_f32_16x16x32_bf16 v[114:117], v[188:191], v[156:159], v[114:117]
	v_mfma_f32_16x16x32_bf16 v[106:109], v[196:199], v[156:159], v[106:109]
	v_mfma_f32_16x16x32_bf16 v[98:101], v[188:191], v[164:167], v[98:101]
	v_mfma_f32_16x16x32_bf16 v[90:93], v[196:199], v[164:167], v[90:93]
	v_mfma_f32_16x16x32_bf16 v[82:85], v[188:191], v[172:175], v[82:85]
	v_mfma_f32_16x16x32_bf16 v[74:77], v[196:199], v[172:175], v[74:77]
	v_mfma_f32_16x16x32_bf16 v[70:73], v[188:191], v[180:183], v[70:73]
	v_mfma_f32_16x16x32_bf16 v[66:69], v[196:199], v[180:183], v[66:69]
	v_mfma_f32_16x16x32_bf16 v[114:117], v[192:195], v[160:163], v[114:117]
	ds_read_b128 v[156:159], v136 offset:16384
	v_mfma_f32_16x16x32_bf16 v[106:109], v[200:203], v[160:163], v[106:109]
	v_mfma_f32_16x16x32_bf16 v[98:101], v[192:195], v[168:171], v[98:101]
	ds_read_b128 v[164:167], v136 offset:18432
	v_mfma_f32_16x16x32_bf16 v[90:93], v[200:203], v[168:171], v[90:93]
	v_mfma_f32_16x16x32_bf16 v[82:85], v[192:195], v[176:179], v[82:85]
	ds_read_b128 v[172:175], v136 offset:20480
	v_mfma_f32_16x16x32_bf16 v[74:77], v[200:203], v[176:179], v[74:77]
	v_mfma_f32_16x16x32_bf16 v[70:73], v[192:195], v[184:187], v[70:73]
	ds_read_b128 v[180:183], v136 offset:22528
	v_mfma_f32_16x16x32_bf16 v[66:69], v[200:203], v[184:187], v[66:69]
	s_barrier
	s_mov_b32 m0, s54
	v_lshl_add_u64 v[204:205], s[88:89], 0, v[0:1]
	ds_read_b128 v[160:163], v136 offset:17408
	ds_read_b128 v[168:171], v136 offset:19456
	ds_read_b128 v[176:179], v136 offset:21504
	ds_read_b128 v[184:187], v136 offset:23552
	global_load_lds_dwordx4 v[204:205], off
	v_lshl_add_u64 v[206:207], v[204:205], 0, s[26:27]
	s_mov_b32 m0, s55
	s_nop 0
	global_load_lds_dwordx4 v[206:207], off
	s_barrier
	s_waitcnt lgkmcnt(0)
	v_mfma_f32_16x16x32_bf16 v[62:65], v[138:141], v[156:159], v[62:65]
	v_mfma_f32_16x16x32_bf16 v[58:61], v[148:151], v[156:159], v[58:61]
	v_mfma_f32_16x16x32_bf16 v[54:57], v[138:141], v[164:167], v[54:57]
	v_mfma_f32_16x16x32_bf16 v[46:49], v[148:151], v[164:167], v[46:49]
	v_mfma_f32_16x16x32_bf16 v[38:41], v[138:141], v[172:175], v[38:41]
	v_mfma_f32_16x16x32_bf16 v[30:33], v[148:151], v[172:175], v[30:33]
	v_mfma_f32_16x16x32_bf16 v[22:25], v[138:141], v[180:183], v[22:25]
	v_mfma_f32_16x16x32_bf16 v[14:17], v[148:151], v[180:183], v[14:17]
	v_mfma_f32_16x16x32_bf16 v[62:65], v[142:145], v[160:163], v[62:65]
	v_mfma_f32_16x16x32_bf16 v[58:61], v[152:155], v[160:163], v[58:61]
	v_mfma_f32_16x16x32_bf16 v[54:57], v[142:145], v[168:171], v[54:57]
	v_mfma_f32_16x16x32_bf16 v[46:49], v[152:155], v[168:171], v[46:49]
	v_mfma_f32_16x16x32_bf16 v[38:41], v[142:145], v[176:179], v[38:41]
	v_mfma_f32_16x16x32_bf16 v[30:33], v[152:155], v[176:179], v[30:33]
	v_mfma_f32_16x16x32_bf16 v[22:25], v[142:145], v[184:187], v[22:25]
	v_mfma_f32_16x16x32_bf16 v[14:17], v[152:155], v[184:187], v[14:17]
	s_barrier
	s_add_i32 s7, s7, s53
	v_lshl_add_u64 v[138:139], v[132:133], 0, s[28:29]
	s_mov_b32 m0, s7
	s_nop 0
	global_load_lds_dwordx4 v[138:139], off
	v_lshl_add_u64 v[138:139], v[132:133], 0, s[30:31]
	s_add_i32 m0, s7, 0x2000
	s_nop 0
	global_load_lds_dwordx4 v[138:139], off
	v_lshl_add_u64 v[230:231], v[204:205], 0, s[28:29]
	s_mov_b32 m0, s56
	s_nop 0
	global_load_lds_dwordx4 v[230:231], off
	v_lshl_add_u64 v[230:231], v[204:205], 0, s[30:31]
	s_mov_b32 m0, s57
	s_nop 0
	global_load_lds_dwordx4 v[230:231], off
	s_waitcnt vmcnt(8)
	s_barrier
	v_mfma_f32_16x16x32_bf16 v[50:53], v[188:191], v[156:159], v[50:53]
	v_mfma_f32_16x16x32_bf16 v[42:45], v[196:199], v[156:159], v[42:45]
	v_mfma_f32_16x16x32_bf16 v[34:37], v[188:191], v[164:167], v[34:37]
	v_mfma_f32_16x16x32_bf16 v[26:29], v[196:199], v[164:167], v[26:29]
	v_mfma_f32_16x16x32_bf16 v[18:21], v[188:191], v[172:175], v[18:21]
	v_mfma_f32_16x16x32_bf16 v[10:13], v[196:199], v[172:175], v[10:13]
	v_mfma_f32_16x16x32_bf16 v[6:9], v[188:191], v[180:183], v[6:9]
	v_mfma_f32_16x16x32_bf16 v[2:5], v[196:199], v[180:183], v[2:5]
	v_mfma_f32_16x16x32_bf16 v[50:53], v[192:195], v[160:163], v[50:53]
	v_mfma_f32_16x16x32_bf16 v[42:45], v[200:203], v[160:163], v[42:45]
	v_mfma_f32_16x16x32_bf16 v[34:37], v[192:195], v[168:171], v[34:37]
	v_mfma_f32_16x16x32_bf16 v[26:29], v[200:203], v[168:171], v[26:29]
	v_mfma_f32_16x16x32_bf16 v[18:21], v[192:195], v[176:179], v[18:21]
	v_mfma_f32_16x16x32_bf16 v[10:13], v[200:203], v[176:179], v[10:13]
	v_mfma_f32_16x16x32_bf16 v[6:9], v[192:195], v[184:187], v[6:9]
	v_mfma_f32_16x16x32_bf16 v[2:5], v[200:203], v[184:187], v[2:5]
	s_barrier
	s_add_i32 s7, 0, 0x18000
	v_add_u32_e32 v137, s7, v135
	ds_read_b128 v[138:141], v137
	ds_read_b128 v[142:145], v137 offset:1024
	ds_read_b128 v[148:151], v137 offset:2048
	ds_read_b128 v[152:155], v137 offset:3072
	ds_read_b128 v[156:159], v136 offset:32768
	ds_read_b128 v[160:163], v136 offset:33792
	ds_read_b128 v[164:167], v136 offset:34816
	ds_read_b128 v[168:171], v136 offset:35840
	ds_read_b128 v[172:175], v136 offset:36864
	ds_read_b128 v[176:179], v136 offset:37888
	ds_read_b128 v[180:183], v136 offset:38912
	ds_read_b128 v[184:187], v136 offset:39936
	s_waitcnt lgkmcnt(8)
	s_barrier
	s_waitcnt lgkmcnt(0)
	v_mfma_f32_16x16x32_bf16 v[126:129], v[138:141], v[156:159], v[126:129]
	v_mfma_f32_16x16x32_bf16 v[122:125], v[148:151], v[156:159], v[122:125]
	v_mfma_f32_16x16x32_bf16 v[118:121], v[138:141], v[164:167], v[118:121]
	v_mfma_f32_16x16x32_bf16 v[110:113], v[148:151], v[164:167], v[110:113]
	v_mfma_f32_16x16x32_bf16 v[102:105], v[138:141], v[172:175], v[102:105]
	v_mfma_f32_16x16x32_bf16 v[94:97], v[148:151], v[172:175], v[94:97]
	v_mfma_f32_16x16x32_bf16 v[86:89], v[138:141], v[180:183], v[86:89]
	v_mfma_f32_16x16x32_bf16 v[78:81], v[148:151], v[180:183], v[78:81]
	v_mfma_f32_16x16x32_bf16 v[126:129], v[142:145], v[160:163], v[126:129]
	v_mfma_f32_16x16x32_bf16 v[122:125], v[152:155], v[160:163], v[122:125]
	v_mfma_f32_16x16x32_bf16 v[118:121], v[142:145], v[168:171], v[118:121]
	v_mfma_f32_16x16x32_bf16 v[110:113], v[152:155], v[168:171], v[110:113]
	v_mfma_f32_16x16x32_bf16 v[102:105], v[142:145], v[176:179], v[102:105]
	v_mfma_f32_16x16x32_bf16 v[94:97], v[152:155], v[176:179], v[94:97]
	v_mfma_f32_16x16x32_bf16 v[86:89], v[142:145], v[184:187], v[86:89]
	v_mfma_f32_16x16x32_bf16 v[78:81], v[152:155], v[184:187], v[78:81]
	s_barrier
	s_add_i32 s78, 0, 0x1c000
	s_add_i32 s7, s7, s53
	v_add_u32_e32 v137, s78, v135
	v_lshl_add_u64 v[206:207], v[132:133], 0, s[34:35]
	s_mov_b32 m0, s7
	ds_read_b128 v[188:191], v137
	ds_read_b128 v[192:195], v137 offset:1024
	ds_read_b128 v[196:199], v137 offset:2048
	ds_read_b128 v[200:203], v137 offset:3072
	global_load_lds_dwordx4 v[206:207], off
	v_lshl_add_u64 v[206:207], v[132:133], 0, s[36:37]
	s_add_i32 m0, s7, 0x2000
	s_nop 0
	global_load_lds_dwordx4 v[206:207], off
	s_barrier
	s_waitcnt lgkmcnt(0)
	v_mfma_f32_16x16x32_bf16 v[114:117], v[188:191], v[156:159], v[114:117]
	v_mfma_f32_16x16x32_bf16 v[106:109], v[196:199], v[156:159], v[106:109]
	v_mfma_f32_16x16x32_bf16 v[98:101], v[188:191], v[164:167], v[98:101]
	v_mfma_f32_16x16x32_bf16 v[90:93], v[196:199], v[164:167], v[90:93]
	v_mfma_f32_16x16x32_bf16 v[82:85], v[188:191], v[172:175], v[82:85]
	v_mfma_f32_16x16x32_bf16 v[74:77], v[196:199], v[172:175], v[74:77]
	v_mfma_f32_16x16x32_bf16 v[70:73], v[188:191], v[180:183], v[70:73]
	v_mfma_f32_16x16x32_bf16 v[66:69], v[196:199], v[180:183], v[66:69]
	v_mfma_f32_16x16x32_bf16 v[114:117], v[192:195], v[160:163], v[114:117]
	ds_read_b128 v[156:159], v136 offset:49152
	v_mfma_f32_16x16x32_bf16 v[106:109], v[200:203], v[160:163], v[106:109]
	v_mfma_f32_16x16x32_bf16 v[98:101], v[192:195], v[168:171], v[98:101]
	ds_read_b128 v[164:167], v136 offset:51200
	v_mfma_f32_16x16x32_bf16 v[90:93], v[200:203], v[168:171], v[90:93]
	v_mfma_f32_16x16x32_bf16 v[82:85], v[192:195], v[176:179], v[82:85]
	ds_read_b128 v[172:175], v136 offset:53248
	v_mfma_f32_16x16x32_bf16 v[74:77], v[200:203], v[176:179], v[74:77]
	v_mfma_f32_16x16x32_bf16 v[70:73], v[192:195], v[184:187], v[70:73]
	ds_read_b128 v[180:183], v136 offset:55296
	v_mfma_f32_16x16x32_bf16 v[66:69], v[200:203], v[184:187], v[66:69]
	s_barrier
	s_mov_b32 m0, s62
	v_lshl_add_u64 v[206:207], v[204:205], 0, s[34:35]
	ds_read_b128 v[160:163], v136 offset:50176
	ds_read_b128 v[168:171], v136 offset:52224
	ds_read_b128 v[176:179], v136 offset:54272
	ds_read_b128 v[184:187], v136 offset:56320
	global_load_lds_dwordx4 v[206:207], off
	v_lshl_add_u64 v[204:205], v[204:205], 0, s[36:37]
	s_mov_b32 m0, s63
	s_nop 0
	global_load_lds_dwordx4 v[204:205], off
	s_barrier
	s_waitcnt lgkmcnt(0)
	v_mfma_f32_16x16x32_bf16 v[62:65], v[138:141], v[156:159], v[62:65]
	v_mfma_f32_16x16x32_bf16 v[58:61], v[148:151], v[156:159], v[58:61]
	v_mfma_f32_16x16x32_bf16 v[54:57], v[138:141], v[164:167], v[54:57]
	v_mfma_f32_16x16x32_bf16 v[46:49], v[148:151], v[164:167], v[46:49]
	v_mfma_f32_16x16x32_bf16 v[38:41], v[138:141], v[172:175], v[38:41]
	v_mfma_f32_16x16x32_bf16 v[30:33], v[148:151], v[172:175], v[30:33]
	v_mfma_f32_16x16x32_bf16 v[22:25], v[138:141], v[180:183], v[22:25]
	v_mfma_f32_16x16x32_bf16 v[14:17], v[148:151], v[180:183], v[14:17]
	v_mfma_f32_16x16x32_bf16 v[62:65], v[142:145], v[160:163], v[62:65]
	v_mfma_f32_16x16x32_bf16 v[58:61], v[152:155], v[160:163], v[58:61]
	v_mfma_f32_16x16x32_bf16 v[54:57], v[142:145], v[168:171], v[54:57]
	v_mfma_f32_16x16x32_bf16 v[46:49], v[152:155], v[168:171], v[46:49]
	v_mfma_f32_16x16x32_bf16 v[38:41], v[142:145], v[176:179], v[38:41]
	v_mfma_f32_16x16x32_bf16 v[30:33], v[152:155], v[176:179], v[30:33]
	v_mfma_f32_16x16x32_bf16 v[22:25], v[142:145], v[184:187], v[22:25]
	v_mfma_f32_16x16x32_bf16 v[14:17], v[152:155], v[184:187], v[14:17]
	s_barrier
	s_add_i32 s7, s78, s53
	v_lshl_add_u64 v[138:139], v[132:133], 0, s[18:19]
	s_mov_b32 m0, s7
	v_lshl_add_u64 v[132:133], v[132:133], 0, s[14:15]
	global_load_lds_dwordx4 v[138:139], off
	s_add_i32 m0, s7, 0x2000
	s_nop 0
	global_load_lds_dwordx4 v[132:133], off
	s_waitcnt vmcnt(6)
	s_add_i32 s6, s6, 2
	s_add_u32 s8, s8, 0x100
	s_addc_u32 s9, s9, 0
	s_add_u32 s46, s46, 0x100
	s_addc_u32 s47, s47, 0
	s_cmpk_gt_u32 s6, 0x55
	s_cbranch_scc0 .LBB0_485
	s_barrier
	v_mfma_f32_16x16x32_bf16 v[50:53], v[188:191], v[156:159], v[50:53]
	v_mfma_f32_16x16x32_bf16 v[42:45], v[196:199], v[156:159], v[42:45]
	v_mfma_f32_16x16x32_bf16 v[34:37], v[188:191], v[164:167], v[34:37]
	v_mfma_f32_16x16x32_bf16 v[26:29], v[196:199], v[164:167], v[26:29]
	v_mfma_f32_16x16x32_bf16 v[18:21], v[188:191], v[172:175], v[18:21]
	v_mfma_f32_16x16x32_bf16 v[10:13], v[196:199], v[172:175], v[10:13]
	v_mfma_f32_16x16x32_bf16 v[6:9], v[188:191], v[180:183], v[6:9]
	v_mfma_f32_16x16x32_bf16 v[2:5], v[196:199], v[180:183], v[2:5]
	v_mfma_f32_16x16x32_bf16 v[50:53], v[192:195], v[160:163], v[50:53]
	v_mfma_f32_16x16x32_bf16 v[42:45], v[200:203], v[160:163], v[42:45]
	v_mfma_f32_16x16x32_bf16 v[34:37], v[192:195], v[168:171], v[34:37]
	v_mfma_f32_16x16x32_bf16 v[26:29], v[200:203], v[168:171], v[26:29]
	v_mfma_f32_16x16x32_bf16 v[18:21], v[192:195], v[176:179], v[18:21]
	v_mfma_f32_16x16x32_bf16 v[10:13], v[200:203], v[176:179], v[10:13]
	v_mfma_f32_16x16x32_bf16 v[6:9], v[192:195], v[184:187], v[6:9]
	v_mfma_f32_16x16x32_bf16 v[2:5], v[200:203], v[184:187], v[2:5]
	s_barrier
	v_mov_b32_e32 v137, v134
	s_lshl_b32 s6, s86, 8
	v_ashrrev_i32_e32 v132, 2, v137
	s_or_b32 s6, s6, s59
	v_and_b32_e32 v132, -4, v132
	v_add_u32_e32 v132, s6, v132
	s_lshl_b32 s6, s85, 8
	s_add_i32 s6, s6, s58
	v_and_or_b32 v188, v137, 15, s6
	v_ashrrev_i32_e32 v189, 31, v188
	v_ashrrev_i32_e32 v133, 31, v132
	v_lshlrev_b64 v[206:207], 13, v[188:189]
	v_or_b32_e32 v156, 16, v188
	v_or_b32_e32 v172, 32, v188
	v_or_b32_e32 v188, 48, v188
	v_lshlrev_b64 v[132:133], 2, v[132:133]
	v_ashrrev_i32_e32 v157, 31, v156
	v_ashrrev_i32_e32 v173, 31, v172
	v_ashrrev_i32_e32 v189, 31, v188
	v_lshl_add_u64 v[204:205], s[4:5], 0, v[132:133]
	v_lshlrev_b64 v[208:209], 13, v[156:157]
	v_lshlrev_b64 v[210:211], 13, v[172:173]
	v_lshlrev_b64 v[212:213], 13, v[188:189]
	v_lshl_add_u64 v[152:153], v[204:205], 0, v[206:207]
	v_lshl_add_u64 v[168:169], v[204:205], 0, v[208:209]
	v_lshl_add_u64 v[184:185], v[204:205], 0, v[210:211]
	v_lshl_add_u64 v[200:201], v[204:205], 0, v[212:213]
	global_load_dwordx4 v[138:141], v[152:153], off
	global_load_dwordx4 v[142:145], v[152:153], off offset:64
	global_load_dwordx4 v[148:151], v[152:153], off offset:512
	s_nop 0
	global_load_dwordx4 v[152:155], v[152:153], off offset:576
	s_nop 0
	global_load_dwordx4 v[156:159], v[168:169], off
	global_load_dwordx4 v[160:163], v[168:169], off offset:64
	global_load_dwordx4 v[164:167], v[168:169], off offset:512
	s_nop 0
	global_load_dwordx4 v[168:171], v[168:169], off offset:576
	s_nop 0
	global_load_dwordx4 v[172:175], v[184:185], off
	global_load_dwordx4 v[176:179], v[184:185], off offset:64
	global_load_dwordx4 v[180:183], v[184:185], off offset:512
	s_nop 0
	global_load_dwordx4 v[184:187], v[184:185], off offset:576
	s_nop 0
	global_load_dwordx4 v[188:191], v[200:201], off
	global_load_dwordx4 v[192:195], v[200:201], off offset:64
	global_load_dwordx4 v[196:199], v[200:201], off offset:512
	s_nop 0
	global_load_dwordx4 v[200:203], v[200:201], off offset:576
	s_waitcnt vmcnt(0) lgkmcnt(0)
	v_pk_fma_f32 v[126:127], v[126:127], 0.5, v[138:139] op_sel_hi:[1,0,1]
	v_lshl_add_u64 v[138:139], s[4:5], 0, v[206:207]
	v_lshl_add_u64 v[138:139], v[138:139], 0, v[132:133]
	v_pk_fma_f32 v[116:117], v[116:117], 0.5, v[150:151] op_sel_hi:[1,0,1]
	v_pk_fma_f32 v[114:115], v[114:115], 0.5, v[148:149] op_sel_hi:[1,0,1]
	global_store_dwordx4 v[138:139], v[114:117], off offset:512
	v_pk_fma_f32 v[100:101], v[100:101], 0.5, v[166:167] op_sel_hi:[1,0,1]
	v_pk_fma_f32 v[98:99], v[98:99], 0.5, v[164:165] op_sel_hi:[1,0,1]
	v_lshl_add_u64 v[114:115], s[4:5], 0, v[208:209]
	v_lshl_add_u64 v[114:115], v[114:115], 0, v[132:133]
	global_store_dwordx4 v[114:115], v[98:101], off offset:512
	v_pk_fma_f32 v[84:85], v[84:85], 0.5, v[182:183] op_sel_hi:[1,0,1]
	v_pk_fma_f32 v[82:83], v[82:83], 0.5, v[180:181] op_sel_hi:[1,0,1]
	v_lshl_add_u64 v[98:99], s[4:5], 0, v[210:211]
	v_lshl_add_u64 v[98:99], v[98:99], 0, v[132:133]
	v_pk_fma_f32 v[108:109], v[108:109], 0.5, v[154:155] op_sel_hi:[1,0,1]
	v_pk_fma_f32 v[106:107], v[106:107], 0.5, v[152:153] op_sel_hi:[1,0,1]
	v_pk_fma_f32 v[92:93], v[92:93], 0.5, v[170:171] op_sel_hi:[1,0,1]
	v_pk_fma_f32 v[90:91], v[90:91], 0.5, v[168:169] op_sel_hi:[1,0,1]
	global_store_dwordx4 v[98:99], v[82:85], off offset:512
	v_pk_fma_f32 v[76:77], v[76:77], 0.5, v[186:187] op_sel_hi:[1,0,1]
	v_pk_fma_f32 v[74:75], v[74:75], 0.5, v[184:185] op_sel_hi:[1,0,1]
	v_lshl_add_u64 v[82:83], s[4:5], 0, v[212:213]
	global_store_dwordx4 v[138:139], v[106:109], off offset:576
	global_store_dwordx4 v[114:115], v[90:93], off offset:576
	global_store_dwordx4 v[98:99], v[74:77], off offset:576
	v_pk_fma_f32 v[108:109], v[120:121], 0.5, v[158:159] op_sel_hi:[1,0,1]
	v_pk_fma_f32 v[106:107], v[118:119], 0.5, v[156:157] op_sel_hi:[1,0,1]
	v_pk_fma_f32 v[92:93], v[104:105], 0.5, v[174:175] op_sel_hi:[1,0,1]
	v_pk_fma_f32 v[90:91], v[102:103], 0.5, v[172:173] op_sel_hi:[1,0,1]
	v_pk_fma_f32 v[76:77], v[88:89], 0.5, v[190:191] op_sel_hi:[1,0,1]
	v_pk_fma_f32 v[74:75], v[86:87], 0.5, v[188:189] op_sel_hi:[1,0,1]
	v_lshl_add_u64 v[82:83], v[82:83], 0, v[132:133]
	v_pk_fma_f32 v[128:129], v[128:129], 0.5, v[140:141] op_sel_hi:[1,0,1]
	v_pk_fma_f32 v[124:125], v[124:125], 0.5, v[144:145] op_sel_hi:[1,0,1]
	v_pk_fma_f32 v[122:123], v[122:123], 0.5, v[142:143] op_sel_hi:[1,0,1]
	global_store_dwordx4 v[114:115], v[106:109], off
	global_store_dwordx4 v[98:99], v[90:93], off
	global_store_dwordx4 v[82:83], v[74:77], off
	v_pk_fma_f32 v[108:109], v[112:113], 0.5, v[162:163] op_sel_hi:[1,0,1]
	v_pk_fma_f32 v[106:107], v[110:111], 0.5, v[160:161] op_sel_hi:[1,0,1]
	v_pk_fma_f32 v[92:93], v[96:97], 0.5, v[178:179] op_sel_hi:[1,0,1]
	v_pk_fma_f32 v[90:91], v[94:95], 0.5, v[176:177] op_sel_hi:[1,0,1]
	v_pk_fma_f32 v[76:77], v[80:81], 0.5, v[194:195] op_sel_hi:[1,0,1]
	v_pk_fma_f32 v[74:75], v[78:79], 0.5, v[192:193] op_sel_hi:[1,0,1]
	v_pk_fma_f32 v[72:73], v[72:73], 0.5, v[198:199] op_sel_hi:[1,0,1]
	v_pk_fma_f32 v[70:71], v[70:71], 0.5, v[196:197] op_sel_hi:[1,0,1]
	v_pk_fma_f32 v[68:69], v[68:69], 0.5, v[202:203] op_sel_hi:[1,0,1]
	v_pk_fma_f32 v[66:67], v[66:67], 0.5, v[200:201] op_sel_hi:[1,0,1]
	global_store_dwordx4 v[138:139], v[126:129], off
	global_store_dwordx4 v[138:139], v[122:125], off offset:64
	global_store_dwordx4 v[114:115], v[106:109], off offset:64
	global_store_dwordx4 v[98:99], v[90:93], off offset:64
	global_store_dwordx4 v[82:83], v[74:77], off offset:64
	global_store_dwordx4 v[82:83], v[70:73], off offset:512
	global_store_dwordx4 v[82:83], v[66:69], off offset:576
	s_mov_b64 s[6:7], 0x120000
	v_lshl_add_u64 v[140:141], v[206:207], 0, s[6:7]
	s_mov_b64 s[6:7], 0x140000
	v_lshl_add_u64 v[138:139], v[206:207], 0, s[0:1]
	v_lshl_add_u64 v[142:143], v[206:207], 0, s[6:7]
	v_lshl_add_u64 v[144:145], v[206:207], 0, s[28:29]
	v_lshl_add_u64 v[78:79], v[204:205], 0, v[138:139]
	v_lshl_add_u64 v[94:95], v[204:205], 0, v[140:141]
	v_lshl_add_u64 v[110:111], v[204:205], 0, v[142:143]
	v_lshl_add_u64 v[126:127], v[204:205], 0, v[144:145]
	global_load_dwordx4 v[66:69], v[78:79], off
	global_load_dwordx4 v[70:73], v[78:79], off offset:64
	global_load_dwordx4 v[74:77], v[78:79], off offset:512
	s_nop 0
	global_load_dwordx4 v[78:81], v[78:79], off offset:576
	s_nop 0
	global_load_dwordx4 v[82:85], v[94:95], off
	global_load_dwordx4 v[86:89], v[94:95], off offset:64
	global_load_dwordx4 v[90:93], v[94:95], off offset:512
	s_nop 0
	global_load_dwordx4 v[94:97], v[94:95], off offset:576
	s_nop 0
	global_load_dwordx4 v[98:101], v[110:111], off
	global_load_dwordx4 v[102:105], v[110:111], off offset:64
	global_load_dwordx4 v[106:109], v[110:111], off offset:512
	s_nop 0
	global_load_dwordx4 v[110:113], v[110:111], off offset:576
	s_nop 0
	global_load_dwordx4 v[114:117], v[126:127], off
	global_load_dwordx4 v[118:121], v[126:127], off offset:64
	global_load_dwordx4 v[122:125], v[126:127], off offset:512
	s_nop 0
	global_load_dwordx4 v[126:129], v[126:127], off offset:576
	s_waitcnt vmcnt(0) lgkmcnt(0)
	v_pk_fma_f32 v[62:63], v[62:63], 0.5, v[66:67] op_sel_hi:[1,0,1]
	v_lshl_add_u64 v[66:67], s[4:5], 0, v[138:139]
	v_lshl_add_u64 v[66:67], v[66:67], 0, v[132:133]
	v_pk_fma_f32 v[52:53], v[52:53], 0.5, v[76:77] op_sel_hi:[1,0,1]
	v_pk_fma_f32 v[50:51], v[50:51], 0.5, v[74:75] op_sel_hi:[1,0,1]
	global_store_dwordx4 v[66:67], v[50:53], off offset:512
	v_pk_fma_f32 v[36:37], v[36:37], 0.5, v[92:93] op_sel_hi:[1,0,1]
	v_pk_fma_f32 v[34:35], v[34:35], 0.5, v[90:91] op_sel_hi:[1,0,1]
	v_lshl_add_u64 v[50:51], s[4:5], 0, v[140:141]
	v_lshl_add_u64 v[50:51], v[50:51], 0, v[132:133]
	global_store_dwordx4 v[50:51], v[34:37], off offset:512
	v_pk_fma_f32 v[20:21], v[20:21], 0.5, v[108:109] op_sel_hi:[1,0,1]
	v_pk_fma_f32 v[18:19], v[18:19], 0.5, v[106:107] op_sel_hi:[1,0,1]
	v_lshl_add_u64 v[34:35], s[4:5], 0, v[142:143]
	v_lshl_add_u64 v[34:35], v[34:35], 0, v[132:133]
	v_pk_fma_f32 v[44:45], v[44:45], 0.5, v[80:81] op_sel_hi:[1,0,1]
	v_pk_fma_f32 v[42:43], v[42:43], 0.5, v[78:79] op_sel_hi:[1,0,1]
	v_pk_fma_f32 v[28:29], v[28:29], 0.5, v[96:97] op_sel_hi:[1,0,1]
	v_pk_fma_f32 v[26:27], v[26:27], 0.5, v[94:95] op_sel_hi:[1,0,1]
	global_store_dwordx4 v[34:35], v[18:21], off offset:512
	v_pk_fma_f32 v[12:13], v[12:13], 0.5, v[112:113] op_sel_hi:[1,0,1]
	v_pk_fma_f32 v[10:11], v[10:11], 0.5, v[110:111] op_sel_hi:[1,0,1]
	v_lshl_add_u64 v[18:19], s[4:5], 0, v[144:145]
	global_store_dwordx4 v[66:67], v[42:45], off offset:576
	global_store_dwordx4 v[50:51], v[26:29], off offset:576
	global_store_dwordx4 v[34:35], v[10:13], off offset:576
	v_pk_fma_f32 v[44:45], v[56:57], 0.5, v[84:85] op_sel_hi:[1,0,1]
	v_pk_fma_f32 v[42:43], v[54:55], 0.5, v[82:83] op_sel_hi:[1,0,1]
	v_pk_fma_f32 v[28:29], v[40:41], 0.5, v[100:101] op_sel_hi:[1,0,1]
	v_pk_fma_f32 v[26:27], v[38:39], 0.5, v[98:99] op_sel_hi:[1,0,1]
	v_pk_fma_f32 v[12:13], v[24:25], 0.5, v[116:117] op_sel_hi:[1,0,1]
	v_pk_fma_f32 v[10:11], v[22:23], 0.5, v[114:115] op_sel_hi:[1,0,1]
	v_lshl_add_u64 v[18:19], v[18:19], 0, v[132:133]
	v_pk_fma_f32 v[64:65], v[64:65], 0.5, v[68:69] op_sel_hi:[1,0,1]
	v_pk_fma_f32 v[60:61], v[60:61], 0.5, v[72:73] op_sel_hi:[1,0,1]
	v_pk_fma_f32 v[58:59], v[58:59], 0.5, v[70:71] op_sel_hi:[1,0,1]
	global_store_dwordx4 v[50:51], v[42:45], off
	global_store_dwordx4 v[34:35], v[26:29], off
	global_store_dwordx4 v[18:19], v[10:13], off
	v_pk_fma_f32 v[44:45], v[48:49], 0.5, v[88:89] op_sel_hi:[1,0,1]
	v_pk_fma_f32 v[42:43], v[46:47], 0.5, v[86:87] op_sel_hi:[1,0,1]
	v_pk_fma_f32 v[28:29], v[32:33], 0.5, v[104:105] op_sel_hi:[1,0,1]
	v_pk_fma_f32 v[26:27], v[30:31], 0.5, v[102:103] op_sel_hi:[1,0,1]
	v_pk_fma_f32 v[12:13], v[16:17], 0.5, v[120:121] op_sel_hi:[1,0,1]
	v_pk_fma_f32 v[10:11], v[14:15], 0.5, v[118:119] op_sel_hi:[1,0,1]
	v_pk_fma_f32 v[8:9], v[8:9], 0.5, v[124:125] op_sel_hi:[1,0,1]
	v_pk_fma_f32 v[6:7], v[6:7], 0.5, v[122:123] op_sel_hi:[1,0,1]
	v_pk_fma_f32 v[4:5], v[4:5], 0.5, v[128:129] op_sel_hi:[1,0,1]
	v_pk_fma_f32 v[2:3], v[2:3], 0.5, v[126:127] op_sel_hi:[1,0,1]
	global_store_dwordx4 v[66:67], v[62:65], off
	global_store_dwordx4 v[66:67], v[58:61], off offset:64
	global_store_dwordx4 v[50:51], v[42:45], off offset:64
	global_store_dwordx4 v[34:35], v[26:29], off offset:64
	global_store_dwordx4 v[18:19], v[10:13], off offset:64
	global_store_dwordx4 v[18:19], v[6:9], off offset:512
	global_store_dwordx4 v[18:19], v[2:5], off offset:576
	s_and_b64 vcc, exec, s[40:41]
	s_mov_b32 s85, s10
	s_mov_b32 s86, s11
	s_mov_b64 s[8:9], s[44:45]
	s_mov_b64 s[6:7], s[42:43]
	s_movk_i32 s89, 0x37ff
	s_mov_b32 s88, 0x16000
	s_movk_i32 s91, 0x60
	s_mov_b32 s78, 0x2a000000
	s_mov_b32 s79, 0x3fffe
	s_mov_b32 s90, 0xc0000
	s_cbranch_vccz .LBB0_478
	s_waitcnt vmcnt(0)
	s_cmpk_gt_u32 s48, 0xff
	s_cbranch_scc1 .LBB0_489
	s_barrier

.Lrot_enter_5:
	s_add_u32 s8, s6, 0x100
	s_addc_u32 s9, s7, 0
	s_add_i32 s78, 0, 0x10000
	v_add_u32_e32 v134, s78, v137
	ds_read_b128 v[140:143], v134
	ds_read_b128 v[148:151], v134 offset:1024
	ds_read_b128 v[152:155], v134 offset:2048
	ds_read_b128 v[156:159], v134 offset:3072
	s_cmp_eq_u32 s87, 28
	s_cselect_b32 s89, s43, s9
	s_cselect_b32 s88, s42, s8
	s_cselect_b32 s91, s47, s86
	s_cselect_b32 s90, s46, s41
	v_lshl_add_u64 v[134:135], s[6:7], 0, v[132:133]
	v_lshl_add_u64 v[144:145], v[134:135], 0, s[16:17]
	s_add_i32 m0, s49, 0xc000
	ds_read_b128 v[160:163], v138
	ds_read_b128 v[164:167], v138 offset:1024
	ds_read_b128 v[168:171], v138 offset:2048
	ds_read_b128 v[172:175], v138 offset:3072
	ds_read_b128 v[176:179], v138 offset:4096
	ds_read_b128 v[180:183], v138 offset:5120
	ds_read_b128 v[184:187], v138 offset:6144
	ds_read_b128 v[188:191], v138 offset:7168
	global_load_lds_dwordx4 v[144:145], off
	v_lshl_add_u64 v[134:135], v[134:135], 0, s[80:81]
	s_add_i32 m0, s49, 0xe000
	s_nop 0
	global_load_lds_dwordx4 v[134:135], off
	s_waitcnt lgkmcnt(8)
	s_barrier
	s_waitcnt lgkmcnt(0)
	v_mfma_f32_16x16x32_bf16 v[126:129], v[140:143], v[160:163], v[126:129]
	v_mfma_f32_16x16x32_bf16 v[118:121], v[152:155], v[160:163], v[118:121]
	v_mfma_f32_16x16x32_bf16 v[110:113], v[140:143], v[168:171], v[110:113]
	v_mfma_f32_16x16x32_bf16 v[102:105], v[152:155], v[168:171], v[102:105]
	v_mfma_f32_16x16x32_bf16 v[94:97], v[140:143], v[176:179], v[94:97]
	v_mfma_f32_16x16x32_bf16 v[86:89], v[152:155], v[176:179], v[86:89]
	v_mfma_f32_16x16x32_bf16 v[78:81], v[140:143], v[184:187], v[78:81]
	v_mfma_f32_16x16x32_bf16 v[70:73], v[152:155], v[184:187], v[70:73]
	v_mfma_f32_16x16x32_bf16 v[126:129], v[148:151], v[164:167], v[126:129]
	v_mfma_f32_16x16x32_bf16 v[118:121], v[156:159], v[164:167], v[118:121]
	v_mfma_f32_16x16x32_bf16 v[110:113], v[148:151], v[172:175], v[110:113]
	v_mfma_f32_16x16x32_bf16 v[102:105], v[156:159], v[172:175], v[102:105]
	v_mfma_f32_16x16x32_bf16 v[94:97], v[148:151], v[180:183], v[94:97]
	v_mfma_f32_16x16x32_bf16 v[86:89], v[156:159], v[180:183], v[86:89]
	v_mfma_f32_16x16x32_bf16 v[78:81], v[148:151], v[188:191], v[78:81]
	v_mfma_f32_16x16x32_bf16 v[70:73], v[156:159], v[188:191], v[70:73]
	s_barrier
	s_add_i32 s6, 0, 0x14000
	v_add_u32_e32 v134, s6, v137
	s_add_i32 s7, s78, s54
	ds_read_b128 v[192:195], v134
	ds_read_b128 v[196:199], v134 offset:1024
	ds_read_b128 v[200:203], v134 offset:2048
	ds_read_b128 v[204:207], v134 offset:3072
	v_lshl_add_u64 v[134:135], s[90:91], 0, v[0:1]
	s_mov_b32 m0, s7
	v_lshl_add_u64 v[144:145], v[134:135], 0, s[60:61]
	global_load_lds_dwordx4 v[134:135], off
	s_add_i32 m0, s7, 0x2000
	s_nop 0
	global_load_lds_dwordx4 v[144:145], off
	s_barrier
	s_waitcnt lgkmcnt(0)
	v_mfma_f32_16x16x32_bf16 v[122:125], v[192:195], v[160:163], v[122:125]
	v_mfma_f32_16x16x32_bf16 v[114:117], v[200:203], v[160:163], v[114:117]
	v_mfma_f32_16x16x32_bf16 v[106:109], v[192:195], v[168:171], v[106:109]
	v_mfma_f32_16x16x32_bf16 v[98:101], v[200:203], v[168:171], v[98:101]
	v_mfma_f32_16x16x32_bf16 v[90:93], v[192:195], v[176:179], v[90:93]
	v_mfma_f32_16x16x32_bf16 v[82:85], v[200:203], v[176:179], v[82:85]
	v_mfma_f32_16x16x32_bf16 v[74:77], v[192:195], v[184:187], v[74:77]
	v_mfma_f32_16x16x32_bf16 v[66:69], v[200:203], v[184:187], v[66:69]
	v_mfma_f32_16x16x32_bf16 v[122:125], v[196:199], v[164:167], v[122:125]
	ds_read_b128 v[160:163], v138 offset:16384
	v_mfma_f32_16x16x32_bf16 v[114:117], v[204:207], v[164:167], v[114:117]
	v_mfma_f32_16x16x32_bf16 v[106:109], v[196:199], v[172:175], v[106:109]
	ds_read_b128 v[168:171], v138 offset:18432
	v_mfma_f32_16x16x32_bf16 v[98:101], v[204:207], v[172:175], v[98:101]
	v_mfma_f32_16x16x32_bf16 v[90:93], v[196:199], v[180:183], v[90:93]
	ds_read_b128 v[176:179], v138 offset:20480
	v_mfma_f32_16x16x32_bf16 v[82:85], v[204:207], v[180:183], v[82:85]
	v_mfma_f32_16x16x32_bf16 v[74:77], v[196:199], v[188:191], v[74:77]
	ds_read_b128 v[184:187], v138 offset:22528
	v_mfma_f32_16x16x32_bf16 v[66:69], v[204:207], v[188:191], v[66:69]
	s_barrier
	s_mov_b32 m0, s49
	v_lshl_add_u64 v[144:145], s[88:89], 0, v[130:131]
	ds_read_b128 v[164:167], v138 offset:17408
	ds_read_b128 v[172:175], v138 offset:19456
	ds_read_b128 v[180:183], v138 offset:21504
	ds_read_b128 v[188:191], v138 offset:23552
	global_load_lds_dwordx4 v[144:145], off
	v_lshl_add_u64 v[208:209], v[144:145], 0, s[60:61]
	s_mov_b32 m0, s55
	s_nop 0
	global_load_lds_dwordx4 v[208:209], off
	s_barrier
	s_waitcnt lgkmcnt(0)
	v_mfma_f32_16x16x32_bf16 v[62:65], v[140:143], v[160:163], v[62:65]
	v_mfma_f32_16x16x32_bf16 v[54:57], v[152:155], v[160:163], v[54:57]
	v_mfma_f32_16x16x32_bf16 v[46:49], v[140:143], v[168:171], v[46:49]
	v_mfma_f32_16x16x32_bf16 v[38:41], v[152:155], v[168:171], v[38:41]
	v_mfma_f32_16x16x32_bf16 v[30:33], v[140:143], v[176:179], v[30:33]
	v_mfma_f32_16x16x32_bf16 v[22:25], v[152:155], v[176:179], v[22:25]
	v_mfma_f32_16x16x32_bf16 v[14:17], v[140:143], v[184:187], v[14:17]
	v_mfma_f32_16x16x32_bf16 v[6:9], v[152:155], v[184:187], v[6:9]
	v_mfma_f32_16x16x32_bf16 v[62:65], v[148:151], v[164:167], v[62:65]
	v_mfma_f32_16x16x32_bf16 v[54:57], v[156:159], v[164:167], v[54:57]
	v_mfma_f32_16x16x32_bf16 v[46:49], v[148:151], v[172:175], v[46:49]
	v_mfma_f32_16x16x32_bf16 v[38:41], v[156:159], v[172:175], v[38:41]
	v_mfma_f32_16x16x32_bf16 v[30:33], v[148:151], v[180:183], v[30:33]
	v_mfma_f32_16x16x32_bf16 v[22:25], v[156:159], v[180:183], v[22:25]
	v_mfma_f32_16x16x32_bf16 v[14:17], v[148:151], v[188:191], v[14:17]
	v_mfma_f32_16x16x32_bf16 v[6:9], v[156:159], v[188:191], v[6:9]
	s_barrier
	s_add_i32 s6, s6, s54
	v_lshl_add_u64 v[140:141], v[134:135], 0, s[20:21]
	s_mov_b32 m0, s6
	s_nop 0
	global_load_lds_dwordx4 v[140:141], off
	v_lshl_add_u64 v[140:141], v[134:135], 0, s[64:65]
	s_add_i32 m0, s6, 0x2000
	s_nop 0
	global_load_lds_dwordx4 v[140:141], off
	v_lshl_add_u64 v[230:231], v[144:145], 0, s[20:21]
	s_mov_b32 m0, s56
	s_nop 0
	global_load_lds_dwordx4 v[230:231], off
	v_lshl_add_u64 v[230:231], v[144:145], 0, s[64:65]
	s_mov_b32 m0, s57
	s_nop 0
	global_load_lds_dwordx4 v[230:231], off
	s_waitcnt vmcnt(8)
	s_barrier
	v_mfma_f32_16x16x32_bf16 v[58:61], v[192:195], v[160:163], v[58:61]
	v_mfma_f32_16x16x32_bf16 v[50:53], v[200:203], v[160:163], v[50:53]
	v_mfma_f32_16x16x32_bf16 v[42:45], v[192:195], v[168:171], v[42:45]
	v_mfma_f32_16x16x32_bf16 v[34:37], v[200:203], v[168:171], v[34:37]
	v_mfma_f32_16x16x32_bf16 v[26:29], v[192:195], v[176:179], v[26:29]
	v_mfma_f32_16x16x32_bf16 v[18:21], v[200:203], v[176:179], v[18:21]
	v_mfma_f32_16x16x32_bf16 v[10:13], v[192:195], v[184:187], v[10:13]
	v_mfma_f32_16x16x32_bf16 v[2:5], v[200:203], v[184:187], v[2:5]
	v_mfma_f32_16x16x32_bf16 v[58:61], v[196:199], v[164:167], v[58:61]
	v_mfma_f32_16x16x32_bf16 v[50:53], v[204:207], v[164:167], v[50:53]
	v_mfma_f32_16x16x32_bf16 v[42:45], v[196:199], v[172:175], v[42:45]
	v_mfma_f32_16x16x32_bf16 v[34:37], v[204:207], v[172:175], v[34:37]
	v_mfma_f32_16x16x32_bf16 v[26:29], v[196:199], v[180:183], v[26:29]
	v_mfma_f32_16x16x32_bf16 v[18:21], v[204:207], v[180:183], v[18:21]
	v_mfma_f32_16x16x32_bf16 v[10:13], v[196:199], v[188:191], v[10:13]
	v_mfma_f32_16x16x32_bf16 v[2:5], v[204:207], v[188:191], v[2:5]
	s_barrier
	s_add_i32 s6, 0, 0x18000
	v_add_u32_e32 v139, s6, v137
	ds_read_b128 v[140:143], v139
	ds_read_b128 v[148:151], v139 offset:1024
	ds_read_b128 v[152:155], v139 offset:2048
	ds_read_b128 v[156:159], v139 offset:3072
	ds_read_b128 v[160:163], v138 offset:32768
	ds_read_b128 v[164:167], v138 offset:33792
	ds_read_b128 v[168:171], v138 offset:34816
	ds_read_b128 v[172:175], v138 offset:35840
	ds_read_b128 v[176:179], v138 offset:36864
	ds_read_b128 v[180:183], v138 offset:37888
	ds_read_b128 v[184:187], v138 offset:38912
	ds_read_b128 v[188:191], v138 offset:39936
	s_waitcnt lgkmcnt(8)
	s_barrier
	s_waitcnt lgkmcnt(0)
	v_mfma_f32_16x16x32_bf16 v[126:129], v[140:143], v[160:163], v[126:129]
	v_mfma_f32_16x16x32_bf16 v[118:121], v[152:155], v[160:163], v[118:121]
	v_mfma_f32_16x16x32_bf16 v[110:113], v[140:143], v[168:171], v[110:113]
	v_mfma_f32_16x16x32_bf16 v[102:105], v[152:155], v[168:171], v[102:105]
	v_mfma_f32_16x16x32_bf16 v[94:97], v[140:143], v[176:179], v[94:97]
	v_mfma_f32_16x16x32_bf16 v[86:89], v[152:155], v[176:179], v[86:89]
	v_mfma_f32_16x16x32_bf16 v[78:81], v[140:143], v[184:187], v[78:81]
	v_mfma_f32_16x16x32_bf16 v[70:73], v[152:155], v[184:187], v[70:73]
	v_mfma_f32_16x16x32_bf16 v[126:129], v[148:151], v[164:167], v[126:129]
	v_mfma_f32_16x16x32_bf16 v[118:121], v[156:159], v[164:167], v[118:121]
	v_mfma_f32_16x16x32_bf16 v[110:113], v[148:151], v[172:175], v[110:113]
	v_mfma_f32_16x16x32_bf16 v[102:105], v[156:159], v[172:175], v[102:105]
	v_mfma_f32_16x16x32_bf16 v[94:97], v[148:151], v[180:183], v[94:97]
	v_mfma_f32_16x16x32_bf16 v[86:89], v[156:159], v[180:183], v[86:89]
	v_mfma_f32_16x16x32_bf16 v[78:81], v[148:151], v[188:191], v[78:81]
	v_mfma_f32_16x16x32_bf16 v[70:73], v[156:159], v[188:191], v[70:73]
	s_barrier
	s_add_i32 s7, 0, 0x1c000
	s_add_i32 s6, s6, s54
	v_add_u32_e32 v139, s7, v137
	v_lshl_add_u64 v[208:209], v[134:135], 0, s[34:35]
	s_mov_b32 m0, s6
	ds_read_b128 v[192:195], v139
	ds_read_b128 v[196:199], v139 offset:1024
	ds_read_b128 v[200:203], v139 offset:2048
	ds_read_b128 v[204:207], v139 offset:3072
	global_load_lds_dwordx4 v[208:209], off
	v_lshl_add_u64 v[208:209], v[134:135], 0, s[66:67]
	s_add_i32 m0, s6, 0x2000
	s_nop 0
	global_load_lds_dwordx4 v[208:209], off
	s_barrier
	s_waitcnt lgkmcnt(0)
	v_mfma_f32_16x16x32_bf16 v[122:125], v[192:195], v[160:163], v[122:125]
	v_mfma_f32_16x16x32_bf16 v[114:117], v[200:203], v[160:163], v[114:117]
	v_mfma_f32_16x16x32_bf16 v[106:109], v[192:195], v[168:171], v[106:109]
	v_mfma_f32_16x16x32_bf16 v[98:101], v[200:203], v[168:171], v[98:101]
	v_mfma_f32_16x16x32_bf16 v[90:93], v[192:195], v[176:179], v[90:93]
	v_mfma_f32_16x16x32_bf16 v[82:85], v[200:203], v[176:179], v[82:85]
	v_mfma_f32_16x16x32_bf16 v[74:77], v[192:195], v[184:187], v[74:77]
	v_mfma_f32_16x16x32_bf16 v[66:69], v[200:203], v[184:187], v[66:69]
	v_mfma_f32_16x16x32_bf16 v[122:125], v[196:199], v[164:167], v[122:125]
	ds_read_b128 v[160:163], v138 offset:49152
	v_mfma_f32_16x16x32_bf16 v[114:117], v[204:207], v[164:167], v[114:117]
	v_mfma_f32_16x16x32_bf16 v[106:109], v[196:199], v[172:175], v[106:109]
	ds_read_b128 v[168:171], v138 offset:51200
	v_mfma_f32_16x16x32_bf16 v[98:101], v[204:207], v[172:175], v[98:101]
	v_mfma_f32_16x16x32_bf16 v[90:93], v[196:199], v[180:183], v[90:93]
	ds_read_b128 v[176:179], v138 offset:53248
	v_mfma_f32_16x16x32_bf16 v[82:85], v[204:207], v[180:183], v[82:85]
	v_mfma_f32_16x16x32_bf16 v[74:77], v[196:199], v[188:191], v[74:77]
	ds_read_b128 v[184:187], v138 offset:55296
	v_mfma_f32_16x16x32_bf16 v[66:69], v[204:207], v[188:191], v[66:69]
	s_barrier
	s_mov_b32 m0, s59
	v_lshl_add_u64 v[208:209], v[144:145], 0, s[34:35]
	ds_read_b128 v[164:167], v138 offset:50176
	ds_read_b128 v[172:175], v138 offset:52224
	ds_read_b128 v[180:183], v138 offset:54272
	ds_read_b128 v[188:191], v138 offset:56320
	global_load_lds_dwordx4 v[208:209], off
	v_lshl_add_u64 v[144:145], v[144:145], 0, s[66:67]
	s_mov_b32 m0, s62
	s_nop 0
	global_load_lds_dwordx4 v[144:145], off
	s_barrier
	s_waitcnt lgkmcnt(0)
	v_mfma_f32_16x16x32_bf16 v[62:65], v[140:143], v[160:163], v[62:65]
	v_mfma_f32_16x16x32_bf16 v[54:57], v[152:155], v[160:163], v[54:57]
	v_mfma_f32_16x16x32_bf16 v[46:49], v[140:143], v[168:171], v[46:49]
	v_mfma_f32_16x16x32_bf16 v[38:41], v[152:155], v[168:171], v[38:41]
	v_mfma_f32_16x16x32_bf16 v[30:33], v[140:143], v[176:179], v[30:33]
	v_mfma_f32_16x16x32_bf16 v[22:25], v[152:155], v[176:179], v[22:25]
	v_mfma_f32_16x16x32_bf16 v[14:17], v[140:143], v[184:187], v[14:17]
	v_mfma_f32_16x16x32_bf16 v[6:9], v[152:155], v[184:187], v[6:9]
	v_mfma_f32_16x16x32_bf16 v[62:65], v[148:151], v[164:167], v[62:65]
	v_mfma_f32_16x16x32_bf16 v[54:57], v[156:159], v[164:167], v[54:57]
	v_mfma_f32_16x16x32_bf16 v[46:49], v[148:151], v[172:175], v[46:49]
	v_mfma_f32_16x16x32_bf16 v[38:41], v[156:159], v[172:175], v[38:41]
	v_mfma_f32_16x16x32_bf16 v[30:33], v[148:151], v[180:183], v[30:33]
	v_mfma_f32_16x16x32_bf16 v[22:25], v[156:159], v[180:183], v[22:25]
	v_mfma_f32_16x16x32_bf16 v[14:17], v[148:151], v[188:191], v[14:17]
	v_mfma_f32_16x16x32_bf16 v[6:9], v[156:159], v[188:191], v[6:9]
	s_barrier
	s_add_i32 s6, s7, s54
	v_lshl_add_u64 v[140:141], v[134:135], 0, s[16:17]
	s_mov_b32 m0, s6
	v_lshl_add_u64 v[134:135], v[134:135], 0, s[80:81]
	global_load_lds_dwordx4 v[140:141], off
	s_add_i32 m0, s6, 0x2000
	s_nop 0
	global_load_lds_dwordx4 v[134:135], off
	s_waitcnt vmcnt(6)
	s_add_i32 s87, s87, 2
	s_add_u32 s41, s41, 0x100
	s_addc_u32 s86, s86, 0
	s_cmp_gt_u32 s87, 29
	s_mov_b64 s[6:7], s[8:9]
	s_cbranch_scc0 .LBB0_503
	s_barrier
	v_mfma_f32_16x16x32_bf16 v[58:61], v[192:195], v[160:163], v[58:61]
	v_mfma_f32_16x16x32_bf16 v[50:53], v[200:203], v[160:163], v[50:53]
	v_mfma_f32_16x16x32_bf16 v[42:45], v[192:195], v[168:171], v[42:45]
	v_mfma_f32_16x16x32_bf16 v[34:37], v[200:203], v[168:171], v[34:37]
	v_mfma_f32_16x16x32_bf16 v[26:29], v[192:195], v[176:179], v[26:29]
	v_mfma_f32_16x16x32_bf16 v[18:21], v[200:203], v[176:179], v[18:21]
	v_mfma_f32_16x16x32_bf16 v[10:13], v[192:195], v[184:187], v[10:13]
	v_mfma_f32_16x16x32_bf16 v[2:5], v[200:203], v[184:187], v[2:5]
	v_mfma_f32_16x16x32_bf16 v[58:61], v[196:199], v[164:167], v[58:61]
	v_mfma_f32_16x16x32_bf16 v[50:53], v[204:207], v[164:167], v[50:53]
	v_mfma_f32_16x16x32_bf16 v[42:45], v[196:199], v[172:175], v[42:45]
	v_mfma_f32_16x16x32_bf16 v[34:37], v[204:207], v[172:175], v[34:37]
	v_mfma_f32_16x16x32_bf16 v[26:29], v[196:199], v[180:183], v[26:29]
	v_mfma_f32_16x16x32_bf16 v[18:21], v[204:207], v[180:183], v[18:21]
	v_mfma_f32_16x16x32_bf16 v[10:13], v[196:199], v[188:191], v[10:13]
	v_mfma_f32_16x16x32_bf16 v[2:5], v[204:207], v[188:191], v[2:5]
	s_barrier
	v_mul_f32_e32 v144, 0xbfb8aa3b, v126
	v_exp_f32_e32 v144, v144
	v_mov_b32_e32 v134, v136
	s_lshl_b32 s6, s48, 8
	v_add_f32_e32 v144, 1.0, v144
	v_rcp_f32_e32 v144, v144
	s_add_i32 s6, s6, s10
	v_and_or_b32 v139, v134, 15, s6
	s_lshl_b32 s6, s85, 7
	v_mul_f32_e32 v126, v126, v144
	v_mul_f32_e32 v122, v126, v122
	v_mul_f32_e32 v126, 0xbfb8aa3b, v127
	v_exp_f32_e32 v126, v126
	v_ashrrev_i32_e32 v134, 1, v134
	s_or_b32 s6, s6, s58
	v_and_b32_e32 v134, -8, v134
	v_add_f32_e32 v126, 1.0, v126
	v_rcp_f32_e32 v126, v126
	v_add_u32_e32 v140, s6, v134
	v_ashrrev_i32_e32 v141, 31, v140
	v_mov_b64_e32 v[134:135], s[4:5]
	v_mul_f32_e32 v126, v127, v126
	v_mul_f32_e32 v123, v126, v123
	v_mul_f32_e32 v126, 0xbfb8aa3b, v128
	v_exp_f32_e32 v126, v126
	v_mad_i64_i32 v[142:143], s[6:7], v139, s74, v[134:135]
	s_and_b64 vcc, exec, s[44:45]
	v_add_f32_e32 v126, 1.0, v126
	v_rcp_f32_e32 v126, v126
	s_mov_b32 s48, s40
	s_mov_b32 s85, s84
	s_mov_b64 s[8:9], s[46:47]
	v_mul_f32_e32 v126, v128, v126
	v_mul_f32_e32 v124, v126, v124
	v_mul_f32_e32 v126, 0xbfb8aa3b, v129
	v_exp_f32_e32 v126, v126
	s_nop 0
	v_add_f32_e32 v126, 1.0, v126
	v_rcp_f32_e32 v126, v126
	s_nop 0
	v_mul_f32_e32 v126, v129, v126
	v_mul_f32_e32 v125, v126, v125
	v_mul_f32_e32 v126, 0xbfb8aa3b, v118
	v_exp_f32_e32 v126, v126
	s_nop 0
	v_add_f32_e32 v126, 1.0, v126
	v_rcp_f32_e32 v126, v126
	s_nop 0
	v_mul_f32_e32 v118, v118, v126
	v_mul_f32_e32 v118, v118, v114
	v_mul_f32_e32 v114, 0xbfb8aa3b, v119
	v_exp_f32_e32 v114, v114
	s_nop 0
	v_add_f32_e32 v114, 1.0, v114
	v_rcp_f32_e32 v114, v114
	s_nop 0
	v_mul_f32_e32 v114, v119, v114
	v_mul_f32_e32 v119, v114, v115
	v_mul_f32_e32 v114, 0xbfb8aa3b, v120
	v_exp_f32_e32 v114, v114
	s_nop 0
	v_add_f32_e32 v114, 1.0, v114
	v_rcp_f32_e32 v114, v114
	s_nop 0
	v_mul_f32_e32 v114, v120, v114
	v_mul_f32_e32 v126, v114, v116
	v_mul_f32_e32 v114, 0xbfb8aa3b, v121
	v_exp_f32_e32 v114, v114
	v_cvt_pk_bf16_f32 v116, v122, v123
	s_nop 0
	v_add_f32_e32 v114, 1.0, v114
	v_rcp_f32_e32 v114, v114
	s_nop 0
	v_mul_f32_e32 v114, v121, v114
	v_mul_f32_e32 v127, v114, v117
	v_lshlrev_b64 v[114:115], 1, v[140:141]
	v_lshl_add_u64 v[120:121], v[142:143], 0, v[114:115]
	v_cvt_pk_bf16_f32 v117, v124, v125
	v_cvt_pk_bf16_f32 v118, v118, v119
	v_cvt_pk_bf16_f32 v119, v126, v127
	global_store_dwordx4 v[120:121], v[116:119], off
	s_nop 1
	v_mul_f32_e32 v118, 0xbfb8aa3b, v110
	v_exp_f32_e32 v118, v118
	v_or_b32_e32 v116, 16, v139
	v_mad_i64_i32 v[116:117], s[6:7], v116, s74, v[134:135]
	v_add_f32_e32 v118, 1.0, v118
	v_rcp_f32_e32 v118, v118
	s_nop 0
	v_mul_f32_e32 v110, v110, v118
	v_mul_f32_e32 v106, v110, v106
	v_mul_f32_e32 v110, 0xbfb8aa3b, v111
	v_exp_f32_e32 v110, v110
	s_nop 0
	v_add_f32_e32 v110, 1.0, v110
	v_rcp_f32_e32 v110, v110
	s_nop 0
	v_mul_f32_e32 v110, v111, v110
	v_mul_f32_e32 v107, v110, v107
	v_mul_f32_e32 v110, 0xbfb8aa3b, v112
	v_exp_f32_e32 v110, v110
	s_nop 0
	v_add_f32_e32 v110, 1.0, v110
	v_rcp_f32_e32 v110, v110
	s_nop 0
	v_mul_f32_e32 v110, v112, v110
	v_mul_f32_e32 v108, v110, v108
	v_mul_f32_e32 v110, 0xbfb8aa3b, v113
	v_exp_f32_e32 v110, v110
	s_nop 0
	v_add_f32_e32 v110, 1.0, v110
	v_rcp_f32_e32 v110, v110
	s_nop 0
	v_mul_f32_e32 v110, v113, v110
	v_mul_f32_e32 v109, v110, v109
	v_mul_f32_e32 v110, 0xbfb8aa3b, v102
	v_exp_f32_e32 v110, v110
	s_nop 0
	v_add_f32_e32 v110, 1.0, v110
	v_rcp_f32_e32 v110, v110
	s_nop 0
	v_mul_f32_e32 v102, v102, v110
	v_mul_f32_e32 v110, v102, v98
	v_mul_f32_e32 v98, 0xbfb8aa3b, v103
	v_exp_f32_e32 v98, v98
	s_nop 0
	v_add_f32_e32 v98, 1.0, v98
	v_rcp_f32_e32 v98, v98
	s_nop 0
	v_mul_f32_e32 v98, v103, v98
	v_mul_f32_e32 v111, v98, v99
	v_mul_f32_e32 v98, 0xbfb8aa3b, v104
	v_exp_f32_e32 v98, v98
	v_lshl_add_u64 v[102:103], v[116:117], 0, v[114:115]
	v_add_f32_e32 v98, 1.0, v98
	v_rcp_f32_e32 v98, v98
	s_nop 0
	v_mul_f32_e32 v98, v104, v98
	v_mul_f32_e32 v104, v98, v100
	v_mul_f32_e32 v98, 0xbfb8aa3b, v105
	v_exp_f32_e32 v98, v98
	s_nop 0
	v_add_f32_e32 v98, 1.0, v98
	v_rcp_f32_e32 v98, v98
	s_nop 0
	v_mul_f32_e32 v98, v105, v98
	v_mul_f32_e32 v101, v98, v101
	v_cvt_pk_bf16_f32 v98, v106, v107
	v_cvt_pk_bf16_f32 v99, v108, v109
	v_cvt_pk_bf16_f32 v100, v110, v111
	v_cvt_pk_bf16_f32 v101, v104, v101
	global_store_dwordx4 v[102:103], v[98:101], off
	s_nop 1
	v_mul_f32_e32 v100, 0xbfb8aa3b, v94
	v_exp_f32_e32 v100, v100
	v_or_b32_e32 v98, 32, v139
	v_mad_i64_i32 v[98:99], s[6:7], v98, s74, v[134:135]
	v_add_f32_e32 v100, 1.0, v100
	v_rcp_f32_e32 v100, v100
	s_nop 0
	v_mul_f32_e32 v94, v94, v100
	v_mul_f32_e32 v90, v94, v90
	v_mul_f32_e32 v94, 0xbfb8aa3b, v95
	v_exp_f32_e32 v94, v94
	s_nop 0
	v_add_f32_e32 v94, 1.0, v94
	v_rcp_f32_e32 v94, v94
	s_nop 0
	v_mul_f32_e32 v94, v95, v94
	v_mul_f32_e32 v91, v94, v91
	v_mul_f32_e32 v94, 0xbfb8aa3b, v96
	v_exp_f32_e32 v94, v94
	s_nop 0
	v_add_f32_e32 v94, 1.0, v94
	v_rcp_f32_e32 v94, v94
	s_nop 0
	v_mul_f32_e32 v94, v96, v94
	v_mul_f32_e32 v92, v94, v92
	v_mul_f32_e32 v94, 0xbfb8aa3b, v97
	v_exp_f32_e32 v94, v94
	s_nop 0
	v_add_f32_e32 v94, 1.0, v94
	v_rcp_f32_e32 v94, v94
	s_nop 0
	v_mul_f32_e32 v94, v97, v94
	v_mul_f32_e32 v93, v94, v93
	v_mul_f32_e32 v94, 0xbfb8aa3b, v86
	v_exp_f32_e32 v94, v94
	s_nop 0
	v_add_f32_e32 v94, 1.0, v94
	v_rcp_f32_e32 v94, v94
	s_nop 0
	v_mul_f32_e32 v86, v86, v94
	v_mul_f32_e32 v94, v86, v82
	v_mul_f32_e32 v82, 0xbfb8aa3b, v87
	v_exp_f32_e32 v82, v82
	s_nop 0
	v_add_f32_e32 v82, 1.0, v82
	v_rcp_f32_e32 v82, v82
	s_nop 0
	v_mul_f32_e32 v82, v87, v82
	v_mul_f32_e32 v95, v82, v83
	v_mul_f32_e32 v82, 0xbfb8aa3b, v88
	v_exp_f32_e32 v82, v82
	v_lshl_add_u64 v[86:87], v[98:99], 0, v[114:115]
	v_add_f32_e32 v82, 1.0, v82
	v_rcp_f32_e32 v82, v82
	s_nop 0
	v_mul_f32_e32 v82, v88, v82
	v_mul_f32_e32 v88, v82, v84
	v_mul_f32_e32 v82, 0xbfb8aa3b, v89
	v_exp_f32_e32 v82, v82
	s_nop 0
	v_add_f32_e32 v82, 1.0, v82
	v_rcp_f32_e32 v82, v82
	s_nop 0
	v_mul_f32_e32 v82, v89, v82
	v_mul_f32_e32 v85, v82, v85
	v_cvt_pk_bf16_f32 v82, v90, v91
	v_cvt_pk_bf16_f32 v83, v92, v93
	v_cvt_pk_bf16_f32 v84, v94, v95
	v_cvt_pk_bf16_f32 v85, v88, v85
	global_store_dwordx4 v[86:87], v[82:85], off
	s_nop 1
	v_mul_f32_e32 v84, 0xbfb8aa3b, v78
	v_exp_f32_e32 v84, v84
	v_or_b32_e32 v82, 48, v139
	v_mad_i64_i32 v[82:83], s[6:7], v82, s74, v[134:135]
	v_add_f32_e32 v84, 1.0, v84
	v_rcp_f32_e32 v84, v84
	s_nop 0
	v_mul_f32_e32 v78, v78, v84
	v_mul_f32_e32 v74, v78, v74
	v_mul_f32_e32 v78, 0xbfb8aa3b, v79
	v_exp_f32_e32 v78, v78
	s_nop 0
	v_add_f32_e32 v78, 1.0, v78
	v_rcp_f32_e32 v78, v78
	s_nop 0
	v_mul_f32_e32 v78, v79, v78
	v_mul_f32_e32 v75, v78, v75
	v_mul_f32_e32 v78, 0xbfb8aa3b, v80
	v_exp_f32_e32 v78, v78
	s_nop 0
	v_add_f32_e32 v78, 1.0, v78
	v_rcp_f32_e32 v78, v78
	s_nop 0
	v_mul_f32_e32 v78, v80, v78
	v_mul_f32_e32 v76, v78, v76
	v_mul_f32_e32 v78, 0xbfb8aa3b, v81
	v_exp_f32_e32 v78, v78
	s_nop 0
	v_add_f32_e32 v78, 1.0, v78
	v_rcp_f32_e32 v78, v78
	s_nop 0
	v_mul_f32_e32 v78, v81, v78
	v_mul_f32_e32 v77, v78, v77
	v_mul_f32_e32 v78, 0xbfb8aa3b, v70
	v_exp_f32_e32 v78, v78
	s_nop 0
	v_add_f32_e32 v78, 1.0, v78
	v_rcp_f32_e32 v78, v78
	s_nop 0
	v_mul_f32_e32 v70, v70, v78
	v_mul_f32_e32 v78, v70, v66
	v_mul_f32_e32 v66, 0xbfb8aa3b, v71
	v_exp_f32_e32 v66, v66
	s_nop 0
	v_add_f32_e32 v66, 1.0, v66
	v_rcp_f32_e32 v66, v66
	s_nop 0
	v_mul_f32_e32 v66, v71, v66
	v_mul_f32_e32 v79, v66, v67
	v_mul_f32_e32 v66, 0xbfb8aa3b, v72
	v_exp_f32_e32 v66, v66
	v_lshl_add_u64 v[70:71], v[82:83], 0, v[114:115]
	v_add_f32_e32 v66, 1.0, v66
	v_rcp_f32_e32 v66, v66
	s_nop 0
	v_mul_f32_e32 v66, v72, v66
	v_mul_f32_e32 v72, v66, v68
	v_mul_f32_e32 v66, 0xbfb8aa3b, v73
	v_exp_f32_e32 v66, v66
	s_nop 0
	v_add_f32_e32 v66, 1.0, v66
	v_rcp_f32_e32 v66, v66
	s_nop 0
	v_mul_f32_e32 v66, v73, v66
	v_mul_f32_e32 v69, v66, v69
	v_cvt_pk_bf16_f32 v66, v74, v75
	v_cvt_pk_bf16_f32 v67, v76, v77
	v_cvt_pk_bf16_f32 v68, v78, v79
	v_cvt_pk_bf16_f32 v69, v72, v69
	global_store_dwordx4 v[70:71], v[66:69], off
	s_nop 1
	v_mul_f32_e32 v68, 0xbfb8aa3b, v62
	v_exp_f32_e32 v68, v68
	v_add_u32_e32 v66, 0x80, v139
	v_mad_i64_i32 v[66:67], s[6:7], v66, s74, v[134:135]
	v_add_f32_e32 v68, 1.0, v68
	v_rcp_f32_e32 v68, v68
	s_nop 0
	v_mul_f32_e32 v62, v62, v68
	v_mul_f32_e32 v58, v62, v58
	v_mul_f32_e32 v62, 0xbfb8aa3b, v63
	v_exp_f32_e32 v62, v62
	s_nop 0
	v_add_f32_e32 v62, 1.0, v62
	v_rcp_f32_e32 v62, v62
	s_nop 0
	v_mul_f32_e32 v62, v63, v62
	v_mul_f32_e32 v59, v62, v59
	v_mul_f32_e32 v62, 0xbfb8aa3b, v64
	v_exp_f32_e32 v62, v62
	s_nop 0
	v_add_f32_e32 v62, 1.0, v62
	v_rcp_f32_e32 v62, v62
	s_nop 0
	v_mul_f32_e32 v62, v64, v62
	v_mul_f32_e32 v60, v62, v60
	v_mul_f32_e32 v62, 0xbfb8aa3b, v65
	v_exp_f32_e32 v62, v62
	s_nop 0
	v_add_f32_e32 v62, 1.0, v62
	v_rcp_f32_e32 v62, v62
	s_nop 0
	v_mul_f32_e32 v62, v65, v62
	v_mul_f32_e32 v61, v62, v61
	v_mul_f32_e32 v62, 0xbfb8aa3b, v54
	v_exp_f32_e32 v62, v62
	s_nop 0
	v_add_f32_e32 v62, 1.0, v62
	v_rcp_f32_e32 v62, v62
	s_nop 0
	v_mul_f32_e32 v54, v54, v62
	v_mul_f32_e32 v62, v54, v50
	v_mul_f32_e32 v50, 0xbfb8aa3b, v55
	v_exp_f32_e32 v50, v50
	s_nop 0
	v_add_f32_e32 v50, 1.0, v50
	v_rcp_f32_e32 v50, v50
	s_nop 0
	v_mul_f32_e32 v50, v55, v50
	v_mul_f32_e32 v63, v50, v51
	v_mul_f32_e32 v50, 0xbfb8aa3b, v56
	v_exp_f32_e32 v50, v50
	v_lshl_add_u64 v[54:55], v[66:67], 0, v[114:115]
	v_add_f32_e32 v50, 1.0, v50
	v_rcp_f32_e32 v50, v50
	s_nop 0
	v_mul_f32_e32 v50, v56, v50
	v_mul_f32_e32 v56, v50, v52
	v_mul_f32_e32 v50, 0xbfb8aa3b, v57
	v_exp_f32_e32 v50, v50
	s_nop 0
	v_add_f32_e32 v50, 1.0, v50
	v_rcp_f32_e32 v50, v50
	s_nop 0
	v_mul_f32_e32 v50, v57, v50
	v_mul_f32_e32 v53, v50, v53
	v_cvt_pk_bf16_f32 v50, v58, v59
	v_cvt_pk_bf16_f32 v51, v60, v61
	v_cvt_pk_bf16_f32 v52, v62, v63
	v_cvt_pk_bf16_f32 v53, v56, v53
	global_store_dwordx4 v[54:55], v[50:53], off
	s_nop 1
	v_mul_f32_e32 v52, 0xbfb8aa3b, v46
	v_exp_f32_e32 v52, v52
	v_add_u32_e32 v50, 0x90, v139
	v_mad_i64_i32 v[50:51], s[6:7], v50, s74, v[134:135]
	v_add_f32_e32 v52, 1.0, v52
	v_rcp_f32_e32 v52, v52
	s_nop 0
	v_mul_f32_e32 v46, v46, v52
	v_mul_f32_e32 v42, v46, v42
	v_mul_f32_e32 v46, 0xbfb8aa3b, v47
	v_exp_f32_e32 v46, v46
	s_nop 0
	v_add_f32_e32 v46, 1.0, v46
	v_rcp_f32_e32 v46, v46
	s_nop 0
	v_mul_f32_e32 v46, v47, v46
	v_mul_f32_e32 v43, v46, v43
	v_mul_f32_e32 v46, 0xbfb8aa3b, v48
	v_exp_f32_e32 v46, v46
	s_nop 0
	v_add_f32_e32 v46, 1.0, v46
	v_rcp_f32_e32 v46, v46
	s_nop 0
	v_mul_f32_e32 v46, v48, v46
	v_mul_f32_e32 v44, v46, v44
	v_mul_f32_e32 v46, 0xbfb8aa3b, v49
	v_exp_f32_e32 v46, v46
	s_nop 0
	v_add_f32_e32 v46, 1.0, v46
	v_rcp_f32_e32 v46, v46
	s_nop 0
	v_mul_f32_e32 v46, v49, v46
	v_mul_f32_e32 v45, v46, v45
	v_mul_f32_e32 v46, 0xbfb8aa3b, v38
	v_exp_f32_e32 v46, v46
	s_nop 0
	v_add_f32_e32 v46, 1.0, v46
	v_rcp_f32_e32 v46, v46
	s_nop 0
	v_mul_f32_e32 v38, v38, v46
	v_mul_f32_e32 v46, v38, v34
	v_mul_f32_e32 v34, 0xbfb8aa3b, v39
	v_exp_f32_e32 v34, v34
	s_nop 0
	v_add_f32_e32 v34, 1.0, v34
	v_rcp_f32_e32 v34, v34
	s_nop 0
	v_mul_f32_e32 v34, v39, v34
	v_mul_f32_e32 v47, v34, v35
	v_mul_f32_e32 v34, 0xbfb8aa3b, v40
	v_exp_f32_e32 v34, v34
	v_lshl_add_u64 v[38:39], v[50:51], 0, v[114:115]
	v_add_f32_e32 v34, 1.0, v34
	v_rcp_f32_e32 v34, v34
	s_nop 0
	v_mul_f32_e32 v34, v40, v34
	v_mul_f32_e32 v40, v34, v36
	v_mul_f32_e32 v34, 0xbfb8aa3b, v41
	v_exp_f32_e32 v34, v34
	s_nop 0
	v_add_f32_e32 v34, 1.0, v34
	v_rcp_f32_e32 v34, v34
	s_nop 0
	v_mul_f32_e32 v34, v41, v34
	v_mul_f32_e32 v37, v34, v37
	v_cvt_pk_bf16_f32 v34, v42, v43
	v_cvt_pk_bf16_f32 v35, v44, v45
	v_cvt_pk_bf16_f32 v36, v46, v47
	v_cvt_pk_bf16_f32 v37, v40, v37
	global_store_dwordx4 v[38:39], v[34:37], off
	s_nop 1
	v_mul_f32_e32 v36, 0xbfb8aa3b, v30
	v_exp_f32_e32 v36, v36
	v_add_u32_e32 v34, 0xa0, v139
	v_mad_i64_i32 v[34:35], s[6:7], v34, s74, v[134:135]
	v_add_f32_e32 v36, 1.0, v36
	v_rcp_f32_e32 v36, v36
	s_nop 0
	v_mul_f32_e32 v30, v30, v36
	v_mul_f32_e32 v26, v30, v26
	v_mul_f32_e32 v30, 0xbfb8aa3b, v31
	v_exp_f32_e32 v30, v30
	s_nop 0
	v_add_f32_e32 v30, 1.0, v30
	v_rcp_f32_e32 v30, v30
	s_nop 0
	v_mul_f32_e32 v30, v31, v30
	v_mul_f32_e32 v27, v30, v27
	v_mul_f32_e32 v30, 0xbfb8aa3b, v32
	v_exp_f32_e32 v30, v30
	s_nop 0
	v_add_f32_e32 v30, 1.0, v30
	v_rcp_f32_e32 v30, v30
	s_nop 0
	v_mul_f32_e32 v30, v32, v30
	v_mul_f32_e32 v28, v30, v28
	v_mul_f32_e32 v30, 0xbfb8aa3b, v33
	v_exp_f32_e32 v30, v30
	s_nop 0
	v_add_f32_e32 v30, 1.0, v30
	v_rcp_f32_e32 v30, v30
	s_nop 0
	v_mul_f32_e32 v30, v33, v30
	v_mul_f32_e32 v29, v30, v29
	v_mul_f32_e32 v30, 0xbfb8aa3b, v22
	v_exp_f32_e32 v30, v30
	s_nop 0
	v_add_f32_e32 v30, 1.0, v30
	v_rcp_f32_e32 v30, v30
	s_nop 0
	v_mul_f32_e32 v22, v22, v30
	v_mul_f32_e32 v30, v22, v18
	v_mul_f32_e32 v18, 0xbfb8aa3b, v23
	v_exp_f32_e32 v18, v18
	s_nop 0
	v_add_f32_e32 v18, 1.0, v18
	v_rcp_f32_e32 v18, v18
	s_nop 0
	v_mul_f32_e32 v18, v23, v18
	v_mul_f32_e32 v31, v18, v19
	v_mul_f32_e32 v18, 0xbfb8aa3b, v24
	v_exp_f32_e32 v18, v18
	v_lshl_add_u64 v[22:23], v[34:35], 0, v[114:115]
	v_add_f32_e32 v18, 1.0, v18
	v_rcp_f32_e32 v18, v18
	s_nop 0
	v_mul_f32_e32 v18, v24, v18
	v_mul_f32_e32 v24, v18, v20
	v_mul_f32_e32 v18, 0xbfb8aa3b, v25
	v_exp_f32_e32 v18, v18
	s_nop 0
	v_add_f32_e32 v18, 1.0, v18
	v_rcp_f32_e32 v18, v18
	s_nop 0
	v_mul_f32_e32 v18, v25, v18
	v_mul_f32_e32 v21, v18, v21
	v_cvt_pk_bf16_f32 v18, v26, v27
	v_cvt_pk_bf16_f32 v19, v28, v29
	v_cvt_pk_bf16_f32 v20, v30, v31
	v_cvt_pk_bf16_f32 v21, v24, v21
	global_store_dwordx4 v[22:23], v[18:21], off
	s_nop 1
	v_mul_f32_e32 v20, 0xbfb8aa3b, v14
	v_exp_f32_e32 v20, v20
	v_add_u32_e32 v18, 0xb0, v139
	v_mad_i64_i32 v[18:19], s[6:7], v18, s74, v[134:135]
	v_add_f32_e32 v20, 1.0, v20
	v_rcp_f32_e32 v20, v20
	s_mov_b64 s[6:7], s[42:43]
	v_mul_f32_e32 v14, v14, v20
	v_mul_f32_e32 v10, v14, v10
	v_mul_f32_e32 v14, 0xbfb8aa3b, v15
	v_exp_f32_e32 v14, v14
	s_nop 0
	v_add_f32_e32 v14, 1.0, v14
	v_rcp_f32_e32 v14, v14
	s_nop 0
	v_mul_f32_e32 v14, v15, v14
	v_mul_f32_e32 v11, v14, v11
	v_mul_f32_e32 v14, 0xbfb8aa3b, v16
	v_exp_f32_e32 v14, v14
	s_nop 0
	v_add_f32_e32 v14, 1.0, v14
	v_rcp_f32_e32 v14, v14
	s_nop 0
	v_mul_f32_e32 v14, v16, v14
	v_mul_f32_e32 v12, v14, v12
	v_mul_f32_e32 v14, 0xbfb8aa3b, v17
	v_exp_f32_e32 v14, v14
	s_nop 0
	v_add_f32_e32 v14, 1.0, v14
	v_rcp_f32_e32 v14, v14
	s_nop 0
	v_mul_f32_e32 v14, v17, v14
	v_mul_f32_e32 v13, v14, v13
	v_mul_f32_e32 v14, 0xbfb8aa3b, v6
	v_exp_f32_e32 v14, v14
	s_nop 0
	v_add_f32_e32 v14, 1.0, v14
	v_rcp_f32_e32 v14, v14
	s_nop 0
	v_mul_f32_e32 v6, v6, v14
	v_mul_f32_e32 v14, v6, v2
	v_mul_f32_e32 v2, 0xbfb8aa3b, v7
	v_exp_f32_e32 v2, v2
	s_nop 0
	v_add_f32_e32 v2, 1.0, v2
	v_rcp_f32_e32 v2, v2
	s_nop 0
	v_mul_f32_e32 v2, v7, v2
	v_mul_f32_e32 v15, v2, v3
	v_mul_f32_e32 v2, 0xbfb8aa3b, v8
	v_exp_f32_e32 v2, v2
	v_lshl_add_u64 v[6:7], v[18:19], 0, v[114:115]
	v_add_f32_e32 v2, 1.0, v2
	v_rcp_f32_e32 v2, v2
	s_nop 0
	v_mul_f32_e32 v2, v8, v2
	v_mul_f32_e32 v8, v2, v4
	v_mul_f32_e32 v2, 0xbfb8aa3b, v9
	v_exp_f32_e32 v2, v2
	s_nop 0
	v_add_f32_e32 v2, 1.0, v2
	v_rcp_f32_e32 v2, v2
	s_nop 0
	v_mul_f32_e32 v2, v9, v2
	v_mul_f32_e32 v5, v2, v5
	v_cvt_pk_bf16_f32 v2, v10, v11
	v_cvt_pk_bf16_f32 v3, v12, v13
	v_cvt_pk_bf16_f32 v4, v14, v15
	v_cvt_pk_bf16_f32 v5, v8, v5
	global_store_dwordx4 v[6:7], v[2:5], off
	s_cbranch_vccz .LBB0_500
	s_waitcnt vmcnt(0)
	v_readlane_b32 s0, v255, 8
	v_readlane_b32 s62, v255, 10
	v_readlane_b32 s84, v255, 12
	s_cmpk_gt_u32 s22, 0xff
	v_readlane_b32 s1, v255, 9
	s_mov_b64 s[58:59], s[92:93]
	v_readlane_b32 s63, v255, 11
	v_readlane_b32 s85, v255, 13
	s_cbranch_scc1 .LBB0_507
	s_barrier

.Lrot_enter_2:
	s_add_u32 s7, s40, 0xfff80080
	s_addc_u32 s11, s41, -1
	s_add_i32 s49, 0, 0x10000
	v_add_u32_e32 v142, s49, v158
	ds_read_b128 v[130:133], v142
	ds_read_b128 v[134:137], v142 offset:1024
	ds_read_b128 v[138:141], v142 offset:2048
	ds_read_b128 v[142:145], v142 offset:3072
	s_cmp_eq_u32 s6, 4
	s_cselect_b32 s95, s51, s11
	s_cselect_b32 s94, s50, s7
	s_cselect_b32 s97, s53, s9
	s_cselect_b32 s96, s52, s8
	v_lshl_add_u64 v[156:157], s[40:41], 0, v[150:151]
	s_add_i32 m0, s55, 0xc000
	ds_read_b128 v[152:155], v159
	ds_read_b128 v[160:163], v159 offset:1024
	ds_read_b128 v[164:167], v159 offset:2048
	ds_read_b128 v[168:171], v159 offset:3072
	ds_read_b128 v[172:175], v159 offset:4096
	ds_read_b128 v[176:179], v159 offset:5120
	ds_read_b128 v[180:183], v159 offset:6144
	ds_read_b128 v[184:187], v159 offset:7168
	global_load_lds_dwordx4 v[156:157], off
	v_lshl_add_u64 v[156:157], v[156:157], 0, s[60:61]
	s_add_i32 m0, s55, 0xe000
	s_nop 0
	global_load_lds_dwordx4 v[156:157], off
	s_waitcnt lgkmcnt(8)
	s_barrier
	s_waitcnt lgkmcnt(0)
	v_mfma_f32_16x16x32_bf16 v[126:129], v[130:133], v[152:155], v[126:129]
	v_mfma_f32_16x16x32_bf16 v[122:125], v[138:141], v[152:155], v[122:125]
	v_mfma_f32_16x16x32_bf16 v[114:117], v[130:133], v[164:167], v[114:117]
	v_mfma_f32_16x16x32_bf16 v[110:113], v[138:141], v[164:167], v[110:113]
	v_mfma_f32_16x16x32_bf16 v[102:105], v[130:133], v[172:175], v[102:105]
	v_mfma_f32_16x16x32_bf16 v[94:97], v[138:141], v[172:175], v[94:97]
	v_mfma_f32_16x16x32_bf16 v[86:89], v[130:133], v[180:183], v[86:89]
	v_mfma_f32_16x16x32_bf16 v[78:81], v[138:141], v[180:183], v[78:81]
	v_mfma_f32_16x16x32_bf16 v[126:129], v[134:137], v[160:163], v[126:129]
	v_mfma_f32_16x16x32_bf16 v[122:125], v[142:145], v[160:163], v[122:125]
	v_mfma_f32_16x16x32_bf16 v[114:117], v[134:137], v[168:171], v[114:117]
	v_mfma_f32_16x16x32_bf16 v[110:113], v[142:145], v[168:171], v[110:113]
	v_mfma_f32_16x16x32_bf16 v[102:105], v[134:137], v[176:179], v[102:105]
	v_mfma_f32_16x16x32_bf16 v[94:97], v[142:145], v[176:179], v[94:97]
	v_mfma_f32_16x16x32_bf16 v[86:89], v[134:137], v[184:187], v[86:89]
	v_mfma_f32_16x16x32_bf16 v[78:81], v[142:145], v[184:187], v[78:81]
	s_barrier
	s_add_i32 s7, 0, 0x14000
	v_add_u32_e32 v156, s7, v158
	s_add_i32 s11, s49, s63
	ds_read_b128 v[188:191], v156
	ds_read_b128 v[192:195], v156 offset:1024
	ds_read_b128 v[196:199], v156 offset:2048
	ds_read_b128 v[200:203], v156 offset:3072
	v_lshl_add_u64 v[156:157], s[96:97], 0, v[0:1]
	s_mov_b32 m0, s11
	v_lshl_add_u64 v[204:205], v[156:157], 0, s[68:69]
	global_load_lds_dwordx4 v[156:157], off
	s_add_i32 m0, s11, 0x2000
	s_nop 0
	global_load_lds_dwordx4 v[204:205], off
	s_barrier
	s_waitcnt lgkmcnt(0)
	v_mfma_f32_16x16x32_bf16 v[118:121], v[188:191], v[152:155], v[118:121]
	v_mfma_f32_16x16x32_bf16 v[106:109], v[196:199], v[152:155], v[106:109]
	v_mfma_f32_16x16x32_bf16 v[98:101], v[188:191], v[164:167], v[98:101]
	v_mfma_f32_16x16x32_bf16 v[90:93], v[196:199], v[164:167], v[90:93]
	v_mfma_f32_16x16x32_bf16 v[82:85], v[188:191], v[172:175], v[82:85]
	v_mfma_f32_16x16x32_bf16 v[74:77], v[196:199], v[172:175], v[74:77]
	v_mfma_f32_16x16x32_bf16 v[70:73], v[188:191], v[180:183], v[70:73]
	v_mfma_f32_16x16x32_bf16 v[66:69], v[196:199], v[180:183], v[66:69]
	v_mfma_f32_16x16x32_bf16 v[118:121], v[192:195], v[160:163], v[118:121]
	ds_read_b128 v[152:155], v159 offset:16384
	v_mfma_f32_16x16x32_bf16 v[106:109], v[200:203], v[160:163], v[106:109]
	v_mfma_f32_16x16x32_bf16 v[98:101], v[192:195], v[168:171], v[98:101]
	ds_read_b128 v[164:167], v159 offset:18432
	v_mfma_f32_16x16x32_bf16 v[90:93], v[200:203], v[168:171], v[90:93]
	v_mfma_f32_16x16x32_bf16 v[82:85], v[192:195], v[176:179], v[82:85]
	ds_read_b128 v[172:175], v159 offset:20480
	v_mfma_f32_16x16x32_bf16 v[74:77], v[200:203], v[176:179], v[74:77]
	v_mfma_f32_16x16x32_bf16 v[70:73], v[192:195], v[184:187], v[70:73]
	ds_read_b128 v[180:183], v159 offset:22528
	v_mfma_f32_16x16x32_bf16 v[66:69], v[200:203], v[184:187], v[66:69]
	s_barrier
	s_mov_b32 m0, s55
	v_lshl_add_u64 v[204:205], s[94:95], 0, v[148:149]
	ds_read_b128 v[160:163], v159 offset:17408
	ds_read_b128 v[168:171], v159 offset:19456
	ds_read_b128 v[176:179], v159 offset:21504
	ds_read_b128 v[184:187], v159 offset:23552
	global_load_lds_dwordx4 v[204:205], off
	v_lshl_add_u64 v[206:207], v[204:205], 0, s[60:61]
	s_mov_b32 m0, s84
	s_nop 0
	global_load_lds_dwordx4 v[206:207], off
	s_barrier
	s_waitcnt lgkmcnt(0)
	v_mfma_f32_16x16x32_bf16 v[62:65], v[130:133], v[152:155], v[62:65]
	v_mfma_f32_16x16x32_bf16 v[58:61], v[138:141], v[152:155], v[58:61]
	v_mfma_f32_16x16x32_bf16 v[54:57], v[130:133], v[164:167], v[54:57]
	v_mfma_f32_16x16x32_bf16 v[46:49], v[138:141], v[164:167], v[46:49]
	v_mfma_f32_16x16x32_bf16 v[38:41], v[130:133], v[172:175], v[38:41]
	v_mfma_f32_16x16x32_bf16 v[30:33], v[138:141], v[172:175], v[30:33]
	v_mfma_f32_16x16x32_bf16 v[22:25], v[130:133], v[180:183], v[22:25]
	v_mfma_f32_16x16x32_bf16 v[14:17], v[138:141], v[180:183], v[14:17]
	v_mfma_f32_16x16x32_bf16 v[62:65], v[134:137], v[160:163], v[62:65]
	v_mfma_f32_16x16x32_bf16 v[58:61], v[142:145], v[160:163], v[58:61]
	v_mfma_f32_16x16x32_bf16 v[54:57], v[134:137], v[168:171], v[54:57]
	v_mfma_f32_16x16x32_bf16 v[46:49], v[142:145], v[168:171], v[46:49]
	v_mfma_f32_16x16x32_bf16 v[38:41], v[134:137], v[176:179], v[38:41]
	v_mfma_f32_16x16x32_bf16 v[30:33], v[142:145], v[176:179], v[30:33]
	v_mfma_f32_16x16x32_bf16 v[22:25], v[134:137], v[184:187], v[22:25]
	v_mfma_f32_16x16x32_bf16 v[14:17], v[142:145], v[184:187], v[14:17]
	s_barrier
	s_add_i32 s7, s7, s63
	v_lshl_add_u64 v[130:131], v[156:157], 0, vcc
	s_mov_b32 m0, s7
	s_nop 0
	global_load_lds_dwordx4 v[130:131], off
	v_lshl_add_u64 v[130:131], v[156:157], 0, s[78:79]
	s_add_i32 m0, s7, 0x2000
	s_nop 0
	global_load_lds_dwordx4 v[130:131], off
	v_lshl_add_u64 v[230:231], v[204:205], 0, s[20:21]
	s_mov_b32 m0, s85
	s_nop 0
	global_load_lds_dwordx4 v[230:231], off
	v_lshl_add_u64 v[230:231], v[204:205], 0, s[64:65]
	s_mov_b32 m0, s86
	s_nop 0
	global_load_lds_dwordx4 v[230:231], off
	s_waitcnt vmcnt(8)
	s_barrier
	v_mfma_f32_16x16x32_bf16 v[50:53], v[188:191], v[152:155], v[50:53]
	v_mfma_f32_16x16x32_bf16 v[42:45], v[196:199], v[152:155], v[42:45]
	v_mfma_f32_16x16x32_bf16 v[34:37], v[188:191], v[164:167], v[34:37]
	v_mfma_f32_16x16x32_bf16 v[26:29], v[196:199], v[164:167], v[26:29]
	v_mfma_f32_16x16x32_bf16 v[18:21], v[188:191], v[172:175], v[18:21]
	v_mfma_f32_16x16x32_bf16 v[10:13], v[196:199], v[172:175], v[10:13]
	v_mfma_f32_16x16x32_bf16 v[6:9], v[188:191], v[180:183], v[6:9]
	v_mfma_f32_16x16x32_bf16 v[2:5], v[196:199], v[180:183], v[2:5]
	v_mfma_f32_16x16x32_bf16 v[50:53], v[192:195], v[160:163], v[50:53]
	v_mfma_f32_16x16x32_bf16 v[42:45], v[200:203], v[160:163], v[42:45]
	v_mfma_f32_16x16x32_bf16 v[34:37], v[192:195], v[168:171], v[34:37]
	v_mfma_f32_16x16x32_bf16 v[26:29], v[200:203], v[168:171], v[26:29]
	v_mfma_f32_16x16x32_bf16 v[18:21], v[192:195], v[176:179], v[18:21]
	v_mfma_f32_16x16x32_bf16 v[10:13], v[200:203], v[176:179], v[10:13]
	v_mfma_f32_16x16x32_bf16 v[6:9], v[192:195], v[184:187], v[6:9]
	v_mfma_f32_16x16x32_bf16 v[2:5], v[200:203], v[184:187], v[2:5]
	s_barrier
	s_add_i32 s7, 0, 0x18000
	v_add_u32_e32 v142, s7, v158
	ds_read_b128 v[130:133], v142
	ds_read_b128 v[134:137], v142 offset:1024
	ds_read_b128 v[138:141], v142 offset:2048
	ds_read_b128 v[142:145], v142 offset:3072
	ds_read_b128 v[152:155], v159 offset:32768
	ds_read_b128 v[160:163], v159 offset:33792
	ds_read_b128 v[164:167], v159 offset:34816
	ds_read_b128 v[168:171], v159 offset:35840
	ds_read_b128 v[172:175], v159 offset:36864
	ds_read_b128 v[176:179], v159 offset:37888
	ds_read_b128 v[180:183], v159 offset:38912
	ds_read_b128 v[184:187], v159 offset:39936
	s_waitcnt lgkmcnt(8)
	s_barrier
	s_waitcnt lgkmcnt(0)
	v_mfma_f32_16x16x32_bf16 v[126:129], v[130:133], v[152:155], v[126:129]
	v_mfma_f32_16x16x32_bf16 v[122:125], v[138:141], v[152:155], v[122:125]
	v_mfma_f32_16x16x32_bf16 v[114:117], v[130:133], v[164:167], v[114:117]
	v_mfma_f32_16x16x32_bf16 v[110:113], v[138:141], v[164:167], v[110:113]
	v_mfma_f32_16x16x32_bf16 v[102:105], v[130:133], v[172:175], v[102:105]
	v_mfma_f32_16x16x32_bf16 v[94:97], v[138:141], v[172:175], v[94:97]
	v_mfma_f32_16x16x32_bf16 v[86:89], v[130:133], v[180:183], v[86:89]
	v_mfma_f32_16x16x32_bf16 v[78:81], v[138:141], v[180:183], v[78:81]
	v_mfma_f32_16x16x32_bf16 v[126:129], v[134:137], v[160:163], v[126:129]
	v_mfma_f32_16x16x32_bf16 v[122:125], v[142:145], v[160:163], v[122:125]
	v_mfma_f32_16x16x32_bf16 v[114:117], v[134:137], v[168:171], v[114:117]
	v_mfma_f32_16x16x32_bf16 v[110:113], v[142:145], v[168:171], v[110:113]
	v_mfma_f32_16x16x32_bf16 v[102:105], v[134:137], v[176:179], v[102:105]
	v_mfma_f32_16x16x32_bf16 v[94:97], v[142:145], v[176:179], v[94:97]
	v_mfma_f32_16x16x32_bf16 v[86:89], v[134:137], v[184:187], v[86:89]
	v_mfma_f32_16x16x32_bf16 v[78:81], v[142:145], v[184:187], v[78:81]
	s_barrier
	s_add_i32 s11, 0, 0x1c000
	s_add_i32 s7, s7, s63
	v_add_u32_e32 v200, s11, v158
	v_lshl_add_u64 v[206:207], v[156:157], 0, s[34:35]
	s_mov_b32 m0, s7
	ds_read_b128 v[188:191], v200
	ds_read_b128 v[192:195], v200 offset:1024
	ds_read_b128 v[196:199], v200 offset:2048
	ds_read_b128 v[200:203], v200 offset:3072
	global_load_lds_dwordx4 v[206:207], off
	v_lshl_add_u64 v[206:207], v[156:157], 0, s[38:39]
	s_add_i32 m0, s7, 0x2000
	s_nop 0
	global_load_lds_dwordx4 v[206:207], off
	s_barrier
	s_waitcnt lgkmcnt(0)
	v_mfma_f32_16x16x32_bf16 v[118:121], v[188:191], v[152:155], v[118:121]
	v_mfma_f32_16x16x32_bf16 v[106:109], v[196:199], v[152:155], v[106:109]
	v_mfma_f32_16x16x32_bf16 v[98:101], v[188:191], v[164:167], v[98:101]
	v_mfma_f32_16x16x32_bf16 v[90:93], v[196:199], v[164:167], v[90:93]
	v_mfma_f32_16x16x32_bf16 v[82:85], v[188:191], v[172:175], v[82:85]
	v_mfma_f32_16x16x32_bf16 v[74:77], v[196:199], v[172:175], v[74:77]
	v_mfma_f32_16x16x32_bf16 v[70:73], v[188:191], v[180:183], v[70:73]
	v_mfma_f32_16x16x32_bf16 v[66:69], v[196:199], v[180:183], v[66:69]
	v_mfma_f32_16x16x32_bf16 v[118:121], v[192:195], v[160:163], v[118:121]
	ds_read_b128 v[152:155], v159 offset:49152
	v_mfma_f32_16x16x32_bf16 v[106:109], v[200:203], v[160:163], v[106:109]
	v_mfma_f32_16x16x32_bf16 v[98:101], v[192:195], v[168:171], v[98:101]
	ds_read_b128 v[164:167], v159 offset:51200
	v_mfma_f32_16x16x32_bf16 v[90:93], v[200:203], v[168:171], v[90:93]
	v_mfma_f32_16x16x32_bf16 v[82:85], v[192:195], v[176:179], v[82:85]
	ds_read_b128 v[172:175], v159 offset:53248
	v_mfma_f32_16x16x32_bf16 v[74:77], v[200:203], v[176:179], v[74:77]
	v_mfma_f32_16x16x32_bf16 v[70:73], v[192:195], v[184:187], v[70:73]
	ds_read_b128 v[180:183], v159 offset:55296
	v_mfma_f32_16x16x32_bf16 v[66:69], v[200:203], v[184:187], v[66:69]
	s_barrier
	s_mov_b32 m0, s89
	v_lshl_add_u64 v[206:207], v[204:205], 0, s[34:35]
	ds_read_b128 v[160:163], v159 offset:50176
	ds_read_b128 v[168:171], v159 offset:52224
	ds_read_b128 v[176:179], v159 offset:54272
	ds_read_b128 v[184:187], v159 offset:56320
	global_load_lds_dwordx4 v[206:207], off
	v_lshl_add_u64 v[204:205], v[204:205], 0, s[66:67]
	s_mov_b32 m0, s90
	s_nop 0
	global_load_lds_dwordx4 v[204:205], off
	s_barrier
	s_waitcnt lgkmcnt(0)
	v_mfma_f32_16x16x32_bf16 v[62:65], v[130:133], v[152:155], v[62:65]
	v_mfma_f32_16x16x32_bf16 v[58:61], v[138:141], v[152:155], v[58:61]
	v_mfma_f32_16x16x32_bf16 v[54:57], v[130:133], v[164:167], v[54:57]
	v_mfma_f32_16x16x32_bf16 v[46:49], v[138:141], v[164:167], v[46:49]
	v_mfma_f32_16x16x32_bf16 v[38:41], v[130:133], v[172:175], v[38:41]
	v_mfma_f32_16x16x32_bf16 v[30:33], v[138:141], v[172:175], v[30:33]
	v_mfma_f32_16x16x32_bf16 v[22:25], v[130:133], v[180:183], v[22:25]
	v_mfma_f32_16x16x32_bf16 v[14:17], v[138:141], v[180:183], v[14:17]
	v_mfma_f32_16x16x32_bf16 v[62:65], v[134:137], v[160:163], v[62:65]
	v_mfma_f32_16x16x32_bf16 v[58:61], v[142:145], v[160:163], v[58:61]
	v_mfma_f32_16x16x32_bf16 v[54:57], v[134:137], v[168:171], v[54:57]
	v_mfma_f32_16x16x32_bf16 v[46:49], v[142:145], v[168:171], v[46:49]
	v_mfma_f32_16x16x32_bf16 v[38:41], v[134:137], v[176:179], v[38:41]
	v_mfma_f32_16x16x32_bf16 v[30:33], v[142:145], v[176:179], v[30:33]
	v_mfma_f32_16x16x32_bf16 v[22:25], v[134:137], v[184:187], v[22:25]
	v_mfma_f32_16x16x32_bf16 v[14:17], v[142:145], v[184:187], v[14:17]
	s_barrier
	s_add_i32 s7, s11, s63
	v_lshl_add_u64 v[130:131], v[156:157], 0, s[72:73]
	s_mov_b32 m0, s7
	s_nop 0
	global_load_lds_dwordx4 v[130:131], off
	v_lshl_add_u64 v[130:131], v[156:157], 0, s[56:57]
	s_add_i32 m0, s7, 0x2000
	s_nop 0
	global_load_lds_dwordx4 v[130:131], off
	s_waitcnt vmcnt(6)
	s_add_i32 s6, s6, 2
	s_add_u32 s8, s8, 0x100
	s_addc_u32 s9, s9, 0
	s_add_u32 s40, s40, 0x100
	s_addc_u32 s41, s41, 0
	s_cmp_gt_u32 s6, 5
	s_cbranch_scc0 .LBB0_578
	s_barrier
	v_mfma_f32_16x16x32_bf16 v[50:53], v[188:191], v[152:155], v[50:53]
	v_mfma_f32_16x16x32_bf16 v[42:45], v[196:199], v[152:155], v[42:45]
	v_mfma_f32_16x16x32_bf16 v[34:37], v[188:191], v[164:167], v[34:37]
	v_mfma_f32_16x16x32_bf16 v[26:29], v[196:199], v[164:167], v[26:29]
	v_mfma_f32_16x16x32_bf16 v[18:21], v[188:191], v[172:175], v[18:21]
	v_mfma_f32_16x16x32_bf16 v[10:13], v[196:199], v[172:175], v[10:13]
	v_mfma_f32_16x16x32_bf16 v[6:9], v[188:191], v[180:183], v[6:9]
	v_mfma_f32_16x16x32_bf16 v[2:5], v[196:199], v[180:183], v[2:5]
	v_mfma_f32_16x16x32_bf16 v[50:53], v[192:195], v[160:163], v[50:53]
	v_mfma_f32_16x16x32_bf16 v[42:45], v[200:203], v[160:163], v[42:45]
	v_mfma_f32_16x16x32_bf16 v[34:37], v[192:195], v[168:171], v[34:37]
	v_mfma_f32_16x16x32_bf16 v[26:29], v[200:203], v[168:171], v[26:29]
	v_mfma_f32_16x16x32_bf16 v[18:21], v[192:195], v[176:179], v[18:21]
	v_mfma_f32_16x16x32_bf16 v[10:13], v[200:203], v[176:179], v[10:13]
	v_mfma_f32_16x16x32_bf16 v[6:9], v[192:195], v[184:187], v[6:9]
	v_mfma_f32_16x16x32_bf16 v[2:5], v[200:203], v[184:187], v[2:5]
	s_barrier
	v_mov_b32_e32 v156, v146
	s_lshl_b32 s6, s92, 8
	v_ashrrev_i32_e32 v130, 2, v156
	s_or_b32 s6, s6, s88
	v_and_b32_e32 v130, -4, v130
	v_add_u32_e32 v152, s6, v130
	v_ashrrev_i32_e32 v153, 31, v152
	v_cndmask_b32_e64 v131, 0, 1, s[44:45]
	v_lshl_add_u64 v[154:155], v[152:153], 2, s[42:43]
	v_mov_b32_e32 v130, 1.0
	v_cmp_ne_u32_e64 s[40:41], 1, v131
	s_andn2_b64 vcc, exec, s[44:45]
	v_mov_b32_e32 v134, 1.0
	v_mov_b32_e32 v135, 1.0
	v_mov_b32_e32 v136, 1.0
	v_mov_b32_e32 v137, 1.0
	s_cbranch_vccnz .LBB0_581
	global_load_dwordx4 v[134:137], v[154:155], off

.Lrot_enter_1:
	s_add_u32 s7, s48, 0xffea0080
	s_addc_u32 s78, s49, -1
	s_add_i32 s79, 0, 0x10000
	v_add_u32_e32 v132, s79, v135
	ds_read_b128 v[138:141], v132
	ds_read_b128 v[142:145], v132 offset:1024
	ds_read_b128 v[148:151], v132 offset:2048
	ds_read_b128 v[152:155], v132 offset:3072
	s_cmpk_eq_i32 s6, 0x54
	s_cselect_b32 s91, s45, s78
	s_cselect_b32 s90, s44, s7
	s_cselect_b32 s93, s47, s9
	s_cselect_b32 s92, s46, s8
	v_lshl_add_u64 v[132:133], s[48:49], 0, v[130:131]
	s_add_i32 m0, s56, 0xc000
	ds_read_b128 v[156:159], v136
	ds_read_b128 v[160:163], v136 offset:1024
	ds_read_b128 v[164:167], v136 offset:2048
	ds_read_b128 v[168:171], v136 offset:3072
	ds_read_b128 v[172:175], v136 offset:4096
	ds_read_b128 v[176:179], v136 offset:5120
	ds_read_b128 v[180:183], v136 offset:6144
	ds_read_b128 v[184:187], v136 offset:7168
	global_load_lds_dwordx4 v[132:133], off
	v_lshl_add_u64 v[132:133], v[132:133], 0, s[26:27]
	s_add_i32 m0, s56, 0xe000
	s_nop 0
	global_load_lds_dwordx4 v[132:133], off
	s_waitcnt lgkmcnt(8)
	s_barrier
	s_waitcnt lgkmcnt(0)
	v_mfma_f32_16x16x32_bf16 v[126:129], v[138:141], v[156:159], v[126:129]
	v_mfma_f32_16x16x32_bf16 v[122:125], v[148:151], v[156:159], v[122:125]
	v_mfma_f32_16x16x32_bf16 v[118:121], v[138:141], v[164:167], v[118:121]
	v_mfma_f32_16x16x32_bf16 v[110:113], v[148:151], v[164:167], v[110:113]
	v_mfma_f32_16x16x32_bf16 v[102:105], v[138:141], v[172:175], v[102:105]
	v_mfma_f32_16x16x32_bf16 v[94:97], v[148:151], v[172:175], v[94:97]
	v_mfma_f32_16x16x32_bf16 v[86:89], v[138:141], v[180:183], v[86:89]
	v_mfma_f32_16x16x32_bf16 v[78:81], v[148:151], v[180:183], v[78:81]
	v_mfma_f32_16x16x32_bf16 v[126:129], v[142:145], v[160:163], v[126:129]
	v_mfma_f32_16x16x32_bf16 v[122:125], v[152:155], v[160:163], v[122:125]
	v_mfma_f32_16x16x32_bf16 v[118:121], v[142:145], v[168:171], v[118:121]
	v_mfma_f32_16x16x32_bf16 v[110:113], v[152:155], v[168:171], v[110:113]
	v_mfma_f32_16x16x32_bf16 v[102:105], v[142:145], v[176:179], v[102:105]
	v_mfma_f32_16x16x32_bf16 v[94:97], v[152:155], v[176:179], v[94:97]
	v_mfma_f32_16x16x32_bf16 v[86:89], v[142:145], v[184:187], v[86:89]
	v_mfma_f32_16x16x32_bf16 v[78:81], v[152:155], v[184:187], v[78:81]
	s_barrier
	s_add_i32 s7, 0, 0x14000
	v_add_u32_e32 v132, s7, v135
	s_add_i32 s78, s79, s55
	ds_read_b128 v[188:191], v132
	ds_read_b128 v[192:195], v132 offset:1024
	ds_read_b128 v[196:199], v132 offset:2048
	ds_read_b128 v[200:203], v132 offset:3072
	v_lshl_add_u64 v[132:133], s[92:93], 0, v[0:1]
	s_mov_b32 m0, s78
	v_lshl_add_u64 v[204:205], v[132:133], 0, s[26:27]
	global_load_lds_dwordx4 v[132:133], off
	s_add_i32 m0, s78, 0x2000
	s_nop 0
	global_load_lds_dwordx4 v[204:205], off
	s_barrier
	s_waitcnt lgkmcnt(0)
	v_mfma_f32_16x16x32_bf16 v[114:117], v[188:191], v[156:159], v[114:117]
	v_mfma_f32_16x16x32_bf16 v[106:109], v[196:199], v[156:159], v[106:109]
	v_mfma_f32_16x16x32_bf16 v[98:101], v[188:191], v[164:167], v[98:101]
	v_mfma_f32_16x16x32_bf16 v[90:93], v[196:199], v[164:167], v[90:93]
	v_mfma_f32_16x16x32_bf16 v[82:85], v[188:191], v[172:175], v[82:85]
	v_mfma_f32_16x16x32_bf16 v[74:77], v[196:199], v[172:175], v[74:77]
	v_mfma_f32_16x16x32_bf16 v[70:73], v[188:191], v[180:183], v[70:73]
	v_mfma_f32_16x16x32_bf16 v[66:69], v[196:199], v[180:183], v[66:69]
	v_mfma_f32_16x16x32_bf16 v[114:117], v[192:195], v[160:163], v[114:117]
	ds_read_b128 v[156:159], v136 offset:16384
	v_mfma_f32_16x16x32_bf16 v[106:109], v[200:203], v[160:163], v[106:109]
	v_mfma_f32_16x16x32_bf16 v[98:101], v[192:195], v[168:171], v[98:101]
	ds_read_b128 v[164:167], v136 offset:18432
	v_mfma_f32_16x16x32_bf16 v[90:93], v[200:203], v[168:171], v[90:93]
	v_mfma_f32_16x16x32_bf16 v[82:85], v[192:195], v[176:179], v[82:85]
	ds_read_b128 v[172:175], v136 offset:20480
	v_mfma_f32_16x16x32_bf16 v[74:77], v[200:203], v[176:179], v[74:77]
	v_mfma_f32_16x16x32_bf16 v[70:73], v[192:195], v[184:187], v[70:73]
	ds_read_b128 v[180:183], v136 offset:22528
	v_mfma_f32_16x16x32_bf16 v[66:69], v[200:203], v[184:187], v[66:69]
	s_barrier
	s_mov_b32 m0, s56
	v_lshl_add_u64 v[204:205], s[90:91], 0, v[0:1]
	ds_read_b128 v[160:163], v136 offset:17408
	ds_read_b128 v[168:171], v136 offset:19456
	ds_read_b128 v[176:179], v136 offset:21504
	ds_read_b128 v[184:187], v136 offset:23552
	global_load_lds_dwordx4 v[204:205], off
	v_lshl_add_u64 v[206:207], v[204:205], 0, s[26:27]
	s_mov_b32 m0, s57
	s_nop 0
	global_load_lds_dwordx4 v[206:207], off
	s_barrier
	s_waitcnt lgkmcnt(0)
	v_mfma_f32_16x16x32_bf16 v[62:65], v[138:141], v[156:159], v[62:65]
	v_mfma_f32_16x16x32_bf16 v[58:61], v[148:151], v[156:159], v[58:61]
	v_mfma_f32_16x16x32_bf16 v[54:57], v[138:141], v[164:167], v[54:57]
	v_mfma_f32_16x16x32_bf16 v[46:49], v[148:151], v[164:167], v[46:49]
	v_mfma_f32_16x16x32_bf16 v[38:41], v[138:141], v[172:175], v[38:41]
	v_mfma_f32_16x16x32_bf16 v[30:33], v[148:151], v[172:175], v[30:33]
	v_mfma_f32_16x16x32_bf16 v[22:25], v[138:141], v[180:183], v[22:25]
	v_mfma_f32_16x16x32_bf16 v[14:17], v[148:151], v[180:183], v[14:17]
	v_mfma_f32_16x16x32_bf16 v[62:65], v[142:145], v[160:163], v[62:65]
	v_mfma_f32_16x16x32_bf16 v[58:61], v[152:155], v[160:163], v[58:61]
	v_mfma_f32_16x16x32_bf16 v[54:57], v[142:145], v[168:171], v[54:57]
	v_mfma_f32_16x16x32_bf16 v[46:49], v[152:155], v[168:171], v[46:49]
	v_mfma_f32_16x16x32_bf16 v[38:41], v[142:145], v[176:179], v[38:41]
	v_mfma_f32_16x16x32_bf16 v[30:33], v[152:155], v[176:179], v[30:33]
	v_mfma_f32_16x16x32_bf16 v[22:25], v[142:145], v[184:187], v[22:25]
	v_mfma_f32_16x16x32_bf16 v[14:17], v[152:155], v[184:187], v[14:17]
	s_barrier
	s_add_i32 s7, s7, s55
	v_lshl_add_u64 v[138:139], v[132:133], 0, s[28:29]
	s_mov_b32 m0, s7
	s_nop 0
	global_load_lds_dwordx4 v[138:139], off
	v_lshl_add_u64 v[138:139], v[132:133], 0, s[30:31]
	s_add_i32 m0, s7, 0x2000
	s_nop 0
	global_load_lds_dwordx4 v[138:139], off
	v_lshl_add_u64 v[230:231], v[204:205], 0, s[28:29]
	s_mov_b32 m0, s58
	s_nop 0
	global_load_lds_dwordx4 v[230:231], off
	v_lshl_add_u64 v[230:231], v[204:205], 0, s[30:31]
	s_mov_b32 m0, s59
	s_nop 0
	global_load_lds_dwordx4 v[230:231], off
	s_waitcnt vmcnt(8)
	s_barrier
	v_mfma_f32_16x16x32_bf16 v[50:53], v[188:191], v[156:159], v[50:53]
	v_mfma_f32_16x16x32_bf16 v[42:45], v[196:199], v[156:159], v[42:45]
	v_mfma_f32_16x16x32_bf16 v[34:37], v[188:191], v[164:167], v[34:37]
	v_mfma_f32_16x16x32_bf16 v[26:29], v[196:199], v[164:167], v[26:29]
	v_mfma_f32_16x16x32_bf16 v[18:21], v[188:191], v[172:175], v[18:21]
	v_mfma_f32_16x16x32_bf16 v[10:13], v[196:199], v[172:175], v[10:13]
	v_mfma_f32_16x16x32_bf16 v[6:9], v[188:191], v[180:183], v[6:9]
	v_mfma_f32_16x16x32_bf16 v[2:5], v[196:199], v[180:183], v[2:5]
	v_mfma_f32_16x16x32_bf16 v[50:53], v[192:195], v[160:163], v[50:53]
	v_mfma_f32_16x16x32_bf16 v[42:45], v[200:203], v[160:163], v[42:45]
	v_mfma_f32_16x16x32_bf16 v[34:37], v[192:195], v[168:171], v[34:37]
	v_mfma_f32_16x16x32_bf16 v[26:29], v[200:203], v[168:171], v[26:29]
	v_mfma_f32_16x16x32_bf16 v[18:21], v[192:195], v[176:179], v[18:21]
	v_mfma_f32_16x16x32_bf16 v[10:13], v[200:203], v[176:179], v[10:13]
	v_mfma_f32_16x16x32_bf16 v[6:9], v[192:195], v[184:187], v[6:9]
	v_mfma_f32_16x16x32_bf16 v[2:5], v[200:203], v[184:187], v[2:5]
	s_barrier
	s_add_i32 s7, 0, 0x18000
	v_add_u32_e32 v137, s7, v135
	ds_read_b128 v[138:141], v137
	ds_read_b128 v[142:145], v137 offset:1024
	ds_read_b128 v[148:151], v137 offset:2048
	ds_read_b128 v[152:155], v137 offset:3072
	ds_read_b128 v[156:159], v136 offset:32768
	ds_read_b128 v[160:163], v136 offset:33792
	ds_read_b128 v[164:167], v136 offset:34816
	ds_read_b128 v[168:171], v136 offset:35840
	ds_read_b128 v[172:175], v136 offset:36864
	ds_read_b128 v[176:179], v136 offset:37888
	ds_read_b128 v[180:183], v136 offset:38912
	ds_read_b128 v[184:187], v136 offset:39936
	s_waitcnt lgkmcnt(8)
	s_barrier
	s_waitcnt lgkmcnt(0)
	v_mfma_f32_16x16x32_bf16 v[126:129], v[138:141], v[156:159], v[126:129]
	v_mfma_f32_16x16x32_bf16 v[122:125], v[148:151], v[156:159], v[122:125]
	v_mfma_f32_16x16x32_bf16 v[118:121], v[138:141], v[164:167], v[118:121]
	v_mfma_f32_16x16x32_bf16 v[110:113], v[148:151], v[164:167], v[110:113]
	v_mfma_f32_16x16x32_bf16 v[102:105], v[138:141], v[172:175], v[102:105]
	v_mfma_f32_16x16x32_bf16 v[94:97], v[148:151], v[172:175], v[94:97]
	v_mfma_f32_16x16x32_bf16 v[86:89], v[138:141], v[180:183], v[86:89]
	v_mfma_f32_16x16x32_bf16 v[78:81], v[148:151], v[180:183], v[78:81]
	v_mfma_f32_16x16x32_bf16 v[126:129], v[142:145], v[160:163], v[126:129]
	v_mfma_f32_16x16x32_bf16 v[122:125], v[152:155], v[160:163], v[122:125]
	v_mfma_f32_16x16x32_bf16 v[118:121], v[142:145], v[168:171], v[118:121]
	v_mfma_f32_16x16x32_bf16 v[110:113], v[152:155], v[168:171], v[110:113]
	v_mfma_f32_16x16x32_bf16 v[102:105], v[142:145], v[176:179], v[102:105]
	v_mfma_f32_16x16x32_bf16 v[94:97], v[152:155], v[176:179], v[94:97]
	v_mfma_f32_16x16x32_bf16 v[86:89], v[142:145], v[184:187], v[86:89]
	v_mfma_f32_16x16x32_bf16 v[78:81], v[152:155], v[184:187], v[78:81]
	s_barrier
	s_add_i32 s78, 0, 0x1c000
	s_add_i32 s7, s7, s55
	v_add_u32_e32 v137, s78, v135
	v_lshl_add_u64 v[206:207], v[132:133], 0, s[34:35]
	s_mov_b32 m0, s7
	ds_read_b128 v[188:191], v137
	ds_read_b128 v[192:195], v137 offset:1024
	ds_read_b128 v[196:199], v137 offset:2048
	ds_read_b128 v[200:203], v137 offset:3072
	global_load_lds_dwordx4 v[206:207], off
	v_lshl_add_u64 v[206:207], v[132:133], 0, s[36:37]
	s_add_i32 m0, s7, 0x2000
	s_nop 0
	global_load_lds_dwordx4 v[206:207], off
	s_barrier
	s_waitcnt lgkmcnt(0)
	v_mfma_f32_16x16x32_bf16 v[114:117], v[188:191], v[156:159], v[114:117]
	v_mfma_f32_16x16x32_bf16 v[106:109], v[196:199], v[156:159], v[106:109]
	v_mfma_f32_16x16x32_bf16 v[98:101], v[188:191], v[164:167], v[98:101]
	v_mfma_f32_16x16x32_bf16 v[90:93], v[196:199], v[164:167], v[90:93]
	v_mfma_f32_16x16x32_bf16 v[82:85], v[188:191], v[172:175], v[82:85]
	v_mfma_f32_16x16x32_bf16 v[74:77], v[196:199], v[172:175], v[74:77]
	v_mfma_f32_16x16x32_bf16 v[70:73], v[188:191], v[180:183], v[70:73]
	v_mfma_f32_16x16x32_bf16 v[66:69], v[196:199], v[180:183], v[66:69]
	v_mfma_f32_16x16x32_bf16 v[114:117], v[192:195], v[160:163], v[114:117]
	ds_read_b128 v[156:159], v136 offset:49152
	v_mfma_f32_16x16x32_bf16 v[106:109], v[200:203], v[160:163], v[106:109]
	v_mfma_f32_16x16x32_bf16 v[98:101], v[192:195], v[168:171], v[98:101]
	ds_read_b128 v[164:167], v136 offset:51200
	v_mfma_f32_16x16x32_bf16 v[90:93], v[200:203], v[168:171], v[90:93]
	v_mfma_f32_16x16x32_bf16 v[82:85], v[192:195], v[176:179], v[82:85]
	ds_read_b128 v[172:175], v136 offset:53248
	v_mfma_f32_16x16x32_bf16 v[74:77], v[200:203], v[176:179], v[74:77]
	v_mfma_f32_16x16x32_bf16 v[70:73], v[192:195], v[184:187], v[70:73]
	ds_read_b128 v[180:183], v136 offset:55296
	v_mfma_f32_16x16x32_bf16 v[66:69], v[200:203], v[184:187], v[66:69]
	s_barrier
	s_mov_b32 m0, s84
	v_lshl_add_u64 v[206:207], v[204:205], 0, s[34:35]
	ds_read_b128 v[160:163], v136 offset:50176
	ds_read_b128 v[168:171], v136 offset:52224
	ds_read_b128 v[176:179], v136 offset:54272
	ds_read_b128 v[184:187], v136 offset:56320
	global_load_lds_dwordx4 v[206:207], off
	v_lshl_add_u64 v[204:205], v[204:205], 0, s[36:37]
	s_mov_b32 m0, s85
	s_nop 0
	global_load_lds_dwordx4 v[204:205], off
	s_barrier
	s_waitcnt lgkmcnt(0)
	v_mfma_f32_16x16x32_bf16 v[62:65], v[138:141], v[156:159], v[62:65]
	v_mfma_f32_16x16x32_bf16 v[58:61], v[148:151], v[156:159], v[58:61]
	v_mfma_f32_16x16x32_bf16 v[54:57], v[138:141], v[164:167], v[54:57]
	v_mfma_f32_16x16x32_bf16 v[46:49], v[148:151], v[164:167], v[46:49]
	v_mfma_f32_16x16x32_bf16 v[38:41], v[138:141], v[172:175], v[38:41]
	v_mfma_f32_16x16x32_bf16 v[30:33], v[148:151], v[172:175], v[30:33]
	v_mfma_f32_16x16x32_bf16 v[22:25], v[138:141], v[180:183], v[22:25]
	v_mfma_f32_16x16x32_bf16 v[14:17], v[148:151], v[180:183], v[14:17]
	v_mfma_f32_16x16x32_bf16 v[62:65], v[142:145], v[160:163], v[62:65]
	v_mfma_f32_16x16x32_bf16 v[58:61], v[152:155], v[160:163], v[58:61]
	v_mfma_f32_16x16x32_bf16 v[54:57], v[142:145], v[168:171], v[54:57]
	v_mfma_f32_16x16x32_bf16 v[46:49], v[152:155], v[168:171], v[46:49]
	v_mfma_f32_16x16x32_bf16 v[38:41], v[142:145], v[176:179], v[38:41]
	v_mfma_f32_16x16x32_bf16 v[30:33], v[152:155], v[176:179], v[30:33]
	v_mfma_f32_16x16x32_bf16 v[22:25], v[142:145], v[184:187], v[22:25]
	v_mfma_f32_16x16x32_bf16 v[14:17], v[152:155], v[184:187], v[14:17]
	s_barrier
	s_add_i32 s7, s78, s55
	v_lshl_add_u64 v[138:139], v[132:133], 0, s[18:19]
	s_mov_b32 m0, s7
	v_lshl_add_u64 v[132:133], v[132:133], 0, s[14:15]
	global_load_lds_dwordx4 v[138:139], off
	s_add_i32 m0, s7, 0x2000
	s_nop 0
	global_load_lds_dwordx4 v[132:133], off
	s_waitcnt vmcnt(6)
	s_add_i32 s6, s6, 2
	s_add_u32 s8, s8, 0x100
	s_addc_u32 s9, s9, 0
	s_add_u32 s48, s48, 0x100
	s_addc_u32 s49, s49, 0
	s_cmpk_gt_u32 s6, 0x55
	s_cbranch_scc0 .LBB0_679
	s_barrier
	v_mfma_f32_16x16x32_bf16 v[50:53], v[188:191], v[156:159], v[50:53]
	v_mfma_f32_16x16x32_bf16 v[42:45], v[196:199], v[156:159], v[42:45]
	v_mfma_f32_16x16x32_bf16 v[34:37], v[188:191], v[164:167], v[34:37]
	v_mfma_f32_16x16x32_bf16 v[26:29], v[196:199], v[164:167], v[26:29]
	v_mfma_f32_16x16x32_bf16 v[18:21], v[188:191], v[172:175], v[18:21]
	v_mfma_f32_16x16x32_bf16 v[10:13], v[196:199], v[172:175], v[10:13]
	v_mfma_f32_16x16x32_bf16 v[6:9], v[188:191], v[180:183], v[6:9]
	v_mfma_f32_16x16x32_bf16 v[2:5], v[196:199], v[180:183], v[2:5]
	v_mfma_f32_16x16x32_bf16 v[50:53], v[192:195], v[160:163], v[50:53]
	v_mfma_f32_16x16x32_bf16 v[42:45], v[200:203], v[160:163], v[42:45]
	v_mfma_f32_16x16x32_bf16 v[34:37], v[192:195], v[168:171], v[34:37]
	v_mfma_f32_16x16x32_bf16 v[26:29], v[200:203], v[168:171], v[26:29]
	v_mfma_f32_16x16x32_bf16 v[18:21], v[192:195], v[176:179], v[18:21]
	v_mfma_f32_16x16x32_bf16 v[10:13], v[200:203], v[176:179], v[10:13]
	v_mfma_f32_16x16x32_bf16 v[6:9], v[192:195], v[184:187], v[6:9]
	v_mfma_f32_16x16x32_bf16 v[2:5], v[200:203], v[184:187], v[2:5]
	s_barrier
	v_mov_b32_e32 v137, v134
	s_lshl_b32 s6, s88, 8
	v_ashrrev_i32_e32 v132, 2, v137
	s_or_b32 s6, s6, s63
	v_and_b32_e32 v132, -4, v132
	v_add_u32_e32 v132, s6, v132
	s_lshl_b32 s6, s87, 8
	s_add_i32 s6, s6, s62
	v_and_or_b32 v188, v137, 15, s6
	v_ashrrev_i32_e32 v189, 31, v188
	v_ashrrev_i32_e32 v133, 31, v132
	v_lshlrev_b64 v[206:207], 13, v[188:189]
	v_or_b32_e32 v156, 16, v188
	v_or_b32_e32 v172, 32, v188
	v_or_b32_e32 v188, 48, v188
	v_lshlrev_b64 v[132:133], 2, v[132:133]
	v_ashrrev_i32_e32 v157, 31, v156
	v_ashrrev_i32_e32 v173, 31, v172
	v_ashrrev_i32_e32 v189, 31, v188
	v_lshl_add_u64 v[204:205], s[40:41], 0, v[132:133]
	v_lshlrev_b64 v[208:209], 13, v[156:157]
	v_lshlrev_b64 v[210:211], 13, v[172:173]
	v_lshlrev_b64 v[212:213], 13, v[188:189]
	v_lshl_add_u64 v[152:153], v[204:205], 0, v[206:207]
	v_lshl_add_u64 v[168:169], v[204:205], 0, v[208:209]
	v_lshl_add_u64 v[184:185], v[204:205], 0, v[210:211]
	v_lshl_add_u64 v[200:201], v[204:205], 0, v[212:213]
	global_load_dwordx4 v[138:141], v[152:153], off
	global_load_dwordx4 v[142:145], v[152:153], off offset:64
	global_load_dwordx4 v[148:151], v[152:153], off offset:512
	s_nop 0
	global_load_dwordx4 v[152:155], v[152:153], off offset:576
	s_nop 0
	global_load_dwordx4 v[156:159], v[168:169], off
	global_load_dwordx4 v[160:163], v[168:169], off offset:64
	global_load_dwordx4 v[164:167], v[168:169], off offset:512
	s_nop 0
	global_load_dwordx4 v[168:171], v[168:169], off offset:576
	s_nop 0
	global_load_dwordx4 v[172:175], v[184:185], off
	global_load_dwordx4 v[176:179], v[184:185], off offset:64
	global_load_dwordx4 v[180:183], v[184:185], off offset:512
	s_nop 0
	global_load_dwordx4 v[184:187], v[184:185], off offset:576
	s_nop 0
	global_load_dwordx4 v[188:191], v[200:201], off
	global_load_dwordx4 v[192:195], v[200:201], off offset:64
	global_load_dwordx4 v[196:199], v[200:201], off offset:512
	s_nop 0
	global_load_dwordx4 v[200:203], v[200:201], off offset:576
	s_waitcnt vmcnt(0)
	v_pk_fma_f32 v[126:127], v[126:127], 0.5, v[138:139] op_sel_hi:[1,0,1]
	v_lshl_add_u64 v[138:139], s[4:5], 0, v[206:207]
	v_lshl_add_u64 v[138:139], v[138:139], 0, v[132:133]
	v_pk_fma_f32 v[116:117], v[116:117], 0.5, v[150:151] op_sel_hi:[1,0,1]
	v_pk_fma_f32 v[114:115], v[114:115], 0.5, v[148:149] op_sel_hi:[1,0,1]
	global_store_dwordx4 v[138:139], v[114:117], off offset:512
	v_pk_fma_f32 v[100:101], v[100:101], 0.5, v[166:167] op_sel_hi:[1,0,1]
	v_pk_fma_f32 v[98:99], v[98:99], 0.5, v[164:165] op_sel_hi:[1,0,1]
	v_lshl_add_u64 v[114:115], s[4:5], 0, v[208:209]
	v_lshl_add_u64 v[114:115], v[114:115], 0, v[132:133]
	global_store_dwordx4 v[114:115], v[98:101], off offset:512
	v_pk_fma_f32 v[84:85], v[84:85], 0.5, v[182:183] op_sel_hi:[1,0,1]
	v_pk_fma_f32 v[82:83], v[82:83], 0.5, v[180:181] op_sel_hi:[1,0,1]
	v_lshl_add_u64 v[98:99], s[4:5], 0, v[210:211]
	v_lshl_add_u64 v[98:99], v[98:99], 0, v[132:133]
	v_pk_fma_f32 v[108:109], v[108:109], 0.5, v[154:155] op_sel_hi:[1,0,1]
	v_pk_fma_f32 v[106:107], v[106:107], 0.5, v[152:153] op_sel_hi:[1,0,1]
	v_pk_fma_f32 v[92:93], v[92:93], 0.5, v[170:171] op_sel_hi:[1,0,1]
	v_pk_fma_f32 v[90:91], v[90:91], 0.5, v[168:169] op_sel_hi:[1,0,1]
	global_store_dwordx4 v[98:99], v[82:85], off offset:512
	v_pk_fma_f32 v[76:77], v[76:77], 0.5, v[186:187] op_sel_hi:[1,0,1]
	v_pk_fma_f32 v[74:75], v[74:75], 0.5, v[184:185] op_sel_hi:[1,0,1]
	v_lshl_add_u64 v[82:83], s[4:5], 0, v[212:213]
	global_store_dwordx4 v[138:139], v[106:109], off offset:576
	global_store_dwordx4 v[114:115], v[90:93], off offset:576
	global_store_dwordx4 v[98:99], v[74:77], off offset:576
	v_pk_fma_f32 v[108:109], v[120:121], 0.5, v[158:159] op_sel_hi:[1,0,1]
	v_pk_fma_f32 v[106:107], v[118:119], 0.5, v[156:157] op_sel_hi:[1,0,1]
	v_pk_fma_f32 v[92:93], v[104:105], 0.5, v[174:175] op_sel_hi:[1,0,1]
	v_pk_fma_f32 v[90:91], v[102:103], 0.5, v[172:173] op_sel_hi:[1,0,1]
	v_pk_fma_f32 v[76:77], v[88:89], 0.5, v[190:191] op_sel_hi:[1,0,1]
	v_pk_fma_f32 v[74:75], v[86:87], 0.5, v[188:189] op_sel_hi:[1,0,1]
	v_lshl_add_u64 v[82:83], v[82:83], 0, v[132:133]
	v_pk_fma_f32 v[128:129], v[128:129], 0.5, v[140:141] op_sel_hi:[1,0,1]
	v_pk_fma_f32 v[124:125], v[124:125], 0.5, v[144:145] op_sel_hi:[1,0,1]
	v_pk_fma_f32 v[122:123], v[122:123], 0.5, v[142:143] op_sel_hi:[1,0,1]
	global_store_dwordx4 v[114:115], v[106:109], off
	global_store_dwordx4 v[98:99], v[90:93], off
	global_store_dwordx4 v[82:83], v[74:77], off
	v_pk_fma_f32 v[108:109], v[112:113], 0.5, v[162:163] op_sel_hi:[1,0,1]
	v_pk_fma_f32 v[106:107], v[110:111], 0.5, v[160:161] op_sel_hi:[1,0,1]
	v_pk_fma_f32 v[92:93], v[96:97], 0.5, v[178:179] op_sel_hi:[1,0,1]
	v_pk_fma_f32 v[90:91], v[94:95], 0.5, v[176:177] op_sel_hi:[1,0,1]
	v_pk_fma_f32 v[76:77], v[80:81], 0.5, v[194:195] op_sel_hi:[1,0,1]
	v_pk_fma_f32 v[74:75], v[78:79], 0.5, v[192:193] op_sel_hi:[1,0,1]
	v_pk_fma_f32 v[72:73], v[72:73], 0.5, v[198:199] op_sel_hi:[1,0,1]
	v_pk_fma_f32 v[70:71], v[70:71], 0.5, v[196:197] op_sel_hi:[1,0,1]
	v_pk_fma_f32 v[68:69], v[68:69], 0.5, v[202:203] op_sel_hi:[1,0,1]
	v_pk_fma_f32 v[66:67], v[66:67], 0.5, v[200:201] op_sel_hi:[1,0,1]
	global_store_dwordx4 v[138:139], v[126:129], off
	global_store_dwordx4 v[138:139], v[122:125], off offset:64
	global_store_dwordx4 v[114:115], v[106:109], off offset:64
	global_store_dwordx4 v[98:99], v[90:93], off offset:64
	global_store_dwordx4 v[82:83], v[74:77], off offset:64
	global_store_dwordx4 v[82:83], v[70:73], off offset:512
	global_store_dwordx4 v[82:83], v[66:69], off offset:576
	s_mov_b64 s[6:7], 0x120000
	v_lshl_add_u64 v[140:141], v[206:207], 0, s[6:7]
	s_mov_b64 s[6:7], 0x140000
	v_lshl_add_u64 v[138:139], v[206:207], 0, s[0:1]
	v_lshl_add_u64 v[142:143], v[206:207], 0, s[6:7]
	v_lshl_add_u64 v[144:145], v[206:207], 0, s[28:29]
	v_lshl_add_u64 v[78:79], v[204:205], 0, v[138:139]
	v_lshl_add_u64 v[94:95], v[204:205], 0, v[140:141]
	v_lshl_add_u64 v[110:111], v[204:205], 0, v[142:143]
	v_lshl_add_u64 v[126:127], v[204:205], 0, v[144:145]
	global_load_dwordx4 v[66:69], v[78:79], off
	global_load_dwordx4 v[70:73], v[78:79], off offset:64
	global_load_dwordx4 v[74:77], v[78:79], off offset:512
	s_nop 0
	global_load_dwordx4 v[78:81], v[78:79], off offset:576
	s_nop 0
	global_load_dwordx4 v[82:85], v[94:95], off
	global_load_dwordx4 v[86:89], v[94:95], off offset:64
	global_load_dwordx4 v[90:93], v[94:95], off offset:512
	s_nop 0
	global_load_dwordx4 v[94:97], v[94:95], off offset:576
	s_nop 0
	global_load_dwordx4 v[98:101], v[110:111], off
	global_load_dwordx4 v[102:105], v[110:111], off offset:64
	global_load_dwordx4 v[106:109], v[110:111], off offset:512
	s_nop 0
	global_load_dwordx4 v[110:113], v[110:111], off offset:576
	s_nop 0
	global_load_dwordx4 v[114:117], v[126:127], off
	global_load_dwordx4 v[118:121], v[126:127], off offset:64
	global_load_dwordx4 v[122:125], v[126:127], off offset:512
	s_nop 0
	global_load_dwordx4 v[126:129], v[126:127], off offset:576
	s_waitcnt vmcnt(0)
	v_pk_fma_f32 v[62:63], v[62:63], 0.5, v[66:67] op_sel_hi:[1,0,1]
	v_lshl_add_u64 v[66:67], s[4:5], 0, v[138:139]
	v_lshl_add_u64 v[66:67], v[66:67], 0, v[132:133]
	v_pk_fma_f32 v[52:53], v[52:53], 0.5, v[76:77] op_sel_hi:[1,0,1]
	v_pk_fma_f32 v[50:51], v[50:51], 0.5, v[74:75] op_sel_hi:[1,0,1]
	global_store_dwordx4 v[66:67], v[50:53], off offset:512
	v_pk_fma_f32 v[36:37], v[36:37], 0.5, v[92:93] op_sel_hi:[1,0,1]
	v_pk_fma_f32 v[34:35], v[34:35], 0.5, v[90:91] op_sel_hi:[1,0,1]
	v_lshl_add_u64 v[50:51], s[4:5], 0, v[140:141]
	v_lshl_add_u64 v[50:51], v[50:51], 0, v[132:133]
	global_store_dwordx4 v[50:51], v[34:37], off offset:512
	v_pk_fma_f32 v[20:21], v[20:21], 0.5, v[108:109] op_sel_hi:[1,0,1]
	v_pk_fma_f32 v[18:19], v[18:19], 0.5, v[106:107] op_sel_hi:[1,0,1]
	v_lshl_add_u64 v[34:35], s[4:5], 0, v[142:143]
	v_lshl_add_u64 v[34:35], v[34:35], 0, v[132:133]
	v_pk_fma_f32 v[44:45], v[44:45], 0.5, v[80:81] op_sel_hi:[1,0,1]
	v_pk_fma_f32 v[42:43], v[42:43], 0.5, v[78:79] op_sel_hi:[1,0,1]
	v_pk_fma_f32 v[28:29], v[28:29], 0.5, v[96:97] op_sel_hi:[1,0,1]
	v_pk_fma_f32 v[26:27], v[26:27], 0.5, v[94:95] op_sel_hi:[1,0,1]
	global_store_dwordx4 v[34:35], v[18:21], off offset:512
	v_pk_fma_f32 v[12:13], v[12:13], 0.5, v[112:113] op_sel_hi:[1,0,1]
	v_pk_fma_f32 v[10:11], v[10:11], 0.5, v[110:111] op_sel_hi:[1,0,1]
	v_lshl_add_u64 v[18:19], s[4:5], 0, v[144:145]
	global_store_dwordx4 v[66:67], v[42:45], off offset:576
	global_store_dwordx4 v[50:51], v[26:29], off offset:576
	global_store_dwordx4 v[34:35], v[10:13], off offset:576
	v_pk_fma_f32 v[44:45], v[56:57], 0.5, v[84:85] op_sel_hi:[1,0,1]
	v_pk_fma_f32 v[42:43], v[54:55], 0.5, v[82:83] op_sel_hi:[1,0,1]
	v_pk_fma_f32 v[28:29], v[40:41], 0.5, v[100:101] op_sel_hi:[1,0,1]
	v_pk_fma_f32 v[26:27], v[38:39], 0.5, v[98:99] op_sel_hi:[1,0,1]
	v_pk_fma_f32 v[12:13], v[24:25], 0.5, v[116:117] op_sel_hi:[1,0,1]
	v_pk_fma_f32 v[10:11], v[22:23], 0.5, v[114:115] op_sel_hi:[1,0,1]
	v_lshl_add_u64 v[18:19], v[18:19], 0, v[132:133]
	v_pk_fma_f32 v[64:65], v[64:65], 0.5, v[68:69] op_sel_hi:[1,0,1]
	v_pk_fma_f32 v[60:61], v[60:61], 0.5, v[72:73] op_sel_hi:[1,0,1]
	v_pk_fma_f32 v[58:59], v[58:59], 0.5, v[70:71] op_sel_hi:[1,0,1]
	global_store_dwordx4 v[50:51], v[42:45], off
	global_store_dwordx4 v[34:35], v[26:29], off
	global_store_dwordx4 v[18:19], v[10:13], off
	v_pk_fma_f32 v[44:45], v[48:49], 0.5, v[88:89] op_sel_hi:[1,0,1]
	v_pk_fma_f32 v[42:43], v[46:47], 0.5, v[86:87] op_sel_hi:[1,0,1]
	v_pk_fma_f32 v[28:29], v[32:33], 0.5, v[104:105] op_sel_hi:[1,0,1]
	v_pk_fma_f32 v[26:27], v[30:31], 0.5, v[102:103] op_sel_hi:[1,0,1]
	v_pk_fma_f32 v[12:13], v[16:17], 0.5, v[120:121] op_sel_hi:[1,0,1]
	v_pk_fma_f32 v[10:11], v[14:15], 0.5, v[118:119] op_sel_hi:[1,0,1]
	v_pk_fma_f32 v[8:9], v[8:9], 0.5, v[124:125] op_sel_hi:[1,0,1]
	v_pk_fma_f32 v[6:7], v[6:7], 0.5, v[122:123] op_sel_hi:[1,0,1]
	v_pk_fma_f32 v[4:5], v[4:5], 0.5, v[128:129] op_sel_hi:[1,0,1]
	v_pk_fma_f32 v[2:3], v[2:3], 0.5, v[126:127] op_sel_hi:[1,0,1]
	global_store_dwordx4 v[66:67], v[62:65], off
	global_store_dwordx4 v[66:67], v[58:61], off offset:64
	global_store_dwordx4 v[50:51], v[42:45], off offset:64
	global_store_dwordx4 v[34:35], v[26:29], off offset:64
	global_store_dwordx4 v[18:19], v[10:13], off offset:64
	global_store_dwordx4 v[18:19], v[6:9], off offset:512
	global_store_dwordx4 v[18:19], v[2:5], off offset:576
	s_and_b64 vcc, exec, s[42:43]
	s_mov_b32 s87, s10
	s_mov_b32 s88, s11
	s_mov_b64 s[8:9], s[46:47]
	s_mov_b64 s[6:7], s[44:45]
	s_movk_i32 s92, 0x4000
	s_movk_i32 s93, 0xf800
	s_movk_i32 s91, 0x60
	s_mov_b32 s78, 0x2a000000
	s_mov_b32 s79, 0x3fffe
	s_mov_b32 s90, 0xc0000
	s_cbranch_vccz .LBB0_672
	s_waitcnt vmcnt(0)
	s_cmpk_gt_u32 s50, 0xff
	s_cbranch_scc1 .LBB0_683
	s_barrier

.Lrot_enter_0:
	s_add_u32 s8, s6, 0x100
	s_addc_u32 s9, s7, 0
	s_add_i32 s78, 0, 0x10000
	v_add_u32_e32 v134, s78, v137
	ds_read_b128 v[140:143], v134
	ds_read_b128 v[148:151], v134 offset:1024
	ds_read_b128 v[152:155], v134 offset:2048
	ds_read_b128 v[156:159], v134 offset:3072
	s_cmp_eq_u32 s87, 28
	s_cselect_b32 s89, s45, s9
	s_cselect_b32 s88, s44, s8
	s_cselect_b32 s91, s47, s86
	s_cselect_b32 s90, s46, s41
	v_lshl_add_u64 v[134:135], s[6:7], 0, v[132:133]
	v_lshl_add_u64 v[144:145], v[134:135], 0, s[16:17]
	s_add_i32 m0, s49, 0xc000
	ds_read_b128 v[160:163], v138
	ds_read_b128 v[164:167], v138 offset:1024
	ds_read_b128 v[168:171], v138 offset:2048
	ds_read_b128 v[172:175], v138 offset:3072
	ds_read_b128 v[176:179], v138 offset:4096
	ds_read_b128 v[180:183], v138 offset:5120
	ds_read_b128 v[184:187], v138 offset:6144
	ds_read_b128 v[188:191], v138 offset:7168
	global_load_lds_dwordx4 v[144:145], off
	v_lshl_add_u64 v[134:135], v[134:135], 0, s[80:81]
	s_add_i32 m0, s49, 0xe000
	s_nop 0
	global_load_lds_dwordx4 v[134:135], off
	s_waitcnt lgkmcnt(8)
	s_barrier
	s_waitcnt lgkmcnt(0)
	v_mfma_f32_16x16x32_bf16 v[126:129], v[140:143], v[160:163], v[126:129]
	v_mfma_f32_16x16x32_bf16 v[122:125], v[152:155], v[160:163], v[122:125]
	v_mfma_f32_16x16x32_bf16 v[110:113], v[140:143], v[168:171], v[110:113]
	v_mfma_f32_16x16x32_bf16 v[106:109], v[152:155], v[168:171], v[106:109]
	v_mfma_f32_16x16x32_bf16 v[94:97], v[140:143], v[176:179], v[94:97]
	v_mfma_f32_16x16x32_bf16 v[90:93], v[152:155], v[176:179], v[90:93]
	v_mfma_f32_16x16x32_bf16 v[78:81], v[140:143], v[184:187], v[78:81]
	v_mfma_f32_16x16x32_bf16 v[74:77], v[152:155], v[184:187], v[74:77]
	v_mfma_f32_16x16x32_bf16 v[126:129], v[148:151], v[164:167], v[126:129]
	v_mfma_f32_16x16x32_bf16 v[122:125], v[156:159], v[164:167], v[122:125]
	v_mfma_f32_16x16x32_bf16 v[110:113], v[148:151], v[172:175], v[110:113]
	v_mfma_f32_16x16x32_bf16 v[106:109], v[156:159], v[172:175], v[106:109]
	v_mfma_f32_16x16x32_bf16 v[94:97], v[148:151], v[180:183], v[94:97]
	v_mfma_f32_16x16x32_bf16 v[90:93], v[156:159], v[180:183], v[90:93]
	v_mfma_f32_16x16x32_bf16 v[78:81], v[148:151], v[188:191], v[78:81]
	v_mfma_f32_16x16x32_bf16 v[74:77], v[156:159], v[188:191], v[74:77]
	s_barrier
	s_add_i32 s6, 0, 0x14000
	v_add_u32_e32 v134, s6, v137
	s_add_i32 s7, s78, s54
	ds_read_b128 v[192:195], v134
	ds_read_b128 v[196:199], v134 offset:1024
	ds_read_b128 v[200:203], v134 offset:2048
	ds_read_b128 v[204:207], v134 offset:3072
	v_lshl_add_u64 v[134:135], s[90:91], 0, v[0:1]
	s_mov_b32 m0, s7
	v_lshl_add_u64 v[144:145], v[134:135], 0, s[60:61]
	global_load_lds_dwordx4 v[134:135], off
	s_add_i32 m0, s7, 0x2000
	s_nop 0
	global_load_lds_dwordx4 v[144:145], off
	s_barrier
	s_waitcnt lgkmcnt(0)
	v_mfma_f32_16x16x32_bf16 v[118:121], v[192:195], v[160:163], v[118:121]
	v_mfma_f32_16x16x32_bf16 v[114:117], v[200:203], v[160:163], v[114:117]
	v_mfma_f32_16x16x32_bf16 v[102:105], v[192:195], v[168:171], v[102:105]
	v_mfma_f32_16x16x32_bf16 v[98:101], v[200:203], v[168:171], v[98:101]
	v_mfma_f32_16x16x32_bf16 v[86:89], v[192:195], v[176:179], v[86:89]
	v_mfma_f32_16x16x32_bf16 v[82:85], v[200:203], v[176:179], v[82:85]
	v_mfma_f32_16x16x32_bf16 v[70:73], v[192:195], v[184:187], v[70:73]
	v_mfma_f32_16x16x32_bf16 v[66:69], v[200:203], v[184:187], v[66:69]
	v_mfma_f32_16x16x32_bf16 v[118:121], v[196:199], v[164:167], v[118:121]
	ds_read_b128 v[160:163], v138 offset:16384
	v_mfma_f32_16x16x32_bf16 v[114:117], v[204:207], v[164:167], v[114:117]
	v_mfma_f32_16x16x32_bf16 v[102:105], v[196:199], v[172:175], v[102:105]
	ds_read_b128 v[168:171], v138 offset:18432
	v_mfma_f32_16x16x32_bf16 v[98:101], v[204:207], v[172:175], v[98:101]
	v_mfma_f32_16x16x32_bf16 v[86:89], v[196:199], v[180:183], v[86:89]
	ds_read_b128 v[176:179], v138 offset:20480
	v_mfma_f32_16x16x32_bf16 v[82:85], v[204:207], v[180:183], v[82:85]
	v_mfma_f32_16x16x32_bf16 v[70:73], v[196:199], v[188:191], v[70:73]
	ds_read_b128 v[184:187], v138 offset:22528
	v_mfma_f32_16x16x32_bf16 v[66:69], v[204:207], v[188:191], v[66:69]
	s_barrier
	s_mov_b32 m0, s49
	v_lshl_add_u64 v[144:145], s[88:89], 0, v[130:131]
	ds_read_b128 v[164:167], v138 offset:17408
	ds_read_b128 v[172:175], v138 offset:19456
	ds_read_b128 v[180:183], v138 offset:21504
	ds_read_b128 v[188:191], v138 offset:23552
	global_load_lds_dwordx4 v[144:145], off
	v_lshl_add_u64 v[208:209], v[144:145], 0, s[60:61]
	s_mov_b32 m0, s55
	s_nop 0
	global_load_lds_dwordx4 v[208:209], off
	s_barrier
	s_waitcnt lgkmcnt(0)
	v_mfma_f32_16x16x32_bf16 v[62:65], v[140:143], v[160:163], v[62:65]
	v_mfma_f32_16x16x32_bf16 v[58:61], v[152:155], v[160:163], v[58:61]
	v_mfma_f32_16x16x32_bf16 v[46:49], v[140:143], v[168:171], v[46:49]
	v_mfma_f32_16x16x32_bf16 v[42:45], v[152:155], v[168:171], v[42:45]
	v_mfma_f32_16x16x32_bf16 v[30:33], v[140:143], v[176:179], v[30:33]
	v_mfma_f32_16x16x32_bf16 v[26:29], v[152:155], v[176:179], v[26:29]
	v_mfma_f32_16x16x32_bf16 v[14:17], v[140:143], v[184:187], v[14:17]
	v_mfma_f32_16x16x32_bf16 v[10:13], v[152:155], v[184:187], v[10:13]
	v_mfma_f32_16x16x32_bf16 v[62:65], v[148:151], v[164:167], v[62:65]
	v_mfma_f32_16x16x32_bf16 v[58:61], v[156:159], v[164:167], v[58:61]
	v_mfma_f32_16x16x32_bf16 v[46:49], v[148:151], v[172:175], v[46:49]
	v_mfma_f32_16x16x32_bf16 v[42:45], v[156:159], v[172:175], v[42:45]
	v_mfma_f32_16x16x32_bf16 v[30:33], v[148:151], v[180:183], v[30:33]
	v_mfma_f32_16x16x32_bf16 v[26:29], v[156:159], v[180:183], v[26:29]
	v_mfma_f32_16x16x32_bf16 v[14:17], v[148:151], v[188:191], v[14:17]
	v_mfma_f32_16x16x32_bf16 v[10:13], v[156:159], v[188:191], v[10:13]
	s_barrier
	s_add_i32 s6, s6, s54
	v_lshl_add_u64 v[140:141], v[134:135], 0, s[20:21]
	s_mov_b32 m0, s6
	s_nop 0
	global_load_lds_dwordx4 v[140:141], off
	v_lshl_add_u64 v[140:141], v[134:135], 0, s[64:65]
	s_add_i32 m0, s6, 0x2000
	s_nop 0
	global_load_lds_dwordx4 v[140:141], off
	v_lshl_add_u64 v[230:231], v[144:145], 0, s[20:21]
	s_mov_b32 m0, s56
	s_nop 0
	global_load_lds_dwordx4 v[230:231], off
	v_lshl_add_u64 v[230:231], v[144:145], 0, s[64:65]
	s_mov_b32 m0, s57
	s_nop 0
	global_load_lds_dwordx4 v[230:231], off
	s_waitcnt vmcnt(8)
	s_barrier
	v_mfma_f32_16x16x32_bf16 v[54:57], v[192:195], v[160:163], v[54:57]
	v_mfma_f32_16x16x32_bf16 v[50:53], v[200:203], v[160:163], v[50:53]
	v_mfma_f32_16x16x32_bf16 v[38:41], v[192:195], v[168:171], v[38:41]
	v_mfma_f32_16x16x32_bf16 v[34:37], v[200:203], v[168:171], v[34:37]
	v_mfma_f32_16x16x32_bf16 v[22:25], v[192:195], v[176:179], v[22:25]
	v_mfma_f32_16x16x32_bf16 v[18:21], v[200:203], v[176:179], v[18:21]
	v_mfma_f32_16x16x32_bf16 v[6:9], v[192:195], v[184:187], v[6:9]
	v_mfma_f32_16x16x32_bf16 v[2:5], v[200:203], v[184:187], v[2:5]
	v_mfma_f32_16x16x32_bf16 v[54:57], v[196:199], v[164:167], v[54:57]
	v_mfma_f32_16x16x32_bf16 v[50:53], v[204:207], v[164:167], v[50:53]
	v_mfma_f32_16x16x32_bf16 v[38:41], v[196:199], v[172:175], v[38:41]
	v_mfma_f32_16x16x32_bf16 v[34:37], v[204:207], v[172:175], v[34:37]
	v_mfma_f32_16x16x32_bf16 v[22:25], v[196:199], v[180:183], v[22:25]
	v_mfma_f32_16x16x32_bf16 v[18:21], v[204:207], v[180:183], v[18:21]
	v_mfma_f32_16x16x32_bf16 v[6:9], v[196:199], v[188:191], v[6:9]
	v_mfma_f32_16x16x32_bf16 v[2:5], v[204:207], v[188:191], v[2:5]
	s_barrier
	s_add_i32 s6, 0, 0x18000
	v_add_u32_e32 v139, s6, v137
	ds_read_b128 v[140:143], v139
	ds_read_b128 v[148:151], v139 offset:1024
	ds_read_b128 v[152:155], v139 offset:2048
	ds_read_b128 v[156:159], v139 offset:3072
	ds_read_b128 v[160:163], v138 offset:32768
	ds_read_b128 v[164:167], v138 offset:33792
	ds_read_b128 v[168:171], v138 offset:34816
	ds_read_b128 v[172:175], v138 offset:35840
	ds_read_b128 v[176:179], v138 offset:36864
	ds_read_b128 v[180:183], v138 offset:37888
	ds_read_b128 v[184:187], v138 offset:38912
	ds_read_b128 v[188:191], v138 offset:39936
	s_waitcnt lgkmcnt(8)
	s_barrier
	s_waitcnt lgkmcnt(0)
	v_mfma_f32_16x16x32_bf16 v[126:129], v[140:143], v[160:163], v[126:129]
	v_mfma_f32_16x16x32_bf16 v[122:125], v[152:155], v[160:163], v[122:125]
	v_mfma_f32_16x16x32_bf16 v[110:113], v[140:143], v[168:171], v[110:113]
	v_mfma_f32_16x16x32_bf16 v[106:109], v[152:155], v[168:171], v[106:109]
	v_mfma_f32_16x16x32_bf16 v[94:97], v[140:143], v[176:179], v[94:97]
	v_mfma_f32_16x16x32_bf16 v[90:93], v[152:155], v[176:179], v[90:93]
	v_mfma_f32_16x16x32_bf16 v[78:81], v[140:143], v[184:187], v[78:81]
	v_mfma_f32_16x16x32_bf16 v[74:77], v[152:155], v[184:187], v[74:77]
	v_mfma_f32_16x16x32_bf16 v[126:129], v[148:151], v[164:167], v[126:129]
	v_mfma_f32_16x16x32_bf16 v[122:125], v[156:159], v[164:167], v[122:125]
	v_mfma_f32_16x16x32_bf16 v[110:113], v[148:151], v[172:175], v[110:113]
	v_mfma_f32_16x16x32_bf16 v[106:109], v[156:159], v[172:175], v[106:109]
	v_mfma_f32_16x16x32_bf16 v[94:97], v[148:151], v[180:183], v[94:97]
	v_mfma_f32_16x16x32_bf16 v[90:93], v[156:159], v[180:183], v[90:93]
	v_mfma_f32_16x16x32_bf16 v[78:81], v[148:151], v[188:191], v[78:81]
	v_mfma_f32_16x16x32_bf16 v[74:77], v[156:159], v[188:191], v[74:77]
	s_barrier
	s_add_i32 s7, 0, 0x1c000
	s_add_i32 s6, s6, s54
	v_add_u32_e32 v139, s7, v137
	v_lshl_add_u64 v[208:209], v[134:135], 0, s[34:35]
	s_mov_b32 m0, s6
	ds_read_b128 v[192:195], v139
	ds_read_b128 v[196:199], v139 offset:1024
	ds_read_b128 v[200:203], v139 offset:2048
	ds_read_b128 v[204:207], v139 offset:3072
	global_load_lds_dwordx4 v[208:209], off
	v_lshl_add_u64 v[208:209], v[134:135], 0, s[66:67]
	s_add_i32 m0, s6, 0x2000
	s_nop 0
	global_load_lds_dwordx4 v[208:209], off
	s_barrier
	s_waitcnt lgkmcnt(0)
	v_mfma_f32_16x16x32_bf16 v[118:121], v[192:195], v[160:163], v[118:121]
	v_mfma_f32_16x16x32_bf16 v[114:117], v[200:203], v[160:163], v[114:117]
	v_mfma_f32_16x16x32_bf16 v[102:105], v[192:195], v[168:171], v[102:105]
	v_mfma_f32_16x16x32_bf16 v[98:101], v[200:203], v[168:171], v[98:101]
	v_mfma_f32_16x16x32_bf16 v[86:89], v[192:195], v[176:179], v[86:89]
	v_mfma_f32_16x16x32_bf16 v[82:85], v[200:203], v[176:179], v[82:85]
	v_mfma_f32_16x16x32_bf16 v[70:73], v[192:195], v[184:187], v[70:73]
	v_mfma_f32_16x16x32_bf16 v[66:69], v[200:203], v[184:187], v[66:69]
	v_mfma_f32_16x16x32_bf16 v[118:121], v[196:199], v[164:167], v[118:121]
	ds_read_b128 v[160:163], v138 offset:49152
	v_mfma_f32_16x16x32_bf16 v[114:117], v[204:207], v[164:167], v[114:117]
	v_mfma_f32_16x16x32_bf16 v[102:105], v[196:199], v[172:175], v[102:105]
	ds_read_b128 v[168:171], v138 offset:51200
	v_mfma_f32_16x16x32_bf16 v[98:101], v[204:207], v[172:175], v[98:101]
	v_mfma_f32_16x16x32_bf16 v[86:89], v[196:199], v[180:183], v[86:89]
	ds_read_b128 v[176:179], v138 offset:53248
	v_mfma_f32_16x16x32_bf16 v[82:85], v[204:207], v[180:183], v[82:85]
	v_mfma_f32_16x16x32_bf16 v[70:73], v[196:199], v[188:191], v[70:73]
	ds_read_b128 v[184:187], v138 offset:55296
	v_mfma_f32_16x16x32_bf16 v[66:69], v[204:207], v[188:191], v[66:69]
	s_barrier
	s_mov_b32 m0, s58
	v_lshl_add_u64 v[208:209], v[144:145], 0, s[34:35]
	ds_read_b128 v[164:167], v138 offset:50176
	ds_read_b128 v[172:175], v138 offset:52224
	ds_read_b128 v[180:183], v138 offset:54272
	ds_read_b128 v[188:191], v138 offset:56320
	global_load_lds_dwordx4 v[208:209], off
	v_lshl_add_u64 v[144:145], v[144:145], 0, s[66:67]
	s_mov_b32 m0, s59
	s_nop 0
	global_load_lds_dwordx4 v[144:145], off
	s_barrier
	s_waitcnt lgkmcnt(0)
	v_mfma_f32_16x16x32_bf16 v[62:65], v[140:143], v[160:163], v[62:65]
	v_mfma_f32_16x16x32_bf16 v[58:61], v[152:155], v[160:163], v[58:61]
	v_mfma_f32_16x16x32_bf16 v[46:49], v[140:143], v[168:171], v[46:49]
	v_mfma_f32_16x16x32_bf16 v[42:45], v[152:155], v[168:171], v[42:45]
	v_mfma_f32_16x16x32_bf16 v[30:33], v[140:143], v[176:179], v[30:33]
	v_mfma_f32_16x16x32_bf16 v[26:29], v[152:155], v[176:179], v[26:29]
	v_mfma_f32_16x16x32_bf16 v[14:17], v[140:143], v[184:187], v[14:17]
	v_mfma_f32_16x16x32_bf16 v[10:13], v[152:155], v[184:187], v[10:13]
	v_mfma_f32_16x16x32_bf16 v[62:65], v[148:151], v[164:167], v[62:65]
	v_mfma_f32_16x16x32_bf16 v[58:61], v[156:159], v[164:167], v[58:61]
	v_mfma_f32_16x16x32_bf16 v[46:49], v[148:151], v[172:175], v[46:49]
	v_mfma_f32_16x16x32_bf16 v[42:45], v[156:159], v[172:175], v[42:45]
	v_mfma_f32_16x16x32_bf16 v[30:33], v[148:151], v[180:183], v[30:33]
	v_mfma_f32_16x16x32_bf16 v[26:29], v[156:159], v[180:183], v[26:29]
	v_mfma_f32_16x16x32_bf16 v[14:17], v[148:151], v[188:191], v[14:17]
	v_mfma_f32_16x16x32_bf16 v[10:13], v[156:159], v[188:191], v[10:13]
	s_barrier
	s_add_i32 s6, s7, s54
	v_lshl_add_u64 v[140:141], v[134:135], 0, s[16:17]
	s_mov_b32 m0, s6
	v_lshl_add_u64 v[134:135], v[134:135], 0, s[80:81]
	global_load_lds_dwordx4 v[140:141], off
	s_add_i32 m0, s6, 0x2000
	s_nop 0
	global_load_lds_dwordx4 v[134:135], off
	s_waitcnt vmcnt(6)
	s_add_i32 s87, s87, 2
	s_add_u32 s41, s41, 0x100
	s_addc_u32 s86, s86, 0
	s_cmp_gt_u32 s87, 29
	s_mov_b64 s[6:7], s[8:9]
	s_cbranch_scc0 .LBB0_694
	s_barrier
	v_mfma_f32_16x16x32_bf16 v[54:57], v[192:195], v[160:163], v[54:57]
	v_mfma_f32_16x16x32_bf16 v[50:53], v[200:203], v[160:163], v[50:53]
	v_mfma_f32_16x16x32_bf16 v[38:41], v[192:195], v[168:171], v[38:41]
	v_mfma_f32_16x16x32_bf16 v[34:37], v[200:203], v[168:171], v[34:37]
	v_mfma_f32_16x16x32_bf16 v[22:25], v[192:195], v[176:179], v[22:25]
	v_mfma_f32_16x16x32_bf16 v[18:21], v[200:203], v[176:179], v[18:21]
	v_mfma_f32_16x16x32_bf16 v[6:9], v[192:195], v[184:187], v[6:9]
	v_mfma_f32_16x16x32_bf16 v[2:5], v[200:203], v[184:187], v[2:5]
	v_mfma_f32_16x16x32_bf16 v[54:57], v[196:199], v[164:167], v[54:57]
	v_mfma_f32_16x16x32_bf16 v[50:53], v[204:207], v[164:167], v[50:53]
	v_mfma_f32_16x16x32_bf16 v[38:41], v[196:199], v[172:175], v[38:41]
	v_mfma_f32_16x16x32_bf16 v[34:37], v[204:207], v[172:175], v[34:37]
	v_mfma_f32_16x16x32_bf16 v[22:25], v[196:199], v[180:183], v[22:25]
	v_mfma_f32_16x16x32_bf16 v[18:21], v[204:207], v[180:183], v[18:21]
	v_mfma_f32_16x16x32_bf16 v[6:9], v[196:199], v[188:191], v[6:9]
	v_mfma_f32_16x16x32_bf16 v[2:5], v[204:207], v[188:191], v[2:5]
	s_barrier
	v_mov_b32_e32 v134, v136
	s_lshl_b32 s6, s48, 8
	s_add_i32 s6, s6, s10
	v_and_or_b32 v139, v134, 15, s6
	s_lshl_b32 s6, s85, 7
	v_ashrrev_i32_e32 v134, 1, v134
	s_or_b32 s6, s6, s62
	v_and_b32_e32 v134, -8, v134
	v_add_u32_e32 v140, s6, v134
	v_mul_f32_e32 v134, 0xbfb8aa3b, v126
	v_exp_f32_e32 v142, v134
	v_mul_f32_e32 v134, 0xbfb8aa3b, v127
	v_exp_f32_e32 v143, v134
	v_ashrrev_i32_e32 v141, 31, v140
	v_add_f32_e32 v142, 1.0, v142
	v_rcp_f32_e32 v144, v142
	v_add_f32_e32 v142, 1.0, v143
	v_rcp_f32_e32 v145, v142
	v_mov_b64_e32 v[134:135], s[4:5]
	v_mul_f32_e32 v126, v126, v144
	v_mul_f32_e32 v118, v126, v118
	v_mul_f32_e32 v126, v127, v145
	v_mul_f32_e32 v127, 0xbfb8aa3b, v128
	v_exp_f32_e32 v127, v127
	v_mul_f32_e32 v144, 0xbfb8aa3b, v129
	v_exp_f32_e32 v144, v144
	v_mul_f32_e32 v119, v126, v119
	v_add_f32_e32 v126, 1.0, v127
	v_rcp_f32_e32 v126, v126
	v_add_f32_e32 v127, 1.0, v144
	v_mul_f32_e32 v144, 0xbfb8aa3b, v122
	v_rcp_f32_e32 v127, v127
	v_exp_f32_e32 v144, v144
	v_mul_f32_e32 v126, v128, v126
	v_mul_f32_e32 v126, v126, v120
	v_mul_f32_e32 v120, v129, v127
	v_add_f32_e32 v127, 1.0, v144
	v_rcp_f32_e32 v127, v127
	v_mul_f32_e32 v128, 0xbfb8aa3b, v123
	v_mul_f32_e32 v129, v120, v121
	v_exp_f32_e32 v128, v128
	v_mul_f32_e32 v120, v122, v127
	v_mul_f32_e32 v122, v120, v114
	v_mul_f32_e32 v120, 0xbfb8aa3b, v124
	v_exp_f32_e32 v120, v120
	v_mul_f32_e32 v121, 0xbfb8aa3b, v125
	v_exp_f32_e32 v121, v121
	v_add_f32_e32 v114, 1.0, v128
	v_rcp_f32_e32 v114, v114
	v_add_f32_e32 v120, 1.0, v120
	v_rcp_f32_e32 v120, v120
	v_add_f32_e32 v121, 1.0, v121
	v_rcp_f32_e32 v121, v121
	v_mul_f32_e32 v114, v123, v114
	v_mul_f32_e32 v123, v114, v115
	v_mul_f32_e32 v114, v124, v120
	v_mul_f32_e32 v124, v114, v116
	v_mul_f32_e32 v114, v125, v121
	v_mad_i64_i32 v[142:143], s[6:7], v139, s74, v[134:135]
	v_mul_f32_e32 v125, v114, v117
	v_lshlrev_b64 v[114:115], 1, v[140:141]
	v_lshl_add_u64 v[120:121], v[142:143], 0, v[114:115]
	v_cvt_pk_bf16_f32 v116, v118, v119
	v_cvt_pk_bf16_f32 v117, v126, v129
	v_cvt_pk_bf16_f32 v118, v122, v123
	v_cvt_pk_bf16_f32 v119, v124, v125
	global_store_dwordx4 v[120:121], v[116:119], off
	s_and_b64 vcc, exec, s[42:43]
	s_mov_b32 s48, s40
	v_mul_f32_e32 v116, 0xbfb8aa3b, v110
	v_exp_f32_e32 v116, v116
	v_mul_f32_e32 v117, 0xbfb8aa3b, v111
	v_exp_f32_e32 v117, v117
	v_or_b32_e32 v118, 16, v139
	v_add_f32_e32 v116, 1.0, v116
	v_rcp_f32_e32 v119, v116
	v_add_f32_e32 v116, 1.0, v117
	v_rcp_f32_e32 v120, v116
	v_mad_i64_i32 v[116:117], s[6:7], v118, s74, v[134:135]
	v_mul_f32_e32 v110, v110, v119
	v_mul_f32_e32 v110, v110, v102
	v_mul_f32_e32 v102, v111, v120
	v_mul_f32_e32 v111, 0xbfb8aa3b, v112
	v_exp_f32_e32 v111, v111
	v_mul_f32_e32 v118, 0xbfb8aa3b, v113
	v_exp_f32_e32 v118, v118
	v_mul_f32_e32 v119, v102, v103
	v_add_f32_e32 v102, 1.0, v111
	v_rcp_f32_e32 v102, v102
	v_add_f32_e32 v103, 1.0, v118
	v_mul_f32_e32 v111, 0xbfb8aa3b, v106
	v_rcp_f32_e32 v103, v103
	v_exp_f32_e32 v111, v111
	v_mul_f32_e32 v102, v112, v102
	v_mul_f32_e32 v104, v102, v104
	v_mul_f32_e32 v102, v113, v103
	v_add_f32_e32 v103, 1.0, v111
	v_rcp_f32_e32 v103, v103
	v_mul_f32_e32 v111, 0xbfb8aa3b, v107
	v_mul_f32_e32 v105, v102, v105
	v_exp_f32_e32 v111, v111
	v_mul_f32_e32 v102, v106, v103
	v_mul_f32_e32 v106, v102, v98
	v_mul_f32_e32 v102, 0xbfb8aa3b, v108
	v_exp_f32_e32 v102, v102
	v_mul_f32_e32 v103, 0xbfb8aa3b, v109
	v_exp_f32_e32 v103, v103
	v_add_f32_e32 v98, 1.0, v111
	v_rcp_f32_e32 v98, v98
	v_add_f32_e32 v102, 1.0, v102
	v_rcp_f32_e32 v102, v102
	v_add_f32_e32 v103, 1.0, v103
	v_rcp_f32_e32 v103, v103
	v_mul_f32_e32 v98, v107, v98
	v_mul_f32_e32 v107, v98, v99
	v_mul_f32_e32 v98, v108, v102
	v_mul_f32_e32 v108, v98, v100
	v_mul_f32_e32 v98, v109, v103
	v_mul_f32_e32 v101, v98, v101
	v_lshl_add_u64 v[102:103], v[116:117], 0, v[114:115]
	v_cvt_pk_bf16_f32 v98, v110, v119
	v_cvt_pk_bf16_f32 v99, v104, v105
	v_cvt_pk_bf16_f32 v100, v106, v107
	v_cvt_pk_bf16_f32 v101, v108, v101
	global_store_dwordx4 v[102:103], v[98:101], off
	s_mov_b32 s85, s84
	s_mov_b64 s[8:9], s[46:47]
	v_mul_f32_e32 v98, 0xbfb8aa3b, v94
	v_exp_f32_e32 v98, v98
	v_mul_f32_e32 v99, 0xbfb8aa3b, v95
	v_exp_f32_e32 v99, v99
	v_or_b32_e32 v100, 32, v139
	v_add_f32_e32 v98, 1.0, v98
	v_rcp_f32_e32 v101, v98
	v_add_f32_e32 v98, 1.0, v99
	v_rcp_f32_e32 v102, v98
	v_mad_i64_i32 v[98:99], s[6:7], v100, s74, v[134:135]
	v_mul_f32_e32 v94, v94, v101
	v_mul_f32_e32 v94, v94, v86
	v_mul_f32_e32 v86, v95, v102
	v_mul_f32_e32 v95, 0xbfb8aa3b, v96
	v_exp_f32_e32 v95, v95
	v_mul_f32_e32 v100, 0xbfb8aa3b, v97
	v_exp_f32_e32 v100, v100
	v_mul_f32_e32 v101, v86, v87
	v_add_f32_e32 v86, 1.0, v95
	v_rcp_f32_e32 v86, v86
	v_add_f32_e32 v87, 1.0, v100
	v_mul_f32_e32 v95, 0xbfb8aa3b, v90
	v_rcp_f32_e32 v87, v87
	v_exp_f32_e32 v95, v95
	v_mul_f32_e32 v86, v96, v86
	v_mul_f32_e32 v88, v86, v88
	v_mul_f32_e32 v86, v97, v87
	v_add_f32_e32 v87, 1.0, v95
	v_rcp_f32_e32 v87, v87
	v_mul_f32_e32 v95, 0xbfb8aa3b, v91
	v_mul_f32_e32 v89, v86, v89
	v_exp_f32_e32 v95, v95
	v_mul_f32_e32 v86, v90, v87
	v_mul_f32_e32 v90, v86, v82
	v_mul_f32_e32 v86, 0xbfb8aa3b, v92
	v_exp_f32_e32 v86, v86
	v_mul_f32_e32 v87, 0xbfb8aa3b, v93
	v_exp_f32_e32 v87, v87
	v_add_f32_e32 v82, 1.0, v95
	v_rcp_f32_e32 v82, v82
	v_add_f32_e32 v86, 1.0, v86
	v_rcp_f32_e32 v86, v86
	v_add_f32_e32 v87, 1.0, v87
	v_rcp_f32_e32 v87, v87
	v_mul_f32_e32 v82, v91, v82
	v_mul_f32_e32 v91, v82, v83
	v_mul_f32_e32 v82, v92, v86
	v_mul_f32_e32 v92, v82, v84
	v_mul_f32_e32 v82, v93, v87
	v_mul_f32_e32 v85, v82, v85
	v_lshl_add_u64 v[86:87], v[98:99], 0, v[114:115]
	v_cvt_pk_bf16_f32 v82, v94, v101
	v_cvt_pk_bf16_f32 v83, v88, v89
	v_cvt_pk_bf16_f32 v84, v90, v91
	v_cvt_pk_bf16_f32 v85, v92, v85
	global_store_dwordx4 v[86:87], v[82:85], off
	s_nop 1
	v_mul_f32_e32 v82, 0xbfb8aa3b, v78
	v_exp_f32_e32 v82, v82
	v_mul_f32_e32 v83, 0xbfb8aa3b, v79
	v_exp_f32_e32 v83, v83
	v_or_b32_e32 v84, 48, v139
	v_add_f32_e32 v82, 1.0, v82
	v_rcp_f32_e32 v85, v82
	v_add_f32_e32 v82, 1.0, v83
	v_rcp_f32_e32 v86, v82
	v_mad_i64_i32 v[82:83], s[6:7], v84, s74, v[134:135]
	v_mul_f32_e32 v78, v78, v85
	v_mul_f32_e32 v78, v78, v70
	v_mul_f32_e32 v70, v79, v86
	v_mul_f32_e32 v79, 0xbfb8aa3b, v80
	v_exp_f32_e32 v79, v79
	v_mul_f32_e32 v84, 0xbfb8aa3b, v81
	v_exp_f32_e32 v84, v84
	v_mul_f32_e32 v85, v70, v71
	v_add_f32_e32 v70, 1.0, v79
	v_rcp_f32_e32 v70, v70
	v_add_f32_e32 v71, 1.0, v84
	v_mul_f32_e32 v79, 0xbfb8aa3b, v74
	v_rcp_f32_e32 v71, v71
	v_exp_f32_e32 v79, v79
	v_mul_f32_e32 v70, v80, v70
	v_mul_f32_e32 v72, v70, v72
	v_mul_f32_e32 v70, v81, v71
	v_add_f32_e32 v71, 1.0, v79
	v_rcp_f32_e32 v71, v71
	v_mul_f32_e32 v79, 0xbfb8aa3b, v75
	v_mul_f32_e32 v73, v70, v73
	v_exp_f32_e32 v79, v79
	v_mul_f32_e32 v70, v74, v71
	v_mul_f32_e32 v74, v70, v66
	v_mul_f32_e32 v70, 0xbfb8aa3b, v76
	v_exp_f32_e32 v70, v70
	v_mul_f32_e32 v71, 0xbfb8aa3b, v77
	v_exp_f32_e32 v71, v71
	v_add_f32_e32 v66, 1.0, v79
	v_rcp_f32_e32 v66, v66
	v_add_f32_e32 v70, 1.0, v70
	v_rcp_f32_e32 v70, v70
	v_add_f32_e32 v71, 1.0, v71
	v_rcp_f32_e32 v71, v71
	v_mul_f32_e32 v66, v75, v66
	v_mul_f32_e32 v75, v66, v67
	v_mul_f32_e32 v66, v76, v70
	v_mul_f32_e32 v76, v66, v68
	v_mul_f32_e32 v66, v77, v71
	v_mul_f32_e32 v69, v66, v69
	v_lshl_add_u64 v[70:71], v[82:83], 0, v[114:115]
	v_cvt_pk_bf16_f32 v66, v78, v85
	v_cvt_pk_bf16_f32 v67, v72, v73
	v_cvt_pk_bf16_f32 v68, v74, v75
	v_cvt_pk_bf16_f32 v69, v76, v69
	global_store_dwordx4 v[70:71], v[66:69], off
	s_nop 1
	v_mul_f32_e32 v66, 0xbfb8aa3b, v62
	v_exp_f32_e32 v66, v66
	v_mul_f32_e32 v67, 0xbfb8aa3b, v63
	v_exp_f32_e32 v67, v67
	v_add_u32_e32 v68, 0x80, v139
	v_add_f32_e32 v66, 1.0, v66
	v_rcp_f32_e32 v69, v66
	v_add_f32_e32 v66, 1.0, v67
	v_rcp_f32_e32 v70, v66
	v_mad_i64_i32 v[66:67], s[6:7], v68, s74, v[134:135]
	v_mul_f32_e32 v62, v62, v69
	v_mul_f32_e32 v62, v62, v54
	v_mul_f32_e32 v54, v63, v70
	v_mul_f32_e32 v63, 0xbfb8aa3b, v64
	v_exp_f32_e32 v63, v63
	v_mul_f32_e32 v68, 0xbfb8aa3b, v65
	v_exp_f32_e32 v68, v68
	v_mul_f32_e32 v69, v54, v55
	v_add_f32_e32 v54, 1.0, v63
	v_rcp_f32_e32 v54, v54
	v_add_f32_e32 v55, 1.0, v68
	v_mul_f32_e32 v63, 0xbfb8aa3b, v58
	v_rcp_f32_e32 v55, v55
	v_exp_f32_e32 v63, v63
	v_mul_f32_e32 v54, v64, v54
	v_mul_f32_e32 v56, v54, v56
	v_mul_f32_e32 v54, v65, v55
	v_add_f32_e32 v55, 1.0, v63
	v_rcp_f32_e32 v55, v55
	v_mul_f32_e32 v63, 0xbfb8aa3b, v59
	v_mul_f32_e32 v57, v54, v57
	v_exp_f32_e32 v63, v63
	v_mul_f32_e32 v54, v58, v55
	v_mul_f32_e32 v58, v54, v50
	v_mul_f32_e32 v54, 0xbfb8aa3b, v60
	v_exp_f32_e32 v54, v54
	v_mul_f32_e32 v55, 0xbfb8aa3b, v61
	v_exp_f32_e32 v55, v55
	v_add_f32_e32 v50, 1.0, v63
	v_rcp_f32_e32 v50, v50
	v_add_f32_e32 v54, 1.0, v54
	v_rcp_f32_e32 v54, v54
	v_add_f32_e32 v55, 1.0, v55
	v_rcp_f32_e32 v55, v55
	v_mul_f32_e32 v50, v59, v50
	v_mul_f32_e32 v59, v50, v51
	v_mul_f32_e32 v50, v60, v54
	v_mul_f32_e32 v60, v50, v52
	v_mul_f32_e32 v50, v61, v55
	v_mul_f32_e32 v53, v50, v53
	v_lshl_add_u64 v[54:55], v[66:67], 0, v[114:115]
	v_cvt_pk_bf16_f32 v50, v62, v69
	v_cvt_pk_bf16_f32 v51, v56, v57
	v_cvt_pk_bf16_f32 v52, v58, v59
	v_cvt_pk_bf16_f32 v53, v60, v53
	global_store_dwordx4 v[54:55], v[50:53], off
	s_nop 1
	v_mul_f32_e32 v50, 0xbfb8aa3b, v46
	v_exp_f32_e32 v50, v50
	v_mul_f32_e32 v51, 0xbfb8aa3b, v47
	v_exp_f32_e32 v51, v51
	v_add_u32_e32 v52, 0x90, v139
	v_add_f32_e32 v50, 1.0, v50
	v_rcp_f32_e32 v53, v50
	v_add_f32_e32 v50, 1.0, v51
	v_rcp_f32_e32 v54, v50
	v_mad_i64_i32 v[50:51], s[6:7], v52, s74, v[134:135]
	v_mul_f32_e32 v46, v46, v53
	v_mul_f32_e32 v46, v46, v38
	v_mul_f32_e32 v38, v47, v54
	v_mul_f32_e32 v47, 0xbfb8aa3b, v48
	v_exp_f32_e32 v47, v47
	v_mul_f32_e32 v52, 0xbfb8aa3b, v49
	v_exp_f32_e32 v52, v52
	v_mul_f32_e32 v53, v38, v39
	v_add_f32_e32 v38, 1.0, v47
	v_rcp_f32_e32 v38, v38
	v_add_f32_e32 v39, 1.0, v52
	v_mul_f32_e32 v47, 0xbfb8aa3b, v42
	v_rcp_f32_e32 v39, v39
	v_exp_f32_e32 v47, v47
	v_mul_f32_e32 v38, v48, v38
	v_mul_f32_e32 v40, v38, v40
	v_mul_f32_e32 v38, v49, v39
	v_add_f32_e32 v39, 1.0, v47
	v_rcp_f32_e32 v39, v39
	v_mul_f32_e32 v47, 0xbfb8aa3b, v43
	v_mul_f32_e32 v41, v38, v41
	v_exp_f32_e32 v47, v47
	v_mul_f32_e32 v38, v42, v39
	v_mul_f32_e32 v42, v38, v34
	v_mul_f32_e32 v38, 0xbfb8aa3b, v44
	v_exp_f32_e32 v38, v38
	v_mul_f32_e32 v39, 0xbfb8aa3b, v45
	v_exp_f32_e32 v39, v39
	v_add_f32_e32 v34, 1.0, v47
	v_rcp_f32_e32 v34, v34
	v_add_f32_e32 v38, 1.0, v38
	v_rcp_f32_e32 v38, v38
	v_add_f32_e32 v39, 1.0, v39
	v_rcp_f32_e32 v39, v39
	v_mul_f32_e32 v34, v43, v34
	v_mul_f32_e32 v43, v34, v35
	v_mul_f32_e32 v34, v44, v38
	v_mul_f32_e32 v44, v34, v36
	v_mul_f32_e32 v34, v45, v39
	v_mul_f32_e32 v37, v34, v37
	v_lshl_add_u64 v[38:39], v[50:51], 0, v[114:115]
	v_cvt_pk_bf16_f32 v34, v46, v53
	v_cvt_pk_bf16_f32 v35, v40, v41
	v_cvt_pk_bf16_f32 v36, v42, v43
	v_cvt_pk_bf16_f32 v37, v44, v37
	global_store_dwordx4 v[38:39], v[34:37], off
	s_nop 1
	v_mul_f32_e32 v34, 0xbfb8aa3b, v30
	v_exp_f32_e32 v34, v34
	v_mul_f32_e32 v35, 0xbfb8aa3b, v31
	v_exp_f32_e32 v35, v35
	v_add_u32_e32 v36, 0xa0, v139
	v_add_f32_e32 v34, 1.0, v34
	v_rcp_f32_e32 v37, v34
	v_add_f32_e32 v34, 1.0, v35
	v_rcp_f32_e32 v38, v34
	v_mad_i64_i32 v[34:35], s[6:7], v36, s74, v[134:135]
	v_mul_f32_e32 v30, v30, v37
	v_mul_f32_e32 v30, v30, v22
	v_mul_f32_e32 v22, v31, v38
	v_mul_f32_e32 v31, 0xbfb8aa3b, v32
	v_exp_f32_e32 v31, v31
	v_mul_f32_e32 v36, 0xbfb8aa3b, v33
	v_exp_f32_e32 v36, v36
	v_mul_f32_e32 v37, v22, v23
	v_add_f32_e32 v22, 1.0, v31
	v_rcp_f32_e32 v22, v22
	v_add_f32_e32 v23, 1.0, v36
	v_mul_f32_e32 v31, 0xbfb8aa3b, v26
	v_rcp_f32_e32 v23, v23
	v_exp_f32_e32 v31, v31
	v_mul_f32_e32 v22, v32, v22
	v_mul_f32_e32 v24, v22, v24
	v_mul_f32_e32 v22, v33, v23
	v_add_f32_e32 v23, 1.0, v31
	v_rcp_f32_e32 v23, v23
	v_mul_f32_e32 v31, 0xbfb8aa3b, v27
	v_mul_f32_e32 v25, v22, v25
	v_exp_f32_e32 v31, v31
	v_mul_f32_e32 v22, v26, v23
	v_mul_f32_e32 v26, v22, v18
	v_mul_f32_e32 v22, 0xbfb8aa3b, v28
	v_exp_f32_e32 v22, v22
	v_mul_f32_e32 v23, 0xbfb8aa3b, v29
	v_exp_f32_e32 v23, v23
	v_add_f32_e32 v18, 1.0, v31
	v_rcp_f32_e32 v18, v18
	v_add_f32_e32 v22, 1.0, v22
	v_rcp_f32_e32 v22, v22
	v_add_f32_e32 v23, 1.0, v23
	v_rcp_f32_e32 v23, v23
	v_mul_f32_e32 v18, v27, v18
	v_mul_f32_e32 v27, v18, v19
	v_mul_f32_e32 v18, v28, v22
	v_mul_f32_e32 v28, v18, v20
	v_mul_f32_e32 v18, v29, v23
	v_mul_f32_e32 v21, v18, v21
	v_lshl_add_u64 v[22:23], v[34:35], 0, v[114:115]
	v_cvt_pk_bf16_f32 v18, v30, v37
	v_cvt_pk_bf16_f32 v19, v24, v25
	v_cvt_pk_bf16_f32 v20, v26, v27
	v_cvt_pk_bf16_f32 v21, v28, v21
	global_store_dwordx4 v[22:23], v[18:21], off
	s_nop 1
	v_mul_f32_e32 v18, 0xbfb8aa3b, v14
	v_exp_f32_e32 v18, v18
	v_mul_f32_e32 v19, 0xbfb8aa3b, v15
	v_exp_f32_e32 v19, v19
	v_add_u32_e32 v20, 0xb0, v139
	v_add_f32_e32 v18, 1.0, v18
	v_rcp_f32_e32 v21, v18
	v_add_f32_e32 v18, 1.0, v19
	v_rcp_f32_e32 v22, v18
	v_mad_i64_i32 v[18:19], s[6:7], v20, s74, v[134:135]
	v_mul_f32_e32 v14, v14, v21
	v_mul_f32_e32 v14, v14, v6
	v_mul_f32_e32 v6, v15, v22
	v_mul_f32_e32 v15, 0xbfb8aa3b, v16
	v_exp_f32_e32 v15, v15
	v_mul_f32_e32 v20, 0xbfb8aa3b, v17
	v_exp_f32_e32 v20, v20
	v_mul_f32_e32 v21, v6, v7
	v_add_f32_e32 v6, 1.0, v15
	v_rcp_f32_e32 v6, v6
	v_add_f32_e32 v7, 1.0, v20
	v_mul_f32_e32 v15, 0xbfb8aa3b, v10
	v_rcp_f32_e32 v7, v7
	v_exp_f32_e32 v15, v15
	v_mul_f32_e32 v6, v16, v6
	v_mul_f32_e32 v8, v6, v8
	v_mul_f32_e32 v6, v17, v7
	v_add_f32_e32 v7, 1.0, v15
	v_rcp_f32_e32 v7, v7
	v_mul_f32_e32 v15, 0xbfb8aa3b, v11
	v_mul_f32_e32 v9, v6, v9
	v_exp_f32_e32 v15, v15
	v_mul_f32_e32 v6, v10, v7
	v_mul_f32_e32 v10, v6, v2
	v_mul_f32_e32 v6, 0xbfb8aa3b, v12
	v_exp_f32_e32 v6, v6
	v_mul_f32_e32 v7, 0xbfb8aa3b, v13
	v_exp_f32_e32 v7, v7
	v_add_f32_e32 v2, 1.0, v15
	v_rcp_f32_e32 v2, v2
	v_add_f32_e32 v6, 1.0, v6
	v_rcp_f32_e32 v6, v6
	v_add_f32_e32 v7, 1.0, v7
	v_rcp_f32_e32 v7, v7
	v_mul_f32_e32 v2, v11, v2
	v_mul_f32_e32 v11, v2, v3
	v_mul_f32_e32 v2, v12, v6
	v_mul_f32_e32 v12, v2, v4
	v_mul_f32_e32 v2, v13, v7
	v_mul_f32_e32 v5, v2, v5
	v_lshl_add_u64 v[6:7], v[18:19], 0, v[114:115]
	s_mov_b64 s[6:7], s[44:45]
	v_cvt_pk_bf16_f32 v2, v14, v21
	v_cvt_pk_bf16_f32 v3, v8, v9
	v_cvt_pk_bf16_f32 v4, v10, v11
	v_cvt_pk_bf16_f32 v5, v12, v5
	global_store_dwordx4 v[6:7], v[2:5], off
	s_cbranch_vccz .LBB0_691
	s_waitcnt vmcnt(0)
	v_readlane_b32 s0, v255, 8
	v_readlane_b32 s62, v255, 10
	v_readlane_b32 s84, v255, 12
	v_readlane_b32 s44, v255, 26
	s_cmpk_gt_u32 s22, 0xff
	v_readlane_b32 s1, v255, 9
	s_mov_b64 s[58:59], s[92:93]
	v_readlane_b32 s63, v255, 11
	v_readlane_b32 s85, v255, 13
	v_readlane_b32 s45, v255, 27
	s_cbranch_scc1 .LBB0_698
	s_barrier
